# v30 + removed the redundant post-barrier lgkmcnt(0) wait before each GEMM MFMA block
# speedup vs baseline: 1.0137x; 1.0137x over previous
; #define PG8_STAGEA(bufoff, gbase, voff) PG8_STAGE_X(bufoff, gbase, voff, PG8_AUX_A)
; #define PG8_STAGEB(bufoff, gbase, voff) PG8_STAGE_X(bufoff, gbase, voff, PG8_AUX_B)
; #define PG8_LDA(dst, b, h) do { _Pragma("unroll") for (int m = 0; m < 4; ++m) _Pragma("unroll") for (int k = 0; k < 2; ++k) dst[m][k] = *(const PG8_LAS bf16x8*)(lds + PG8_SA(b, h) + aoff + m * 2048 + k * 1024); } while (0)
; #define PG8_LDB(dst, b, h) do { _Pragma("unroll") for (int n = 0; n < 2; ++n) _Pragma("unroll") for (int k = 0; k < 2; ++k) dst[n][k] = *(const PG8_LAS bf16x8*)(lds + PG8_SB(b, h) + boff + n * 2048 + k * 1024); } while (0)
; #define PG8_MMA(ai, bj, At, Bt) do { __builtin_amdgcn_s_setprio(1); _Pragma("unroll") for (int m = 0; m < 4; ++m) _Pragma("unroll") for (int n = 0; n < 2; ++n) _Pragma("unroll") for (int k = 0; k < 2; ++k) \
;         acc[ai][bj][m][n] = __builtin_amdgcn_mfma_f32_16x16x32_bf16(Bt[n][k], At[m][k], acc[ai][bj][m][n], 0, 0, 0); __builtin_amdgcn_s_setprio(0); } while (0)
; #define PG8_WAIT_V(n) asm volatile("s_waitcnt vmcnt(" #n ")" ::: "memory")
; #define PG8_WAIT_L(n) asm volatile("s_waitcnt lgkmcnt(" #n ")" ::: "memory")
; template <class Epi, class Sched, bool ALIGN_EPI = false, bool SP2 = false>
; __device__ __forceinline__ void gemm_phase(PG8_LAS unsigned char* lds, const Gemm g, const Sched& S, const Epi& E) {
;     ...
;             const bool last = (t == nt - 2);
;             if constexpr (HasMid<Epi>::value) { if (t == ns) E.mid(acc, cur, wr, wc, fr, fq); }
;             const char* sA1 = (t + 1 >= ns) ? cA2 : cA; const char* sA2 = (t + 2 >= ns) ? cA2 : cA; const char* sB2 = (t + 2 >= ns) ? cB2 : cB;
;             const char* a1 = sA1 + (size_t)(t + 1) * kstep;
;             const char* a2 = last ? nA : sA2 + (size_t)(t + 2) * kstep; const char* b2 = last ? nB : sB2 + (size_t)(t + 2) * kstep;
;             const char* a3 = a2 + kstep; const char* b3 = b2 + kstep;
;             if (last && has_next) S.a_ready(nxt);
;             if constexpr (SP2) {
;             PG8_LDB(B0, 0, 0); PG8_LDB(B1, 0, 1); PG8_SCHED; PG8_LDA(At, 0, 0); PG8_STAGEA(PG8_SA(1, 1), a1 + hstep, voffA);
;             PG8_WAIT_V(8); PG8_WAIT_L(0); PG8_BAR; PG8_MMA(0, 0, At, B0); PG8_MMA(0, 1, At, B1); PG8_BAR; PG8_SCHED;
;             PG8_LDA(At, 0, 1); PG8_STAGEB(PG8_SB(0, 0), b2, voffB); PG8_STAGEB(PG8_SB(0, 1), b2 + hstep, voffB); PG8_STAGEA(PG8_SA(0, 0), a2, voffA);
.LBB0_94:
	s_add_i32 s71, s73, 2
	s_cmp_gt_u32 s71, 29
	s_cselect_b64 s[34:35], -1, 0
	s_and_b64 vcc, s[34:35], exec
	ds_read_b128 v[134:137], v184
	ds_read_b128 v[138:141], v184 offset:1024
	ds_read_b128 v[142:145], v184 offset:2048
	ds_read_b128 v[170:173], v184 offset:3072
	ds_read_b128 v[174:177], v185
	ds_read_b128 v[178:181], v185 offset:1024
	ds_read_b128 v[190:193], v185 offset:2048
	ds_read_b128 v[194:197], v185 offset:3072
	s_cselect_b32 s83, s60, s78
	s_cselect_b32 s34, s59, s9
	s_cselect_b32 s35, s58, s8
	s_cselect_b32 s82, s61, s79
	s_add_u32 s83, s83, s80
	s_addc_u32 s82, s82, s81
	s_add_u32 s83, s83, 0xfff80080
	s_addc_u32 s82, s82, -1
	s_add_u32 s35, s35, s80
	s_addc_u32 s34, s34, s81
	s_add_u32 s35, s35, 0xfff80080
	s_addc_u32 s34, s34, -1
	s_cmp_eq_u32 s73, 28
	s_cselect_b32 s85, s7, s82
	s_cselect_b32 s84, s26, s83
	s_cselect_b32 s83, s27, s34
	s_cselect_b32 s82, s57, s35
	v_lshl_add_u64 v[230:231], v[130:131], 0, s[80:81]
	s_add_i32 m0, s90, 0xc000
	ds_read_b128 v[198:201], v186
	ds_read_b128 v[202:205], v186 offset:1024
	ds_read_b128 v[206:209], v186 offset:2048
	ds_read_b128 v[210:213], v186 offset:3072
	ds_read_b128 v[214:217], v186 offset:4096
	ds_read_b128 v[218:221], v186 offset:5120
	ds_read_b128 v[222:225], v186 offset:6144
	ds_read_b128 v[226:229], v186 offset:7168
	global_load_lds_dwordx4 v[230:231], off
	v_lshl_add_u64 v[230:231], v[132:133], 0, s[80:81]
	s_add_i32 m0, s90, 0xe000
	s_nop 0
	global_load_lds_dwordx4 v[230:231], off
	s_waitcnt vmcnt(8)
	s_waitcnt lgkmcnt(0)
	s_barrier
	s_setprio 1
	v_mfma_f32_16x16x32_bf16 v[126:129], v[134:137], v[198:201], v[126:129]
	v_mfma_f32_16x16x32_bf16 v[94:97], v[142:145], v[198:201], v[94:97]
	v_mfma_f32_16x16x32_bf16 v[122:125], v[134:137], v[206:209], v[122:125]
	v_mfma_f32_16x16x32_bf16 v[90:93], v[142:145], v[206:209], v[90:93]
	v_mfma_f32_16x16x32_bf16 v[118:121], v[134:137], v[214:217], v[118:121]
	v_mfma_f32_16x16x32_bf16 v[86:89], v[142:145], v[214:217], v[86:89]
	v_mfma_f32_16x16x32_bf16 v[114:117], v[134:137], v[222:225], v[114:117]
	v_mfma_f32_16x16x32_bf16 v[82:85], v[142:145], v[222:225], v[82:85]
	v_mfma_f32_16x16x32_bf16 v[126:129], v[138:141], v[202:205], v[126:129]
	v_mfma_f32_16x16x32_bf16 v[94:97], v[170:173], v[202:205], v[94:97]
	v_mfma_f32_16x16x32_bf16 v[122:125], v[138:141], v[210:213], v[122:125]
	v_mfma_f32_16x16x32_bf16 v[90:93], v[170:173], v[210:213], v[90:93]
	v_mfma_f32_16x16x32_bf16 v[118:121], v[138:141], v[218:221], v[118:121]
	v_mfma_f32_16x16x32_bf16 v[86:89], v[170:173], v[218:221], v[86:89]
	v_mfma_f32_16x16x32_bf16 v[114:117], v[138:141], v[226:229], v[114:117]
	v_mfma_f32_16x16x32_bf16 v[82:85], v[170:173], v[226:229], v[82:85]
	s_setprio 0
	s_setprio 1
	v_mfma_f32_16x16x32_bf16 v[62:65], v[174:177], v[198:201], v[62:65]
	v_mfma_f32_16x16x32_bf16 v[30:33], v[190:193], v[198:201], v[30:33]
	v_mfma_f32_16x16x32_bf16 v[58:61], v[174:177], v[206:209], v[58:61]
	v_mfma_f32_16x16x32_bf16 v[26:29], v[190:193], v[206:209], v[26:29]
	v_mfma_f32_16x16x32_bf16 v[54:57], v[174:177], v[214:217], v[54:57]
	v_mfma_f32_16x16x32_bf16 v[22:25], v[190:193], v[214:217], v[22:25]
	v_mfma_f32_16x16x32_bf16 v[50:53], v[174:177], v[222:225], v[50:53]
	v_mfma_f32_16x16x32_bf16 v[18:21], v[190:193], v[222:225], v[18:21]
	v_mfma_f32_16x16x32_bf16 v[62:65], v[178:181], v[202:205], v[62:65]
	v_mfma_f32_16x16x32_bf16 v[30:33], v[194:197], v[202:205], v[30:33]
	v_mfma_f32_16x16x32_bf16 v[58:61], v[178:181], v[210:213], v[58:61]
	v_mfma_f32_16x16x32_bf16 v[26:29], v[194:197], v[210:213], v[26:29]
	v_mfma_f32_16x16x32_bf16 v[54:57], v[178:181], v[218:221], v[54:57]
	v_mfma_f32_16x16x32_bf16 v[22:25], v[194:197], v[218:221], v[22:25]
	v_mfma_f32_16x16x32_bf16 v[50:53], v[178:181], v[226:229], v[50:53]
	v_mfma_f32_16x16x32_bf16 v[18:21], v[194:197], v[226:229], v[18:21]
	s_setprio 0
	s_barrier
	s_add_i32 s34, s97, s87
	v_lshl_add_u64 v[230:231], s[82:83], 0, v[148:149]
	s_mov_b32 m0, s34
	ds_read_b128 v[198:201], v186 offset:16384
	ds_read_b128 v[202:205], v186 offset:17408
	ds_read_b128 v[206:209], v186 offset:18432
	ds_read_b128 v[210:213], v186 offset:19456
	ds_read_b128 v[214:217], v186 offset:20480
	ds_read_b128 v[218:221], v186 offset:21504
	ds_read_b128 v[222:225], v186 offset:22528
	ds_read_b128 v[226:229], v186 offset:23552
	global_load_lds_dwordx4 v[230:231], off
	s_add_i32 m0, s34, 0x2000
	s_add_u32 s34, s82, 0x80000
	v_lshl_add_u64 v[232:233], s[82:83], 0, v[152:153]
	s_addc_u32 s35, s83, 0
	s_add_i32 s73, s11, s87
	global_load_lds_dwordx4 v[232:233], off
	v_lshl_add_u64 v[234:235], s[34:35], 0, v[148:149]
	s_mov_b32 m0, s73
	v_lshl_add_u64 v[236:237], s[84:85], 0, v[150:151]
	global_load_lds_dwordx4 v[234:235], off
	v_lshl_add_u64 v[234:235], s[34:35], 0, v[152:153]
	s_add_i32 m0, s73, 0x2000
	s_nop 0
	global_load_lds_dwordx4 v[234:235], off
	v_lshl_add_u64 v[234:235], s[84:85], 0, v[146:147]
	s_mov_b32 m0, s90
	s_nop 0
	global_load_lds_dwordx4 v[234:235], off
	s_mov_b32 m0, s91
	s_nop 0
	global_load_lds_dwordx4 v[236:237], off
	s_waitcnt vmcnt(8)
	s_waitcnt lgkmcnt(0)
	s_barrier
; #define PG8_STAGEA(bufoff, gbase, voff) PG8_STAGE_X(bufoff, gbase, voff, PG8_AUX_A)
; #define PG8_LDA(dst, b, h) do { _Pragma("unroll") for (int m = 0; m < 4; ++m) _Pragma("unroll") for (int k = 0; k < 2; ++k) dst[m][k] = *(const PG8_LAS bf16x8*)(lds + PG8_SA(b, h) + aoff + m * 2048 + k * 1024); } while (0)
; #define PG8_LDB(dst, b, h) do { _Pragma("unroll") for (int n = 0; n < 2; ++n) _Pragma("unroll") for (int k = 0; k < 2; ++k) dst[n][k] = *(const PG8_LAS bf16x8*)(lds + PG8_SB(b, h) + boff + n * 2048 + k * 1024); } while (0)
; #define PG8_MMA(ai, bj, At, Bt) do { __builtin_amdgcn_s_setprio(1); _Pragma("unroll") for (int m = 0; m < 4; ++m) _Pragma("unroll") for (int n = 0; n < 2; ++n) _Pragma("unroll") for (int k = 0; k < 2; ++k) \
;         acc[ai][bj][m][n] = __builtin_amdgcn_mfma_f32_16x16x32_bf16(Bt[n][k], At[m][k], acc[ai][bj][m][n], 0, 0, 0); __builtin_amdgcn_s_setprio(0); } while (0)
; #define PG8_WAIT_V(n) asm volatile("s_waitcnt vmcnt(" #n ")" ::: "memory")
; #define PG8_WAIT_L(n) asm volatile("s_waitcnt lgkmcnt(" #n ")" ::: "memory")
; #define PG8_BAR __builtin_amdgcn_s_barrier()
; #define PG8_SCHED __builtin_amdgcn_sched_barrier(0)
; template <class Epi, class Sched, bool ALIGN_EPI = false, bool SP2 = false>
; __device__ __forceinline__ void gemm_phase(PG8_LAS unsigned char* lds, const Gemm g, const Sched& S, const Epi& E) {
;     ...
;             PG8_WAIT_V(8); PG8_WAIT_L(0); PG8_BAR; PG8_MMA(1, 0, At, B0); PG8_MMA(1, 1, At, B1); PG8_BAR; PG8_SCHED;
;             PG8_LDB(B0, 1, 0); PG8_LDB(B1, 1, 1); PG8_SCHED; PG8_LDA(At, 1, 0); PG8_STAGEA(PG8_SA(0, 1), a2 + hstep, voffA);
;             PG8_WAIT_V(8); PG8_WAIT_L(0); PG8_BAR; PG8_MMA(0, 0, At, B0); PG8_MMA(0, 1, At, B1); PG8_BAR; PG8_SCHED;
	s_setprio 1
	v_mfma_f32_16x16x32_bf16 v[110:113], v[134:137], v[198:201], v[110:113]
	v_mfma_f32_16x16x32_bf16 v[78:81], v[142:145], v[198:201], v[78:81]
	v_mfma_f32_16x16x32_bf16 v[106:109], v[134:137], v[206:209], v[106:109]
	v_mfma_f32_16x16x32_bf16 v[74:77], v[142:145], v[206:209], v[74:77]
	v_mfma_f32_16x16x32_bf16 v[102:105], v[134:137], v[214:217], v[102:105]
	v_mfma_f32_16x16x32_bf16 v[70:73], v[142:145], v[214:217], v[70:73]
	v_mfma_f32_16x16x32_bf16 v[98:101], v[134:137], v[222:225], v[98:101]
	v_mfma_f32_16x16x32_bf16 v[66:69], v[142:145], v[222:225], v[66:69]
	v_mfma_f32_16x16x32_bf16 v[110:113], v[138:141], v[202:205], v[110:113]
	v_mfma_f32_16x16x32_bf16 v[78:81], v[170:173], v[202:205], v[78:81]
	v_mfma_f32_16x16x32_bf16 v[106:109], v[138:141], v[210:213], v[106:109]
	v_mfma_f32_16x16x32_bf16 v[74:77], v[170:173], v[210:213], v[74:77]
	v_mfma_f32_16x16x32_bf16 v[102:105], v[138:141], v[218:221], v[102:105]
	v_mfma_f32_16x16x32_bf16 v[70:73], v[170:173], v[218:221], v[70:73]
	v_mfma_f32_16x16x32_bf16 v[98:101], v[138:141], v[226:229], v[98:101]
	v_mfma_f32_16x16x32_bf16 v[66:69], v[170:173], v[226:229], v[66:69]
	s_setprio 0
	s_setprio 1
	v_mfma_f32_16x16x32_bf16 v[46:49], v[174:177], v[198:201], v[46:49]
	v_mfma_f32_16x16x32_bf16 v[14:17], v[190:193], v[198:201], v[14:17]
	v_mfma_f32_16x16x32_bf16 v[42:45], v[174:177], v[206:209], v[42:45]
	v_mfma_f32_16x16x32_bf16 v[10:13], v[190:193], v[206:209], v[10:13]
	v_mfma_f32_16x16x32_bf16 v[38:41], v[174:177], v[214:217], v[38:41]
	v_mfma_f32_16x16x32_bf16 v[6:9], v[190:193], v[214:217], v[6:9]
	v_mfma_f32_16x16x32_bf16 v[34:37], v[174:177], v[222:225], v[34:37]
	v_mfma_f32_16x16x32_bf16 v[2:5], v[190:193], v[222:225], v[2:5]
	v_mfma_f32_16x16x32_bf16 v[46:49], v[178:181], v[202:205], v[46:49]
	v_mfma_f32_16x16x32_bf16 v[14:17], v[194:197], v[202:205], v[14:17]
	v_mfma_f32_16x16x32_bf16 v[42:45], v[178:181], v[210:213], v[42:45]
	v_mfma_f32_16x16x32_bf16 v[10:13], v[194:197], v[210:213], v[10:13]
	v_mfma_f32_16x16x32_bf16 v[38:41], v[178:181], v[218:221], v[38:41]
	v_mfma_f32_16x16x32_bf16 v[6:9], v[194:197], v[218:221], v[6:9]
	v_mfma_f32_16x16x32_bf16 v[34:37], v[178:181], v[226:229], v[34:37]
	v_mfma_f32_16x16x32_bf16 v[2:5], v[194:197], v[226:229], v[2:5]
	s_setprio 0
	s_barrier
	s_add_i32 s73, 0, 0x18000
	v_add_u32_e32 v154, s73, v182
	s_add_i32 s54, 0, 0x1c000
	ds_read_b128 v[134:137], v154
	ds_read_b128 v[138:141], v154 offset:1024
	ds_read_b128 v[142:145], v154 offset:2048
	ds_read_b128 v[170:173], v154 offset:3072
	v_add_u32_e32 v154, s54, v182
	ds_read_b128 v[174:177], v154
	ds_read_b128 v[178:181], v154 offset:1024
	ds_read_b128 v[190:193], v154 offset:2048
	ds_read_b128 v[194:197], v154 offset:3072
	s_add_u32 s34, s84, 0x80000
	s_addc_u32 s35, s85, 0
	s_mov_b32 m0, s92
	v_lshl_add_u64 v[238:239], s[34:35], 0, v[146:147]
	ds_read_b128 v[198:201], v186 offset:32768
	ds_read_b128 v[202:205], v186 offset:33792
	ds_read_b128 v[206:209], v186 offset:34816
	ds_read_b128 v[210:213], v186 offset:35840
	ds_read_b128 v[214:217], v186 offset:36864
	ds_read_b128 v[218:221], v186 offset:37888
	ds_read_b128 v[222:225], v186 offset:38912
	ds_read_b128 v[226:229], v186 offset:39936
	global_load_lds_dwordx4 v[238:239], off
	v_lshl_add_u64 v[238:239], s[34:35], 0, v[150:151]
	s_mov_b32 m0, s93
	s_nop 0
	global_load_lds_dwordx4 v[238:239], off
	s_waitcnt vmcnt(8)
	s_waitcnt lgkmcnt(0)
	s_barrier
	s_setprio 1
	v_mfma_f32_16x16x32_bf16 v[126:129], v[134:137], v[198:201], v[126:129]
	v_mfma_f32_16x16x32_bf16 v[94:97], v[142:145], v[198:201], v[94:97]
	v_mfma_f32_16x16x32_bf16 v[122:125], v[134:137], v[206:209], v[122:125]
	v_mfma_f32_16x16x32_bf16 v[90:93], v[142:145], v[206:209], v[90:93]
	v_mfma_f32_16x16x32_bf16 v[118:121], v[134:137], v[214:217], v[118:121]
	v_mfma_f32_16x16x32_bf16 v[86:89], v[142:145], v[214:217], v[86:89]
	v_mfma_f32_16x16x32_bf16 v[114:117], v[134:137], v[222:225], v[114:117]
	v_mfma_f32_16x16x32_bf16 v[82:85], v[142:145], v[222:225], v[82:85]
	v_mfma_f32_16x16x32_bf16 v[126:129], v[138:141], v[202:205], v[126:129]
	v_mfma_f32_16x16x32_bf16 v[94:97], v[170:173], v[202:205], v[94:97]
	v_mfma_f32_16x16x32_bf16 v[122:125], v[138:141], v[210:213], v[122:125]
	v_mfma_f32_16x16x32_bf16 v[90:93], v[170:173], v[210:213], v[90:93]
	v_mfma_f32_16x16x32_bf16 v[118:121], v[138:141], v[218:221], v[118:121]
	v_mfma_f32_16x16x32_bf16 v[86:89], v[170:173], v[218:221], v[86:89]
	v_mfma_f32_16x16x32_bf16 v[114:117], v[138:141], v[226:229], v[114:117]
	v_mfma_f32_16x16x32_bf16 v[82:85], v[170:173], v[226:229], v[82:85]
	s_setprio 0
	s_setprio 1
	v_mfma_f32_16x16x32_bf16 v[62:65], v[174:177], v[198:201], v[62:65]
	v_mfma_f32_16x16x32_bf16 v[30:33], v[190:193], v[198:201], v[30:33]
	v_mfma_f32_16x16x32_bf16 v[58:61], v[174:177], v[206:209], v[58:61]
	v_mfma_f32_16x16x32_bf16 v[26:29], v[190:193], v[206:209], v[26:29]
	v_mfma_f32_16x16x32_bf16 v[54:57], v[174:177], v[214:217], v[54:57]
	v_mfma_f32_16x16x32_bf16 v[22:25], v[190:193], v[214:217], v[22:25]
	v_mfma_f32_16x16x32_bf16 v[50:53], v[174:177], v[222:225], v[50:53]
	v_mfma_f32_16x16x32_bf16 v[18:21], v[190:193], v[222:225], v[18:21]
	v_mfma_f32_16x16x32_bf16 v[62:65], v[178:181], v[202:205], v[62:65]
	v_mfma_f32_16x16x32_bf16 v[30:33], v[194:197], v[202:205], v[30:33]
	v_mfma_f32_16x16x32_bf16 v[58:61], v[178:181], v[210:213], v[58:61]
	v_mfma_f32_16x16x32_bf16 v[26:29], v[194:197], v[210:213], v[26:29]
	v_mfma_f32_16x16x32_bf16 v[54:57], v[178:181], v[218:221], v[54:57]
	v_mfma_f32_16x16x32_bf16 v[22:25], v[194:197], v[218:221], v[22:25]
	v_mfma_f32_16x16x32_bf16 v[50:53], v[178:181], v[226:229], v[50:53]
	v_mfma_f32_16x16x32_bf16 v[18:21], v[194:197], v[226:229], v[18:21]
	s_setprio 0
	s_barrier
; #define PG8_STAGEA(bufoff, gbase, voff) PG8_STAGE_X(bufoff, gbase, voff, PG8_AUX_A)
; #define PG8_STAGEB(bufoff, gbase, voff) PG8_STAGE_X(bufoff, gbase, voff, PG8_AUX_B)
; #define PG8_LDA(dst, b, h) do { _Pragma("unroll") for (int m = 0; m < 4; ++m) _Pragma("unroll") for (int k = 0; k < 2; ++k) dst[m][k] = *(const PG8_LAS bf16x8*)(lds + PG8_SA(b, h) + aoff + m * 2048 + k * 1024); } while (0)
; #define PG8_MMA(ai, bj, At, Bt) do { __builtin_amdgcn_s_setprio(1); _Pragma("unroll") for (int m = 0; m < 4; ++m) _Pragma("unroll") for (int n = 0; n < 2; ++n) _Pragma("unroll") for (int k = 0; k < 2; ++k) \
;         acc[ai][bj][m][n] = __builtin_amdgcn_mfma_f32_16x16x32_bf16(Bt[n][k], At[m][k], acc[ai][bj][m][n], 0, 0, 0); __builtin_amdgcn_s_setprio(0); } while (0)
; #define PG8_WAIT_V(n) asm volatile("s_waitcnt vmcnt(" #n ")" ::: "memory")
; #define PG8_WAIT_L(n) asm volatile("s_waitcnt lgkmcnt(" #n ")" ::: "memory")
; #define PG8_BAR __builtin_amdgcn_s_barrier()
; #define PG8_SCHED __builtin_amdgcn_sched_barrier(0)
; template <class Epi, class Sched, bool ALIGN_EPI = false, bool SP2 = false>
; __device__ __forceinline__ void gemm_phase(PG8_LAS unsigned char* lds, const Gemm g, const Sched& S, const Epi& E) {
;     ...
;             PG8_LDA(At, 1, 1); PG8_STAGEB(PG8_SB(1, 0), b3, voffB); PG8_STAGEB(PG8_SB(1, 1), b3 + hstep, voffB); PG8_STAGEA(PG8_SA(1, 0), a3, voffA);
;             PG8_WAIT_V(8); PG8_WAIT_L(0); PG8_BAR; PG8_MMA(1, 0, At, B0); PG8_MMA(1, 1, At, B1); PG8_BAR; PG8_SCHED;
	s_add_i32 s34, s73, s87
	v_lshl_add_u64 v[230:231], v[230:231], 0, s[64:65]
	s_mov_b32 m0, s34
	ds_read_b128 v[198:201], v186 offset:49152
	ds_read_b128 v[202:205], v186 offset:50176
	ds_read_b128 v[206:209], v186 offset:51200
	ds_read_b128 v[210:213], v186 offset:52224
	ds_read_b128 v[214:217], v186 offset:53248
	ds_read_b128 v[218:221], v186 offset:54272
	ds_read_b128 v[222:225], v186 offset:55296
	ds_read_b128 v[226:229], v186 offset:56320
	global_load_lds_dwordx4 v[230:231], off
	s_add_i32 m0, s34, 0x2000
	s_add_u32 s34, s82, 0x80080
	v_lshl_add_u64 v[230:231], v[232:233], 0, s[64:65]
	s_addc_u32 s35, s83, 0
	s_add_i32 s54, s54, s87
	global_load_lds_dwordx4 v[230:231], off
	v_lshl_add_u64 v[230:231], s[34:35], 0, v[148:149]
	s_mov_b32 m0, s54
	s_nop 0
	global_load_lds_dwordx4 v[230:231], off
	v_lshl_add_u64 v[230:231], s[34:35], 0, v[152:153]
	s_add_i32 m0, s54, 0x2000
	s_nop 0
	global_load_lds_dwordx4 v[230:231], off
	v_lshl_add_u64 v[230:231], v[234:235], 0, s[64:65]
	s_mov_b32 m0, s95
	s_nop 0
	global_load_lds_dwordx4 v[230:231], off
	v_lshl_add_u64 v[230:231], v[236:237], 0, s[64:65]
	s_mov_b32 m0, s96
	s_nop 0
	global_load_lds_dwordx4 v[230:231], off
	s_waitcnt vmcnt(8)
	s_waitcnt lgkmcnt(0)
	s_barrier
	s_setprio 1
	v_mfma_f32_16x16x32_bf16 v[110:113], v[134:137], v[198:201], v[110:113]
	v_mfma_f32_16x16x32_bf16 v[78:81], v[142:145], v[198:201], v[78:81]
	v_mfma_f32_16x16x32_bf16 v[106:109], v[134:137], v[206:209], v[106:109]
	v_mfma_f32_16x16x32_bf16 v[74:77], v[142:145], v[206:209], v[74:77]
	v_mfma_f32_16x16x32_bf16 v[102:105], v[134:137], v[214:217], v[102:105]
	v_mfma_f32_16x16x32_bf16 v[70:73], v[142:145], v[214:217], v[70:73]
	v_mfma_f32_16x16x32_bf16 v[98:101], v[134:137], v[222:225], v[98:101]
	v_mfma_f32_16x16x32_bf16 v[66:69], v[142:145], v[222:225], v[66:69]
	v_mfma_f32_16x16x32_bf16 v[110:113], v[138:141], v[202:205], v[110:113]
	v_mfma_f32_16x16x32_bf16 v[78:81], v[170:173], v[202:205], v[78:81]
	v_mfma_f32_16x16x32_bf16 v[106:109], v[138:141], v[210:213], v[106:109]
	v_mfma_f32_16x16x32_bf16 v[74:77], v[170:173], v[210:213], v[74:77]
	v_mfma_f32_16x16x32_bf16 v[102:105], v[138:141], v[218:221], v[102:105]
	v_mfma_f32_16x16x32_bf16 v[70:73], v[170:173], v[218:221], v[70:73]
	v_mfma_f32_16x16x32_bf16 v[98:101], v[138:141], v[226:229], v[98:101]
	v_mfma_f32_16x16x32_bf16 v[66:69], v[170:173], v[226:229], v[66:69]
	s_setprio 0
	s_setprio 1
	v_mfma_f32_16x16x32_bf16 v[46:49], v[174:177], v[198:201], v[46:49]
	v_mfma_f32_16x16x32_bf16 v[14:17], v[190:193], v[198:201], v[14:17]
	v_mfma_f32_16x16x32_bf16 v[42:45], v[174:177], v[206:209], v[42:45]
	v_mfma_f32_16x16x32_bf16 v[10:13], v[190:193], v[206:209], v[10:13]
	v_mfma_f32_16x16x32_bf16 v[38:41], v[174:177], v[214:217], v[38:41]
	v_mfma_f32_16x16x32_bf16 v[6:9], v[190:193], v[214:217], v[6:9]
	v_mfma_f32_16x16x32_bf16 v[34:37], v[174:177], v[222:225], v[34:37]
	v_mfma_f32_16x16x32_bf16 v[2:5], v[190:193], v[222:225], v[2:5]
	v_mfma_f32_16x16x32_bf16 v[46:49], v[178:181], v[202:205], v[46:49]
	v_mfma_f32_16x16x32_bf16 v[14:17], v[194:197], v[202:205], v[14:17]
	v_mfma_f32_16x16x32_bf16 v[42:45], v[178:181], v[210:213], v[42:45]
	v_mfma_f32_16x16x32_bf16 v[10:13], v[194:197], v[210:213], v[10:13]
	v_mfma_f32_16x16x32_bf16 v[38:41], v[178:181], v[218:221], v[38:41]
	v_mfma_f32_16x16x32_bf16 v[6:9], v[194:197], v[218:221], v[6:9]
	v_mfma_f32_16x16x32_bf16 v[34:37], v[178:181], v[226:229], v[34:37]
	v_mfma_f32_16x16x32_bf16 v[2:5], v[194:197], v[226:229], v[2:5]
	s_setprio 0
	s_barrier
	s_add_u32 s80, s80, 0x100
	s_addc_u32 s81, s81, 0
	s_mov_b32 s73, s71
	s_cbranch_vccz .LBB0_94
	s_and_b64 vcc, exec, s[66:67]
	s_cbranch_vccz .LBB0_97
	s_barrier

; #define PG8_STAGEA(bufoff, gbase, voff) PG8_STAGE_X(bufoff, gbase, voff, PG8_AUX_A)
; #define PG8_STAGEB(bufoff, gbase, voff) PG8_STAGE_X(bufoff, gbase, voff, PG8_AUX_B)
; #define PG8_LDA(dst, b, h) do { _Pragma("unroll") for (int m = 0; m < 4; ++m) _Pragma("unroll") for (int k = 0; k < 2; ++k) dst[m][k] = *(const PG8_LAS bf16x8*)(lds + PG8_SA(b, h) + aoff + m * 2048 + k * 1024); } while (0)
; #define PG8_LDB(dst, b, h) do { _Pragma("unroll") for (int n = 0; n < 2; ++n) _Pragma("unroll") for (int k = 0; k < 2; ++k) dst[n][k] = *(const PG8_LAS bf16x8*)(lds + PG8_SB(b, h) + boff + n * 2048 + k * 1024); } while (0)
; #define PG8_MMA(ai, bj, At, Bt) do { __builtin_amdgcn_s_setprio(1); _Pragma("unroll") for (int m = 0; m < 4; ++m) _Pragma("unroll") for (int n = 0; n < 2; ++n) _Pragma("unroll") for (int k = 0; k < 2; ++k) \
;         acc[ai][bj][m][n] = __builtin_amdgcn_mfma_f32_16x16x32_bf16(Bt[n][k], At[m][k], acc[ai][bj][m][n], 0, 0, 0); __builtin_amdgcn_s_setprio(0); } while (0)
; #define PG8_WAIT_V(n) asm volatile("s_waitcnt vmcnt(" #n ")" ::: "memory")
; #define PG8_WAIT_L(n) asm volatile("s_waitcnt lgkmcnt(" #n ")" ::: "memory")
; template <class Epi, class Sched, bool ALIGN_EPI = false, bool SP2 = false>
; __device__ __forceinline__ void gemm_phase(PG8_LAS unsigned char* lds, const Gemm g, const Sched& S, const Epi& E) {
;     ...
;             const bool last = (t == nt - 2);
;             if constexpr (HasMid<Epi>::value) { if (t == ns) E.mid(acc, cur, wr, wc, fr, fq); }
;             const char* sA1 = (t + 1 >= ns) ? cA2 : cA; const char* sA2 = (t + 2 >= ns) ? cA2 : cA; const char* sB2 = (t + 2 >= ns) ? cB2 : cB;
;             const char* a1 = sA1 + (size_t)(t + 1) * kstep;
;             const char* a2 = last ? nA : sA2 + (size_t)(t + 2) * kstep; const char* b2 = last ? nB : sB2 + (size_t)(t + 2) * kstep;
;             const char* a3 = a2 + kstep; const char* b3 = b2 + kstep;
;             if (last && has_next) S.a_ready(nxt);
;             if constexpr (SP2) {
;             PG8_LDB(B0, 0, 0); PG8_LDB(B1, 0, 1); PG8_SCHED; PG8_LDA(At, 0, 0); PG8_STAGEA(PG8_SA(1, 1), a1 + hstep, voffA);
;             PG8_WAIT_V(8); PG8_WAIT_L(0); PG8_BAR; PG8_MMA(0, 0, At, B0); PG8_MMA(0, 1, At, B1); PG8_BAR; PG8_SCHED;
;             PG8_LDA(At, 0, 1); PG8_STAGEB(PG8_SB(0, 0), b2, voffB); PG8_STAGEB(PG8_SB(0, 1), b2 + hstep, voffB); PG8_STAGEA(PG8_SA(0, 0), a2, voffA);
.LBB0_295:
	s_add_i32 s92, s74, 2
	s_cmp_gt_u32 s92, 29
	s_cselect_b64 s[34:35], -1, 0
	s_and_b64 vcc, s[34:35], exec
	s_cselect_b32 s76, s6, s70
	ds_read_b128 v[156:159], v152
	ds_read_b128 v[160:163], v152 offset:1024
	ds_read_b128 v[164:167], v152 offset:2048
	ds_read_b128 v[168:171], v152 offset:3072
	ds_read_b128 v[172:175], v153
	ds_read_b128 v[176:179], v153 offset:1024
	ds_read_b128 v[180:183], v153 offset:2048
	ds_read_b128 v[184:187], v153 offset:3072
	s_cselect_b32 s34, s5, s69
	s_cselect_b32 s35, s4, s68
	s_cselect_b32 s75, s7, s71
	s_add_u32 s76, s76, s72
	s_addc_u32 s75, s75, s73
	s_add_u32 s76, s76, 0xfff80080
	s_addc_u32 s75, s75, -1
	s_add_u32 s35, s35, s72
	s_addc_u32 s34, s34, s73
	s_add_u32 s35, s35, 0xfff80080
	s_addc_u32 s34, s34, -1
	s_cmp_eq_u32 s74, 28
	s_cselect_b32 s74, s91, s35
	s_cselect_b32 s77, s61, s75
	s_cselect_b32 s76, s90, s76
	s_cselect_b32 s75, s59, s34
	v_lshl_add_u64 v[220:221], v[146:147], 0, s[72:73]
	s_add_i32 m0, s67, 0xc000
	ds_read_b128 v[188:191], v154
	ds_read_b128 v[192:195], v154 offset:1024
	ds_read_b128 v[196:199], v154 offset:2048
	ds_read_b128 v[200:203], v154 offset:3072
	ds_read_b128 v[204:207], v154 offset:4096
	ds_read_b128 v[208:211], v154 offset:5120
	ds_read_b128 v[212:215], v154 offset:6144
	ds_read_b128 v[216:219], v154 offset:7168
	global_load_lds_dwordx4 v[220:221], off
	v_lshl_add_u64 v[220:221], v[148:149], 0, s[72:73]
	s_add_i32 m0, s67, 0xe000
	s_nop 0
	global_load_lds_dwordx4 v[220:221], off
	s_waitcnt vmcnt(8)
	s_waitcnt lgkmcnt(0)
	s_barrier
	s_setprio 1
	v_mfma_f32_16x16x32_bf16 v[126:129], v[156:159], v[188:191], v[126:129]
	v_mfma_f32_16x16x32_bf16 v[122:125], v[164:167], v[188:191], v[122:125]
	v_mfma_f32_16x16x32_bf16 v[118:121], v[156:159], v[196:199], v[118:121]
	v_mfma_f32_16x16x32_bf16 v[110:113], v[164:167], v[196:199], v[110:113]
	v_mfma_f32_16x16x32_bf16 v[102:105], v[156:159], v[204:207], v[102:105]
	v_mfma_f32_16x16x32_bf16 v[94:97], v[164:167], v[204:207], v[94:97]
	v_mfma_f32_16x16x32_bf16 v[86:89], v[156:159], v[212:215], v[86:89]
	v_mfma_f32_16x16x32_bf16 v[78:81], v[164:167], v[212:215], v[78:81]
	v_mfma_f32_16x16x32_bf16 v[126:129], v[160:163], v[192:195], v[126:129]
	v_mfma_f32_16x16x32_bf16 v[122:125], v[168:171], v[192:195], v[122:125]
	v_mfma_f32_16x16x32_bf16 v[118:121], v[160:163], v[200:203], v[118:121]
	v_mfma_f32_16x16x32_bf16 v[110:113], v[168:171], v[200:203], v[110:113]
	v_mfma_f32_16x16x32_bf16 v[102:105], v[160:163], v[208:211], v[102:105]
	v_mfma_f32_16x16x32_bf16 v[94:97], v[168:171], v[208:211], v[94:97]
	v_mfma_f32_16x16x32_bf16 v[86:89], v[160:163], v[216:219], v[86:89]
	v_mfma_f32_16x16x32_bf16 v[78:81], v[168:171], v[216:219], v[78:81]
	s_setprio 0
	s_setprio 1
	v_mfma_f32_16x16x32_bf16 v[114:117], v[172:175], v[188:191], v[114:117]
	v_mfma_f32_16x16x32_bf16 v[106:109], v[180:183], v[188:191], v[106:109]
	v_mfma_f32_16x16x32_bf16 v[98:101], v[172:175], v[196:199], v[98:101]
	v_mfma_f32_16x16x32_bf16 v[90:93], v[180:183], v[196:199], v[90:93]
	v_mfma_f32_16x16x32_bf16 v[82:85], v[172:175], v[204:207], v[82:85]
	v_mfma_f32_16x16x32_bf16 v[74:77], v[180:183], v[204:207], v[74:77]
	v_mfma_f32_16x16x32_bf16 v[70:73], v[172:175], v[212:215], v[70:73]
	v_mfma_f32_16x16x32_bf16 v[66:69], v[180:183], v[212:215], v[66:69]
	v_mfma_f32_16x16x32_bf16 v[114:117], v[176:179], v[192:195], v[114:117]
	v_mfma_f32_16x16x32_bf16 v[106:109], v[184:187], v[192:195], v[106:109]
	v_mfma_f32_16x16x32_bf16 v[98:101], v[176:179], v[200:203], v[98:101]
	v_mfma_f32_16x16x32_bf16 v[90:93], v[184:187], v[200:203], v[90:93]
	v_mfma_f32_16x16x32_bf16 v[82:85], v[176:179], v[208:211], v[82:85]
	v_mfma_f32_16x16x32_bf16 v[74:77], v[184:187], v[208:211], v[74:77]
	v_mfma_f32_16x16x32_bf16 v[70:73], v[176:179], v[216:219], v[70:73]
	v_mfma_f32_16x16x32_bf16 v[66:69], v[184:187], v[216:219], v[66:69]
	s_setprio 0
	s_barrier
	s_add_i32 s34, s84, s11
	v_lshl_add_u64 v[220:221], s[74:75], 0, v[134:135]
	s_mov_b32 m0, s34
	ds_read_b128 v[188:191], v154 offset:16384
	ds_read_b128 v[192:195], v154 offset:17408
	ds_read_b128 v[196:199], v154 offset:18432
	ds_read_b128 v[200:203], v154 offset:19456
	ds_read_b128 v[204:207], v154 offset:20480
	ds_read_b128 v[208:211], v154 offset:21504
	ds_read_b128 v[212:215], v154 offset:22528
	ds_read_b128 v[216:219], v154 offset:23552
	global_load_lds_dwordx4 v[220:221], off
	s_add_i32 m0, s34, 0x2000
	s_add_u32 s34, s74, 0x80000
	v_lshl_add_u64 v[222:223], s[74:75], 0, v[130:131]
	s_addc_u32 s35, s75, 0
	s_add_i32 s93, s85, s11
	global_load_lds_dwordx4 v[222:223], off
	v_lshl_add_u64 v[224:225], s[34:35], 0, v[134:135]
	s_mov_b32 m0, s93
	v_lshl_add_u64 v[226:227], s[76:77], 0, v[132:133]
	global_load_lds_dwordx4 v[224:225], off
	v_lshl_add_u64 v[224:225], s[34:35], 0, v[130:131]
	s_add_i32 m0, s93, 0x2000
	s_nop 0
	global_load_lds_dwordx4 v[224:225], off
	v_lshl_add_u64 v[224:225], s[76:77], 0, v[136:137]
	s_mov_b32 m0, s67
	s_nop 0
	global_load_lds_dwordx4 v[224:225], off
	s_mov_b32 m0, s78
	s_nop 0
	global_load_lds_dwordx4 v[226:227], off
	s_waitcnt vmcnt(8)
	s_waitcnt lgkmcnt(0)
	s_barrier
; #define PG8_STAGEA(bufoff, gbase, voff) PG8_STAGE_X(bufoff, gbase, voff, PG8_AUX_A)
; #define PG8_LDA(dst, b, h) do { _Pragma("unroll") for (int m = 0; m < 4; ++m) _Pragma("unroll") for (int k = 0; k < 2; ++k) dst[m][k] = *(const PG8_LAS bf16x8*)(lds + PG8_SA(b, h) + aoff + m * 2048 + k * 1024); } while (0)
; #define PG8_LDB(dst, b, h) do { _Pragma("unroll") for (int n = 0; n < 2; ++n) _Pragma("unroll") for (int k = 0; k < 2; ++k) dst[n][k] = *(const PG8_LAS bf16x8*)(lds + PG8_SB(b, h) + boff + n * 2048 + k * 1024); } while (0)
; #define PG8_MMA(ai, bj, At, Bt) do { __builtin_amdgcn_s_setprio(1); _Pragma("unroll") for (int m = 0; m < 4; ++m) _Pragma("unroll") for (int n = 0; n < 2; ++n) _Pragma("unroll") for (int k = 0; k < 2; ++k) \
;         acc[ai][bj][m][n] = __builtin_amdgcn_mfma_f32_16x16x32_bf16(Bt[n][k], At[m][k], acc[ai][bj][m][n], 0, 0, 0); __builtin_amdgcn_s_setprio(0); } while (0)
; #define PG8_WAIT_V(n) asm volatile("s_waitcnt vmcnt(" #n ")" ::: "memory")
; #define PG8_WAIT_L(n) asm volatile("s_waitcnt lgkmcnt(" #n ")" ::: "memory")
; #define PG8_BAR __builtin_amdgcn_s_barrier()
; #define PG8_SCHED __builtin_amdgcn_sched_barrier(0)
; template <class Epi, class Sched, bool ALIGN_EPI = false, bool SP2 = false>
; __device__ __forceinline__ void gemm_phase(PG8_LAS unsigned char* lds, const Gemm g, const Sched& S, const Epi& E) {
;     ...
;             PG8_WAIT_V(8); PG8_WAIT_L(0); PG8_BAR; PG8_MMA(1, 0, At, B0); PG8_MMA(1, 1, At, B1); PG8_BAR; PG8_SCHED;
;             PG8_LDB(B0, 1, 0); PG8_LDB(B1, 1, 1); PG8_SCHED; PG8_LDA(At, 1, 0); PG8_STAGEA(PG8_SA(0, 1), a2 + hstep, voffA);
;             PG8_WAIT_V(8); PG8_WAIT_L(0); PG8_BAR; PG8_MMA(0, 0, At, B0); PG8_MMA(0, 1, At, B1); PG8_BAR; PG8_SCHED;
	s_setprio 1
	v_mfma_f32_16x16x32_bf16 v[62:65], v[156:159], v[188:191], v[62:65]
	v_mfma_f32_16x16x32_bf16 v[58:61], v[164:167], v[188:191], v[58:61]
	v_mfma_f32_16x16x32_bf16 v[54:57], v[156:159], v[196:199], v[54:57]
	v_mfma_f32_16x16x32_bf16 v[46:49], v[164:167], v[196:199], v[46:49]
	v_mfma_f32_16x16x32_bf16 v[38:41], v[156:159], v[204:207], v[38:41]
	v_mfma_f32_16x16x32_bf16 v[30:33], v[164:167], v[204:207], v[30:33]
	v_mfma_f32_16x16x32_bf16 v[22:25], v[156:159], v[212:215], v[22:25]
	v_mfma_f32_16x16x32_bf16 v[14:17], v[164:167], v[212:215], v[14:17]
	v_mfma_f32_16x16x32_bf16 v[62:65], v[160:163], v[192:195], v[62:65]
	v_mfma_f32_16x16x32_bf16 v[58:61], v[168:171], v[192:195], v[58:61]
	v_mfma_f32_16x16x32_bf16 v[54:57], v[160:163], v[200:203], v[54:57]
	v_mfma_f32_16x16x32_bf16 v[46:49], v[168:171], v[200:203], v[46:49]
	v_mfma_f32_16x16x32_bf16 v[38:41], v[160:163], v[208:211], v[38:41]
	v_mfma_f32_16x16x32_bf16 v[30:33], v[168:171], v[208:211], v[30:33]
	v_mfma_f32_16x16x32_bf16 v[22:25], v[160:163], v[216:219], v[22:25]
	v_mfma_f32_16x16x32_bf16 v[14:17], v[168:171], v[216:219], v[14:17]
	s_setprio 0
	s_setprio 1
	v_mfma_f32_16x16x32_bf16 v[50:53], v[172:175], v[188:191], v[50:53]
	v_mfma_f32_16x16x32_bf16 v[42:45], v[180:183], v[188:191], v[42:45]
	v_mfma_f32_16x16x32_bf16 v[34:37], v[172:175], v[196:199], v[34:37]
	v_mfma_f32_16x16x32_bf16 v[26:29], v[180:183], v[196:199], v[26:29]
	v_mfma_f32_16x16x32_bf16 v[18:21], v[172:175], v[204:207], v[18:21]
	v_mfma_f32_16x16x32_bf16 v[10:13], v[180:183], v[204:207], v[10:13]
	v_mfma_f32_16x16x32_bf16 v[6:9], v[172:175], v[212:215], v[6:9]
	v_mfma_f32_16x16x32_bf16 v[2:5], v[180:183], v[212:215], v[2:5]
	v_mfma_f32_16x16x32_bf16 v[50:53], v[176:179], v[192:195], v[50:53]
	v_mfma_f32_16x16x32_bf16 v[42:45], v[184:187], v[192:195], v[42:45]
	v_mfma_f32_16x16x32_bf16 v[34:37], v[176:179], v[200:203], v[34:37]
	v_mfma_f32_16x16x32_bf16 v[26:29], v[184:187], v[200:203], v[26:29]
	v_mfma_f32_16x16x32_bf16 v[18:21], v[176:179], v[208:211], v[18:21]
	v_mfma_f32_16x16x32_bf16 v[10:13], v[184:187], v[208:211], v[10:13]
	v_mfma_f32_16x16x32_bf16 v[6:9], v[176:179], v[216:219], v[6:9]
	v_mfma_f32_16x16x32_bf16 v[2:5], v[184:187], v[216:219], v[2:5]
	s_setprio 0
	s_barrier
	s_add_i32 s93, 0, 0x18000
	v_add_u32_e32 v155, s93, v150
	s_add_i32 s94, 0, 0x1c000
	ds_read_b128 v[156:159], v155
	ds_read_b128 v[160:163], v155 offset:1024
	ds_read_b128 v[164:167], v155 offset:2048
	ds_read_b128 v[168:171], v155 offset:3072
	v_add_u32_e32 v155, s94, v150
	ds_read_b128 v[172:175], v155
	ds_read_b128 v[176:179], v155 offset:1024
	ds_read_b128 v[180:183], v155 offset:2048
	ds_read_b128 v[184:187], v155 offset:3072
	s_add_u32 s34, s76, 0x80000
	s_addc_u32 s35, s77, 0
	s_mov_b32 m0, s79
	v_lshl_add_u64 v[228:229], s[34:35], 0, v[136:137]
	ds_read_b128 v[188:191], v154 offset:32768
	ds_read_b128 v[192:195], v154 offset:33792
	ds_read_b128 v[196:199], v154 offset:34816
	ds_read_b128 v[200:203], v154 offset:35840
	ds_read_b128 v[204:207], v154 offset:36864
	ds_read_b128 v[208:211], v154 offset:37888
	ds_read_b128 v[212:215], v154 offset:38912
	ds_read_b128 v[216:219], v154 offset:39936
	global_load_lds_dwordx4 v[228:229], off
	v_lshl_add_u64 v[228:229], s[34:35], 0, v[132:133]
	s_mov_b32 m0, s80
	s_nop 0
	global_load_lds_dwordx4 v[228:229], off
	s_waitcnt vmcnt(8)
	s_waitcnt lgkmcnt(0)
	s_barrier
	s_setprio 1
	v_mfma_f32_16x16x32_bf16 v[126:129], v[156:159], v[188:191], v[126:129]
	v_mfma_f32_16x16x32_bf16 v[122:125], v[164:167], v[188:191], v[122:125]
	v_mfma_f32_16x16x32_bf16 v[118:121], v[156:159], v[196:199], v[118:121]
	v_mfma_f32_16x16x32_bf16 v[110:113], v[164:167], v[196:199], v[110:113]
	v_mfma_f32_16x16x32_bf16 v[102:105], v[156:159], v[204:207], v[102:105]
	v_mfma_f32_16x16x32_bf16 v[94:97], v[164:167], v[204:207], v[94:97]
	v_mfma_f32_16x16x32_bf16 v[86:89], v[156:159], v[212:215], v[86:89]
	v_mfma_f32_16x16x32_bf16 v[78:81], v[164:167], v[212:215], v[78:81]
	v_mfma_f32_16x16x32_bf16 v[126:129], v[160:163], v[192:195], v[126:129]
	v_mfma_f32_16x16x32_bf16 v[122:125], v[168:171], v[192:195], v[122:125]
	v_mfma_f32_16x16x32_bf16 v[118:121], v[160:163], v[200:203], v[118:121]
	v_mfma_f32_16x16x32_bf16 v[110:113], v[168:171], v[200:203], v[110:113]
	v_mfma_f32_16x16x32_bf16 v[102:105], v[160:163], v[208:211], v[102:105]
	v_mfma_f32_16x16x32_bf16 v[94:97], v[168:171], v[208:211], v[94:97]
	v_mfma_f32_16x16x32_bf16 v[86:89], v[160:163], v[216:219], v[86:89]
	v_mfma_f32_16x16x32_bf16 v[78:81], v[168:171], v[216:219], v[78:81]
	s_setprio 0
	s_setprio 1
	v_mfma_f32_16x16x32_bf16 v[114:117], v[172:175], v[188:191], v[114:117]
	v_mfma_f32_16x16x32_bf16 v[106:109], v[180:183], v[188:191], v[106:109]
	v_mfma_f32_16x16x32_bf16 v[98:101], v[172:175], v[196:199], v[98:101]
	v_mfma_f32_16x16x32_bf16 v[90:93], v[180:183], v[196:199], v[90:93]
	v_mfma_f32_16x16x32_bf16 v[82:85], v[172:175], v[204:207], v[82:85]
	v_mfma_f32_16x16x32_bf16 v[74:77], v[180:183], v[204:207], v[74:77]
	v_mfma_f32_16x16x32_bf16 v[70:73], v[172:175], v[212:215], v[70:73]
	v_mfma_f32_16x16x32_bf16 v[66:69], v[180:183], v[212:215], v[66:69]
	v_mfma_f32_16x16x32_bf16 v[114:117], v[176:179], v[192:195], v[114:117]
	v_mfma_f32_16x16x32_bf16 v[106:109], v[184:187], v[192:195], v[106:109]
	v_mfma_f32_16x16x32_bf16 v[98:101], v[176:179], v[200:203], v[98:101]
	v_mfma_f32_16x16x32_bf16 v[90:93], v[184:187], v[200:203], v[90:93]
	v_mfma_f32_16x16x32_bf16 v[82:85], v[176:179], v[208:211], v[82:85]
	v_mfma_f32_16x16x32_bf16 v[74:77], v[184:187], v[208:211], v[74:77]
	v_mfma_f32_16x16x32_bf16 v[70:73], v[176:179], v[216:219], v[70:73]
	v_mfma_f32_16x16x32_bf16 v[66:69], v[184:187], v[216:219], v[66:69]
	s_setprio 0
	s_barrier
; #define PG8_STAGEA(bufoff, gbase, voff) PG8_STAGE_X(bufoff, gbase, voff, PG8_AUX_A)
; #define PG8_STAGEB(bufoff, gbase, voff) PG8_STAGE_X(bufoff, gbase, voff, PG8_AUX_B)
; #define PG8_LDA(dst, b, h) do { _Pragma("unroll") for (int m = 0; m < 4; ++m) _Pragma("unroll") for (int k = 0; k < 2; ++k) dst[m][k] = *(const PG8_LAS bf16x8*)(lds + PG8_SA(b, h) + aoff + m * 2048 + k * 1024); } while (0)
; #define PG8_MMA(ai, bj, At, Bt) do { __builtin_amdgcn_s_setprio(1); _Pragma("unroll") for (int m = 0; m < 4; ++m) _Pragma("unroll") for (int n = 0; n < 2; ++n) _Pragma("unroll") for (int k = 0; k < 2; ++k) \
;         acc[ai][bj][m][n] = __builtin_amdgcn_mfma_f32_16x16x32_bf16(Bt[n][k], At[m][k], acc[ai][bj][m][n], 0, 0, 0); __builtin_amdgcn_s_setprio(0); } while (0)
; #define PG8_WAIT_V(n) asm volatile("s_waitcnt vmcnt(" #n ")" ::: "memory")
; #define PG8_WAIT_L(n) asm volatile("s_waitcnt lgkmcnt(" #n ")" ::: "memory")
; #define PG8_BAR __builtin_amdgcn_s_barrier()
; #define PG8_SCHED __builtin_amdgcn_sched_barrier(0)
; template <class Epi, class Sched, bool ALIGN_EPI = false, bool SP2 = false>
; __device__ __forceinline__ void gemm_phase(PG8_LAS unsigned char* lds, const Gemm g, const Sched& S, const Epi& E) {
;     ...
;             PG8_LDA(At, 1, 1); PG8_STAGEB(PG8_SB(1, 0), b3, voffB); PG8_STAGEB(PG8_SB(1, 1), b3 + hstep, voffB); PG8_STAGEA(PG8_SA(1, 0), a3, voffA);
;             PG8_WAIT_V(8); PG8_WAIT_L(0); PG8_BAR; PG8_MMA(1, 0, At, B0); PG8_MMA(1, 1, At, B1); PG8_BAR; PG8_SCHED;
	s_add_i32 s34, s93, s11
	v_lshl_add_u64 v[220:221], v[220:221], 0, s[54:55]
	s_mov_b32 m0, s34
	ds_read_b128 v[188:191], v154 offset:49152
	ds_read_b128 v[192:195], v154 offset:50176
	ds_read_b128 v[196:199], v154 offset:51200
	ds_read_b128 v[200:203], v154 offset:52224
	ds_read_b128 v[204:207], v154 offset:53248
	ds_read_b128 v[208:211], v154 offset:54272
	ds_read_b128 v[212:215], v154 offset:55296
	ds_read_b128 v[216:219], v154 offset:56320
	global_load_lds_dwordx4 v[220:221], off
	s_add_i32 m0, s34, 0x2000
	s_add_u32 s34, s74, 0x80080
	v_lshl_add_u64 v[220:221], v[222:223], 0, s[54:55]
	s_addc_u32 s35, s75, 0
	s_add_i32 s74, s94, s11
	global_load_lds_dwordx4 v[220:221], off
	v_lshl_add_u64 v[220:221], s[34:35], 0, v[134:135]
	s_mov_b32 m0, s74
	s_nop 0
	global_load_lds_dwordx4 v[220:221], off
	v_lshl_add_u64 v[220:221], s[34:35], 0, v[130:131]
	s_add_i32 m0, s74, 0x2000
	s_nop 0
	global_load_lds_dwordx4 v[220:221], off
	v_lshl_add_u64 v[220:221], v[224:225], 0, s[54:55]
	s_mov_b32 m0, s82
	s_nop 0
	global_load_lds_dwordx4 v[220:221], off
	v_lshl_add_u64 v[220:221], v[226:227], 0, s[54:55]
	s_mov_b32 m0, s83
	s_nop 0
	global_load_lds_dwordx4 v[220:221], off
	s_waitcnt vmcnt(8)
	s_waitcnt lgkmcnt(0)
	s_barrier
	s_setprio 1
	v_mfma_f32_16x16x32_bf16 v[62:65], v[156:159], v[188:191], v[62:65]
	v_mfma_f32_16x16x32_bf16 v[58:61], v[164:167], v[188:191], v[58:61]
	v_mfma_f32_16x16x32_bf16 v[54:57], v[156:159], v[196:199], v[54:57]
	v_mfma_f32_16x16x32_bf16 v[46:49], v[164:167], v[196:199], v[46:49]
	v_mfma_f32_16x16x32_bf16 v[38:41], v[156:159], v[204:207], v[38:41]
	v_mfma_f32_16x16x32_bf16 v[30:33], v[164:167], v[204:207], v[30:33]
	v_mfma_f32_16x16x32_bf16 v[22:25], v[156:159], v[212:215], v[22:25]
	v_mfma_f32_16x16x32_bf16 v[14:17], v[164:167], v[212:215], v[14:17]
	v_mfma_f32_16x16x32_bf16 v[62:65], v[160:163], v[192:195], v[62:65]
	v_mfma_f32_16x16x32_bf16 v[58:61], v[168:171], v[192:195], v[58:61]
	v_mfma_f32_16x16x32_bf16 v[54:57], v[160:163], v[200:203], v[54:57]
	v_mfma_f32_16x16x32_bf16 v[46:49], v[168:171], v[200:203], v[46:49]
	v_mfma_f32_16x16x32_bf16 v[38:41], v[160:163], v[208:211], v[38:41]
	v_mfma_f32_16x16x32_bf16 v[30:33], v[168:171], v[208:211], v[30:33]
	v_mfma_f32_16x16x32_bf16 v[22:25], v[160:163], v[216:219], v[22:25]
	v_mfma_f32_16x16x32_bf16 v[14:17], v[168:171], v[216:219], v[14:17]
	s_setprio 0
	s_setprio 1
	v_mfma_f32_16x16x32_bf16 v[50:53], v[172:175], v[188:191], v[50:53]
	v_mfma_f32_16x16x32_bf16 v[42:45], v[180:183], v[188:191], v[42:45]
	v_mfma_f32_16x16x32_bf16 v[34:37], v[172:175], v[196:199], v[34:37]
	v_mfma_f32_16x16x32_bf16 v[26:29], v[180:183], v[196:199], v[26:29]
	v_mfma_f32_16x16x32_bf16 v[18:21], v[172:175], v[204:207], v[18:21]
	v_mfma_f32_16x16x32_bf16 v[10:13], v[180:183], v[204:207], v[10:13]
	v_mfma_f32_16x16x32_bf16 v[6:9], v[172:175], v[212:215], v[6:9]
	v_mfma_f32_16x16x32_bf16 v[2:5], v[180:183], v[212:215], v[2:5]
	v_mfma_f32_16x16x32_bf16 v[50:53], v[176:179], v[192:195], v[50:53]
	v_mfma_f32_16x16x32_bf16 v[42:45], v[184:187], v[192:195], v[42:45]
	v_mfma_f32_16x16x32_bf16 v[34:37], v[176:179], v[200:203], v[34:37]
	v_mfma_f32_16x16x32_bf16 v[26:29], v[184:187], v[200:203], v[26:29]
	v_mfma_f32_16x16x32_bf16 v[18:21], v[176:179], v[208:211], v[18:21]
	v_mfma_f32_16x16x32_bf16 v[10:13], v[184:187], v[208:211], v[10:13]
	v_mfma_f32_16x16x32_bf16 v[6:9], v[176:179], v[216:219], v[6:9]
	v_mfma_f32_16x16x32_bf16 v[2:5], v[184:187], v[216:219], v[2:5]
	s_setprio 0
	s_barrier
	s_add_u32 s72, s72, 0x100
	s_addc_u32 s73, s73, 0
	s_mov_b32 s74, s92
	s_cbranch_vccz .LBB0_295
	s_and_b64 vcc, exec, s[56:57]
	s_cbranch_vccz .LBB0_298
	s_barrier

; #define PG8_STAGEA(bufoff, gbase, voff) PG8_STAGE_X(bufoff, gbase, voff, PG8_AUX_A)
; #define PG8_STAGEB(bufoff, gbase, voff) PG8_STAGE_X(bufoff, gbase, voff, PG8_AUX_B)
; #define PG8_LDA(dst, b, h) do { _Pragma("unroll") for (int m = 0; m < 4; ++m) _Pragma("unroll") for (int k = 0; k < 2; ++k) dst[m][k] = *(const PG8_LAS bf16x8*)(lds + PG8_SA(b, h) + aoff + m * 2048 + k * 1024); } while (0)
; #define PG8_LDB(dst, b, h) do { _Pragma("unroll") for (int n = 0; n < 2; ++n) _Pragma("unroll") for (int k = 0; k < 2; ++k) dst[n][k] = *(const PG8_LAS bf16x8*)(lds + PG8_SB(b, h) + boff + n * 2048 + k * 1024); } while (0)
; #define PG8_MMA(ai, bj, At, Bt) do { __builtin_amdgcn_s_setprio(1); _Pragma("unroll") for (int m = 0; m < 4; ++m) _Pragma("unroll") for (int n = 0; n < 2; ++n) _Pragma("unroll") for (int k = 0; k < 2; ++k) \
;         acc[ai][bj][m][n] = __builtin_amdgcn_mfma_f32_16x16x32_bf16(Bt[n][k], At[m][k], acc[ai][bj][m][n], 0, 0, 0); __builtin_amdgcn_s_setprio(0); } while (0)
; #define PG8_WAIT_V(n) asm volatile("s_waitcnt vmcnt(" #n ")" ::: "memory")
; #define PG8_WAIT_L(n) asm volatile("s_waitcnt lgkmcnt(" #n ")" ::: "memory")
; template <class Epi, class Sched, bool ALIGN_EPI = false, bool SP2 = false>
; __device__ __forceinline__ void gemm_phase(PG8_LAS unsigned char* lds, const Gemm g, const Sched& S, const Epi& E) {
;     ...
;             const bool last = (t == nt - 2);
;             if constexpr (HasMid<Epi>::value) { if (t == ns) E.mid(acc, cur, wr, wc, fr, fq); }
;             const char* sA1 = (t + 1 >= ns) ? cA2 : cA; const char* sA2 = (t + 2 >= ns) ? cA2 : cA; const char* sB2 = (t + 2 >= ns) ? cB2 : cB;
;             const char* a1 = sA1 + (size_t)(t + 1) * kstep;
;             const char* a2 = last ? nA : sA2 + (size_t)(t + 2) * kstep; const char* b2 = last ? nB : sB2 + (size_t)(t + 2) * kstep;
;             const char* a3 = a2 + kstep; const char* b3 = b2 + kstep;
;             if (last && has_next) S.a_ready(nxt);
;             if constexpr (SP2) {
;             PG8_LDB(B0, 0, 0); PG8_LDB(B1, 0, 1); PG8_SCHED; PG8_LDA(At, 0, 0); PG8_STAGEA(PG8_SA(1, 1), a1 + hstep, voffA);
;             PG8_WAIT_V(8); PG8_WAIT_L(0); PG8_BAR; PG8_MMA(0, 0, At, B0); PG8_MMA(0, 1, At, B1); PG8_BAR; PG8_SCHED;
;             PG8_LDA(At, 0, 1); PG8_STAGEB(PG8_SB(0, 0), b2, voffB); PG8_STAGEB(PG8_SB(0, 1), b2 + hstep, voffB); PG8_STAGEA(PG8_SA(0, 0), a2, voffA);
.LBB0_564:
	s_add_i32 s26, s26, 2
	s_cmp_gt_u32 s26, 29
	s_cselect_b32 s80, vcc_lo, s76
	s_cselect_b32 s27, s9, s75
	s_cselect_b32 s34, s8, s74
	s_cselect_b32 s35, vcc_hi, s77
	s_add_u32 s80, s80, s78
	s_addc_u32 s35, s35, s79
	v_add_u32_e32 v3, s11, v162
	s_add_u32 s80, s80, 0x100
	ds_read_b128 v[134:137], v3
	ds_read_b128 v[138:141], v3 offset:1024
	ds_read_b128 v[166:169], v3 offset:2048
	ds_read_b128 v[170:173], v3 offset:3072
	v_add_u32_e32 v3, s90, v162
	s_addc_u32 s81, s35, 0
	ds_read_b128 v[174:177], v3
	ds_read_b128 v[178:181], v3 offset:1024
	ds_read_b128 v[182:185], v3 offset:2048
	ds_read_b128 v[186:189], v3 offset:3072
	s_add_u32 s34, s34, s78
	s_addc_u32 s27, s27, s79
	s_add_u32 s36, s34, 0x100
	s_addc_u32 s27, s27, 0
	s_cmp_gt_u32 s26, 31
	s_cselect_b32 s34, vcc_lo, s76
	s_cselect_b32 s35, vcc_hi, s77
	s_cmpk_eq_i32 s78, 0x1f00
	s_cselect_b32 s83, s69, s81
	s_cselect_b32 s82, s4, s80
	s_cselect_b32 s81, s5, s27
	s_cselect_b32 s80, s67, s36
	v_lshl_add_u64 v[4:5], s[34:35], 0, v[150:151]
	v_lshl_add_u64 v[4:5], v[4:5], 0, s[78:79]
	s_add_i32 m0, s86, 0xc000
	ds_read_b128 v[190:193], v164
	ds_read_b128 v[194:197], v164 offset:1024
	ds_read_b128 v[198:201], v164 offset:2048
	ds_read_b128 v[202:205], v164 offset:3072
	ds_read_b128 v[206:209], v164 offset:4096
	ds_read_b128 v[210:213], v164 offset:5120
	ds_read_b128 v[214:217], v164 offset:6144
	ds_read_b128 v[218:221], v164 offset:7168
	global_load_lds_dwordx4 v[4:5], off
	v_lshl_add_u64 v[4:5], s[34:35], 0, v[152:153]
	v_lshl_add_u64 v[4:5], v[4:5], 0, s[78:79]
	s_add_i32 m0, s86, 0xe000
	s_nop 0
	global_load_lds_dwordx4 v[4:5], off
	s_waitcnt vmcnt(8)
	s_waitcnt lgkmcnt(0)
	s_barrier
	s_setprio 1
	v_mfma_f32_16x16x32_bf16 v[130:133], v[134:137], v[190:193], v[130:133]
	v_mfma_f32_16x16x32_bf16 v[126:129], v[166:169], v[190:193], v[126:129]
	v_mfma_f32_16x16x32_bf16 v[114:117], v[134:137], v[198:201], v[114:117]
	v_mfma_f32_16x16x32_bf16 v[110:113], v[166:169], v[198:201], v[110:113]
	v_mfma_f32_16x16x32_bf16 v[98:101], v[134:137], v[206:209], v[98:101]
	v_mfma_f32_16x16x32_bf16 v[94:97], v[166:169], v[206:209], v[94:97]
	v_mfma_f32_16x16x32_bf16 v[82:85], v[134:137], v[214:217], v[82:85]
	v_mfma_f32_16x16x32_bf16 v[78:81], v[166:169], v[214:217], v[78:81]
	v_mfma_f32_16x16x32_bf16 v[130:133], v[138:141], v[194:197], v[130:133]
	v_mfma_f32_16x16x32_bf16 v[126:129], v[170:173], v[194:197], v[126:129]
	v_mfma_f32_16x16x32_bf16 v[114:117], v[138:141], v[202:205], v[114:117]
	v_mfma_f32_16x16x32_bf16 v[110:113], v[170:173], v[202:205], v[110:113]
	v_mfma_f32_16x16x32_bf16 v[98:101], v[138:141], v[210:213], v[98:101]
	v_mfma_f32_16x16x32_bf16 v[94:97], v[170:173], v[210:213], v[94:97]
	v_mfma_f32_16x16x32_bf16 v[82:85], v[138:141], v[218:221], v[82:85]
	v_mfma_f32_16x16x32_bf16 v[78:81], v[170:173], v[218:221], v[78:81]
	s_setprio 0
	s_setprio 1
	v_mfma_f32_16x16x32_bf16 v[122:125], v[174:177], v[190:193], v[122:125]
	v_mfma_f32_16x16x32_bf16 v[118:121], v[182:185], v[190:193], v[118:121]
	v_mfma_f32_16x16x32_bf16 v[106:109], v[174:177], v[198:201], v[106:109]
	v_mfma_f32_16x16x32_bf16 v[102:105], v[182:185], v[198:201], v[102:105]
	v_mfma_f32_16x16x32_bf16 v[90:93], v[174:177], v[206:209], v[90:93]
	v_mfma_f32_16x16x32_bf16 v[86:89], v[182:185], v[206:209], v[86:89]
	v_mfma_f32_16x16x32_bf16 v[74:77], v[174:177], v[214:217], v[74:77]
	v_mfma_f32_16x16x32_bf16 v[70:73], v[182:185], v[214:217], v[70:73]
	v_mfma_f32_16x16x32_bf16 v[122:125], v[178:181], v[194:197], v[122:125]
	v_mfma_f32_16x16x32_bf16 v[118:121], v[186:189], v[194:197], v[118:121]
	v_mfma_f32_16x16x32_bf16 v[106:109], v[178:181], v[202:205], v[106:109]
	v_mfma_f32_16x16x32_bf16 v[102:105], v[186:189], v[202:205], v[102:105]
	v_mfma_f32_16x16x32_bf16 v[90:93], v[178:181], v[210:213], v[90:93]
	v_mfma_f32_16x16x32_bf16 v[86:89], v[186:189], v[210:213], v[86:89]
	v_mfma_f32_16x16x32_bf16 v[74:77], v[178:181], v[218:221], v[74:77]
	v_mfma_f32_16x16x32_bf16 v[70:73], v[186:189], v[218:221], v[70:73]
	s_setprio 0
	s_barrier
	s_add_i32 s27, s11, s84
	v_lshl_add_u64 v[222:223], s[80:81], 0, v[146:147]
	s_mov_b32 m0, s27
	ds_read_b128 v[190:193], v164 offset:16384
	ds_read_b128 v[194:197], v164 offset:17408
	ds_read_b128 v[198:201], v164 offset:18432
	ds_read_b128 v[202:205], v164 offset:19456
	ds_read_b128 v[206:209], v164 offset:20480
	ds_read_b128 v[210:213], v164 offset:21504
	ds_read_b128 v[214:217], v164 offset:22528
	ds_read_b128 v[218:221], v164 offset:23552
	global_load_lds_dwordx4 v[222:223], off
	s_add_i32 m0, s27, 0x2000
	s_add_u32 s34, s80, 0x80000
	v_lshl_add_u64 v[224:225], s[80:81], 0, v[142:143]
	s_addc_u32 s35, s81, 0
	s_add_i32 s27, s90, s84
	global_load_lds_dwordx4 v[224:225], off
	v_lshl_add_u64 v[4:5], s[34:35], 0, v[146:147]
	s_mov_b32 m0, s27
	v_lshl_add_u64 v[226:227], s[82:83], 0, v[148:149]
	global_load_lds_dwordx4 v[4:5], off
	v_lshl_add_u64 v[4:5], s[34:35], 0, v[142:143]
	s_add_i32 m0, s27, 0x2000
	v_lshl_add_u64 v[228:229], s[82:83], 0, v[144:145]
	global_load_lds_dwordx4 v[4:5], off
	s_mov_b32 m0, s86
	s_nop 0
	global_load_lds_dwordx4 v[226:227], off
	s_mov_b32 m0, s87
	s_nop 0
	global_load_lds_dwordx4 v[228:229], off
	s_waitcnt vmcnt(8)
	s_waitcnt lgkmcnt(0)
	s_barrier
; #define PG8_STAGEA(bufoff, gbase, voff) PG8_STAGE_X(bufoff, gbase, voff, PG8_AUX_A)
; #define PG8_LDA(dst, b, h) do { _Pragma("unroll") for (int m = 0; m < 4; ++m) _Pragma("unroll") for (int k = 0; k < 2; ++k) dst[m][k] = *(const PG8_LAS bf16x8*)(lds + PG8_SA(b, h) + aoff + m * 2048 + k * 1024); } while (0)
; #define PG8_LDB(dst, b, h) do { _Pragma("unroll") for (int n = 0; n < 2; ++n) _Pragma("unroll") for (int k = 0; k < 2; ++k) dst[n][k] = *(const PG8_LAS bf16x8*)(lds + PG8_SB(b, h) + boff + n * 2048 + k * 1024); } while (0)
; #define PG8_MMA(ai, bj, At, Bt) do { __builtin_amdgcn_s_setprio(1); _Pragma("unroll") for (int m = 0; m < 4; ++m) _Pragma("unroll") for (int n = 0; n < 2; ++n) _Pragma("unroll") for (int k = 0; k < 2; ++k) \
;         acc[ai][bj][m][n] = __builtin_amdgcn_mfma_f32_16x16x32_bf16(Bt[n][k], At[m][k], acc[ai][bj][m][n], 0, 0, 0); __builtin_amdgcn_s_setprio(0); } while (0)
; #define PG8_WAIT_V(n) asm volatile("s_waitcnt vmcnt(" #n ")" ::: "memory")
; #define PG8_WAIT_L(n) asm volatile("s_waitcnt lgkmcnt(" #n ")" ::: "memory")
; #define PG8_BAR __builtin_amdgcn_s_barrier()
; #define PG8_SCHED __builtin_amdgcn_sched_barrier(0)
; template <class Epi, class Sched, bool ALIGN_EPI = false, bool SP2 = false>
; __device__ __forceinline__ void gemm_phase(PG8_LAS unsigned char* lds, const Gemm g, const Sched& S, const Epi& E) {
;     ...
;             PG8_WAIT_V(8); PG8_WAIT_L(0); PG8_BAR; PG8_MMA(1, 0, At, B0); PG8_MMA(1, 1, At, B1); PG8_BAR; PG8_SCHED;
;             PG8_LDB(B0, 1, 0); PG8_LDB(B1, 1, 1); PG8_SCHED; PG8_LDA(At, 1, 0); PG8_STAGEA(PG8_SA(0, 1), a2 + hstep, voffA);
;             PG8_WAIT_V(8); PG8_WAIT_L(0); PG8_BAR; PG8_MMA(0, 0, At, B0); PG8_MMA(0, 1, At, B1); PG8_BAR; PG8_SCHED;
	s_setprio 1
	v_mfma_f32_16x16x32_bf16 v[66:69], v[134:137], v[190:193], v[66:69]
	v_mfma_f32_16x16x32_bf16 v[62:65], v[166:169], v[190:193], v[62:65]
	v_mfma_f32_16x16x32_bf16 v[50:53], v[134:137], v[198:201], v[50:53]
	v_mfma_f32_16x16x32_bf16 v[46:49], v[166:169], v[198:201], v[46:49]
	v_mfma_f32_16x16x32_bf16 v[34:37], v[134:137], v[206:209], v[34:37]
	v_mfma_f32_16x16x32_bf16 v[30:33], v[166:169], v[206:209], v[30:33]
	v_mfma_f32_16x16x32_bf16 v[18:21], v[134:137], v[214:217], v[18:21]
	v_mfma_f32_16x16x32_bf16 v[14:17], v[166:169], v[214:217], v[14:17]
	v_mfma_f32_16x16x32_bf16 v[66:69], v[138:141], v[194:197], v[66:69]
	v_mfma_f32_16x16x32_bf16 v[62:65], v[170:173], v[194:197], v[62:65]
	v_mfma_f32_16x16x32_bf16 v[50:53], v[138:141], v[202:205], v[50:53]
	v_mfma_f32_16x16x32_bf16 v[46:49], v[170:173], v[202:205], v[46:49]
	v_mfma_f32_16x16x32_bf16 v[34:37], v[138:141], v[210:213], v[34:37]
	v_mfma_f32_16x16x32_bf16 v[30:33], v[170:173], v[210:213], v[30:33]
	v_mfma_f32_16x16x32_bf16 v[18:21], v[138:141], v[218:221], v[18:21]
	v_mfma_f32_16x16x32_bf16 v[14:17], v[170:173], v[218:221], v[14:17]
	s_setprio 0
	s_setprio 1
	v_mfma_f32_16x16x32_bf16 v[58:61], v[174:177], v[190:193], v[58:61]
	v_mfma_f32_16x16x32_bf16 v[54:57], v[182:185], v[190:193], v[54:57]
	v_mfma_f32_16x16x32_bf16 v[42:45], v[174:177], v[198:201], v[42:45]
	v_mfma_f32_16x16x32_bf16 v[38:41], v[182:185], v[198:201], v[38:41]
	v_mfma_f32_16x16x32_bf16 v[26:29], v[174:177], v[206:209], v[26:29]
	v_mfma_f32_16x16x32_bf16 v[22:25], v[182:185], v[206:209], v[22:25]
	v_mfma_f32_16x16x32_bf16 v[10:13], v[174:177], v[214:217], v[10:13]
	v_mfma_f32_16x16x32_bf16 v[4:7], v[182:185], v[214:217], v[6:9]
	v_mfma_f32_16x16x32_bf16 v[58:61], v[178:181], v[194:197], v[58:61]
	v_mfma_f32_16x16x32_bf16 v[54:57], v[186:189], v[194:197], v[54:57]
	v_mfma_f32_16x16x32_bf16 v[42:45], v[178:181], v[202:205], v[42:45]
	v_mfma_f32_16x16x32_bf16 v[38:41], v[186:189], v[202:205], v[38:41]
	v_mfma_f32_16x16x32_bf16 v[26:29], v[178:181], v[210:213], v[26:29]
	v_mfma_f32_16x16x32_bf16 v[22:25], v[186:189], v[210:213], v[22:25]
	v_mfma_f32_16x16x32_bf16 v[10:13], v[178:181], v[218:221], v[10:13]
	v_mfma_f32_16x16x32_bf16 v[4:7], v[186:189], v[218:221], v[4:7]
	s_setprio 0
	s_barrier
	s_add_i32 s27, 0, 0x18000
	v_add_u32_e32 v3, s27, v162
	s_add_i32 s36, 0, 0x1c000
	ds_read_b128 v[134:137], v3
	ds_read_b128 v[138:141], v3 offset:1024
	ds_read_b128 v[166:169], v3 offset:2048
	ds_read_b128 v[170:173], v3 offset:3072
	v_add_u32_e32 v3, s36, v162
	ds_read_b128 v[174:177], v3
	ds_read_b128 v[178:181], v3 offset:1024
	ds_read_b128 v[182:185], v3 offset:2048
	ds_read_b128 v[186:189], v3 offset:3072
	s_add_u32 s34, s82, 0x80000
	s_addc_u32 s35, s83, 0
	s_mov_b32 m0, s91
	v_lshl_add_u64 v[8:9], s[34:35], 0, v[148:149]
	ds_read_b128 v[190:193], v164 offset:32768
	ds_read_b128 v[194:197], v164 offset:33792
	ds_read_b128 v[198:201], v164 offset:34816
	ds_read_b128 v[202:205], v164 offset:35840
	ds_read_b128 v[206:209], v164 offset:36864
	ds_read_b128 v[210:213], v164 offset:37888
	ds_read_b128 v[214:217], v164 offset:38912
	ds_read_b128 v[218:221], v164 offset:39936
	global_load_lds_dwordx4 v[8:9], off
	v_lshl_add_u64 v[8:9], s[34:35], 0, v[144:145]
	s_mov_b32 m0, s92
	s_nop 0
	global_load_lds_dwordx4 v[8:9], off
	s_waitcnt vmcnt(8)
	s_waitcnt lgkmcnt(0)
	s_barrier
	s_setprio 1
	v_mfma_f32_16x16x32_bf16 v[130:133], v[134:137], v[190:193], v[130:133]
	v_mfma_f32_16x16x32_bf16 v[126:129], v[166:169], v[190:193], v[126:129]
	v_mfma_f32_16x16x32_bf16 v[114:117], v[134:137], v[198:201], v[114:117]
	v_mfma_f32_16x16x32_bf16 v[110:113], v[166:169], v[198:201], v[110:113]
	v_mfma_f32_16x16x32_bf16 v[98:101], v[134:137], v[206:209], v[98:101]
	v_mfma_f32_16x16x32_bf16 v[94:97], v[166:169], v[206:209], v[94:97]
	v_mfma_f32_16x16x32_bf16 v[82:85], v[134:137], v[214:217], v[82:85]
	v_mfma_f32_16x16x32_bf16 v[78:81], v[166:169], v[214:217], v[78:81]
	v_mfma_f32_16x16x32_bf16 v[130:133], v[138:141], v[194:197], v[130:133]
	v_mfma_f32_16x16x32_bf16 v[126:129], v[170:173], v[194:197], v[126:129]
	v_mfma_f32_16x16x32_bf16 v[114:117], v[138:141], v[202:205], v[114:117]
	v_mfma_f32_16x16x32_bf16 v[110:113], v[170:173], v[202:205], v[110:113]
	v_mfma_f32_16x16x32_bf16 v[98:101], v[138:141], v[210:213], v[98:101]
	v_mfma_f32_16x16x32_bf16 v[94:97], v[170:173], v[210:213], v[94:97]
	v_mfma_f32_16x16x32_bf16 v[82:85], v[138:141], v[218:221], v[82:85]
	v_mfma_f32_16x16x32_bf16 v[78:81], v[170:173], v[218:221], v[78:81]
	s_setprio 0
	s_setprio 1
	v_mfma_f32_16x16x32_bf16 v[122:125], v[174:177], v[190:193], v[122:125]
	v_mfma_f32_16x16x32_bf16 v[118:121], v[182:185], v[190:193], v[118:121]
	v_mfma_f32_16x16x32_bf16 v[106:109], v[174:177], v[198:201], v[106:109]
	v_mfma_f32_16x16x32_bf16 v[102:105], v[182:185], v[198:201], v[102:105]
	v_mfma_f32_16x16x32_bf16 v[90:93], v[174:177], v[206:209], v[90:93]
	v_mfma_f32_16x16x32_bf16 v[86:89], v[182:185], v[206:209], v[86:89]
	v_mfma_f32_16x16x32_bf16 v[74:77], v[174:177], v[214:217], v[74:77]
	v_mfma_f32_16x16x32_bf16 v[70:73], v[182:185], v[214:217], v[70:73]
	v_mfma_f32_16x16x32_bf16 v[122:125], v[178:181], v[194:197], v[122:125]
	v_mfma_f32_16x16x32_bf16 v[118:121], v[186:189], v[194:197], v[118:121]
	v_mfma_f32_16x16x32_bf16 v[106:109], v[178:181], v[202:205], v[106:109]
	v_mfma_f32_16x16x32_bf16 v[102:105], v[186:189], v[202:205], v[102:105]
	v_mfma_f32_16x16x32_bf16 v[90:93], v[178:181], v[210:213], v[90:93]
	v_mfma_f32_16x16x32_bf16 v[86:89], v[186:189], v[210:213], v[86:89]
	v_mfma_f32_16x16x32_bf16 v[74:77], v[178:181], v[218:221], v[74:77]
	v_mfma_f32_16x16x32_bf16 v[70:73], v[186:189], v[218:221], v[70:73]
	s_setprio 0
	s_barrier
; #define PG8_STAGEA(bufoff, gbase, voff) PG8_STAGE_X(bufoff, gbase, voff, PG8_AUX_A)
; #define PG8_STAGEB(bufoff, gbase, voff) PG8_STAGE_X(bufoff, gbase, voff, PG8_AUX_B)
; #define PG8_LDA(dst, b, h) do { _Pragma("unroll") for (int m = 0; m < 4; ++m) _Pragma("unroll") for (int k = 0; k < 2; ++k) dst[m][k] = *(const PG8_LAS bf16x8*)(lds + PG8_SA(b, h) + aoff + m * 2048 + k * 1024); } while (0)
; #define PG8_MMA(ai, bj, At, Bt) do { __builtin_amdgcn_s_setprio(1); _Pragma("unroll") for (int m = 0; m < 4; ++m) _Pragma("unroll") for (int n = 0; n < 2; ++n) _Pragma("unroll") for (int k = 0; k < 2; ++k) \
;         acc[ai][bj][m][n] = __builtin_amdgcn_mfma_f32_16x16x32_bf16(Bt[n][k], At[m][k], acc[ai][bj][m][n], 0, 0, 0); __builtin_amdgcn_s_setprio(0); } while (0)
; #define PG8_WAIT_V(n) asm volatile("s_waitcnt vmcnt(" #n ")" ::: "memory")
; #define PG8_WAIT_L(n) asm volatile("s_waitcnt lgkmcnt(" #n ")" ::: "memory")
; #define PG8_BAR __builtin_amdgcn_s_barrier()
; #define PG8_SCHED __builtin_amdgcn_sched_barrier(0)
; template <class Epi, class Sched, bool ALIGN_EPI = false, bool SP2 = false>
; __device__ __forceinline__ void gemm_phase(PG8_LAS unsigned char* lds, const Gemm g, const Sched& S, const Epi& E) {
;     ...
;             PG8_LDA(At, 1, 1); PG8_STAGEB(PG8_SB(1, 0), b3, voffB); PG8_STAGEB(PG8_SB(1, 1), b3 + hstep, voffB); PG8_STAGEA(PG8_SA(1, 0), a3, voffA);
;             PG8_WAIT_V(8); PG8_WAIT_L(0); PG8_BAR; PG8_MMA(1, 0, At, B0); PG8_MMA(1, 1, At, B1); PG8_BAR; PG8_SCHED;
	s_add_i32 s27, s27, s84
	v_lshl_add_u64 v[8:9], v[222:223], 0, s[56:57]
	s_mov_b32 m0, s27
	ds_read_b128 v[190:193], v164 offset:49152
	ds_read_b128 v[194:197], v164 offset:50176
	ds_read_b128 v[198:201], v164 offset:51200
	ds_read_b128 v[202:205], v164 offset:52224
	ds_read_b128 v[206:209], v164 offset:53248
	ds_read_b128 v[210:213], v164 offset:54272
	ds_read_b128 v[214:217], v164 offset:55296
	ds_read_b128 v[218:221], v164 offset:56320
	global_load_lds_dwordx4 v[8:9], off
	s_add_i32 m0, s27, 0x2000
	s_add_u32 s34, s80, 0x80080
	v_lshl_add_u64 v[8:9], v[224:225], 0, s[56:57]
	s_addc_u32 s35, s81, 0
	s_add_i32 s27, s36, s84
	global_load_lds_dwordx4 v[8:9], off
	v_lshl_add_u64 v[8:9], s[34:35], 0, v[146:147]
	s_mov_b32 m0, s27
	s_nop 0
	global_load_lds_dwordx4 v[8:9], off
	v_lshl_add_u64 v[8:9], s[34:35], 0, v[142:143]
	s_add_i32 m0, s27, 0x2000
	s_nop 0
	global_load_lds_dwordx4 v[8:9], off
	v_lshl_add_u64 v[8:9], v[226:227], 0, s[56:57]
	s_mov_b32 m0, s95
	s_nop 0
	global_load_lds_dwordx4 v[8:9], off
	v_lshl_add_u64 v[8:9], v[228:229], 0, s[56:57]
	s_mov_b32 m0, s96
	s_nop 0
	global_load_lds_dwordx4 v[8:9], off
	s_waitcnt vmcnt(8)
	s_waitcnt lgkmcnt(0)
	s_barrier
	s_setprio 1
	v_mfma_f32_16x16x32_bf16 v[66:69], v[134:137], v[190:193], v[66:69]
	v_mfma_f32_16x16x32_bf16 v[62:65], v[166:169], v[190:193], v[62:65]
	v_mfma_f32_16x16x32_bf16 v[50:53], v[134:137], v[198:201], v[50:53]
	v_mfma_f32_16x16x32_bf16 v[46:49], v[166:169], v[198:201], v[46:49]
	v_mfma_f32_16x16x32_bf16 v[34:37], v[134:137], v[206:209], v[34:37]
	v_mfma_f32_16x16x32_bf16 v[30:33], v[166:169], v[206:209], v[30:33]
	v_mfma_f32_16x16x32_bf16 v[18:21], v[134:137], v[214:217], v[18:21]
	v_mfma_f32_16x16x32_bf16 v[14:17], v[166:169], v[214:217], v[14:17]
	v_mfma_f32_16x16x32_bf16 v[66:69], v[138:141], v[194:197], v[66:69]
	v_mfma_f32_16x16x32_bf16 v[62:65], v[170:173], v[194:197], v[62:65]
	v_mfma_f32_16x16x32_bf16 v[50:53], v[138:141], v[202:205], v[50:53]
	v_mfma_f32_16x16x32_bf16 v[46:49], v[170:173], v[202:205], v[46:49]
	v_mfma_f32_16x16x32_bf16 v[34:37], v[138:141], v[210:213], v[34:37]
	v_mfma_f32_16x16x32_bf16 v[30:33], v[170:173], v[210:213], v[30:33]
	v_mfma_f32_16x16x32_bf16 v[18:21], v[138:141], v[218:221], v[18:21]
	v_mfma_f32_16x16x32_bf16 v[14:17], v[170:173], v[218:221], v[14:17]
	s_setprio 0
	s_setprio 1
	v_mfma_f32_16x16x32_bf16 v[58:61], v[174:177], v[190:193], v[58:61]
	v_mfma_f32_16x16x32_bf16 v[54:57], v[182:185], v[190:193], v[54:57]
	v_mfma_f32_16x16x32_bf16 v[42:45], v[174:177], v[198:201], v[42:45]
	v_mfma_f32_16x16x32_bf16 v[38:41], v[182:185], v[198:201], v[38:41]
	v_mfma_f32_16x16x32_bf16 v[26:29], v[174:177], v[206:209], v[26:29]
	v_mfma_f32_16x16x32_bf16 v[22:25], v[182:185], v[206:209], v[22:25]
	v_mfma_f32_16x16x32_bf16 v[8:11], v[174:177], v[214:217], v[10:13]
	v_mfma_f32_16x16x32_bf16 v[4:7], v[182:185], v[214:217], v[4:7]
	v_mfma_f32_16x16x32_bf16 v[58:61], v[178:181], v[194:197], v[58:61]
	v_mfma_f32_16x16x32_bf16 v[54:57], v[186:189], v[194:197], v[54:57]
	v_mfma_f32_16x16x32_bf16 v[42:45], v[178:181], v[202:205], v[42:45]
	v_mfma_f32_16x16x32_bf16 v[38:41], v[186:189], v[202:205], v[38:41]
	v_mfma_f32_16x16x32_bf16 v[26:29], v[178:181], v[210:213], v[26:29]
	v_mfma_f32_16x16x32_bf16 v[22:25], v[186:189], v[210:213], v[22:25]
	v_mfma_f32_16x16x32_bf16 v[10:13], v[178:181], v[218:221], v[8:11]
	v_mfma_f32_16x16x32_bf16 v[6:9], v[186:189], v[218:221], v[4:7]
	s_setprio 0
	s_barrier
	s_add_u32 s78, s78, 0x100
	s_addc_u32 s79, s79, 0
	s_cmp_gt_u32 s26, 61
	s_cbranch_scc1 .LBB0_567

; #define PG8_STAGEA(bufoff, gbase, voff) PG8_STAGE_X(bufoff, gbase, voff, PG8_AUX_A)
; #define PG8_STAGEB(bufoff, gbase, voff) PG8_STAGE_X(bufoff, gbase, voff, PG8_AUX_B)
; #define PG8_LDA(dst, b, h) do { _Pragma("unroll") for (int m = 0; m < 4; ++m) _Pragma("unroll") for (int k = 0; k < 2; ++k) dst[m][k] = *(const PG8_LAS bf16x8*)(lds + PG8_SA(b, h) + aoff + m * 2048 + k * 1024); } while (0)
; #define PG8_LDB(dst, b, h) do { _Pragma("unroll") for (int n = 0; n < 2; ++n) _Pragma("unroll") for (int k = 0; k < 2; ++k) dst[n][k] = *(const PG8_LAS bf16x8*)(lds + PG8_SB(b, h) + boff + n * 2048 + k * 1024); } while (0)
; #define PG8_MMA(ai, bj, At, Bt) do { __builtin_amdgcn_s_setprio(1); _Pragma("unroll") for (int m = 0; m < 4; ++m) _Pragma("unroll") for (int n = 0; n < 2; ++n) _Pragma("unroll") for (int k = 0; k < 2; ++k) \
;         acc[ai][bj][m][n] = __builtin_amdgcn_mfma_f32_16x16x32_bf16(Bt[n][k], At[m][k], acc[ai][bj][m][n], 0, 0, 0); __builtin_amdgcn_s_setprio(0); } while (0)
; #define PG8_WAIT_V(n) asm volatile("s_waitcnt vmcnt(" #n ")" ::: "memory")
; #define PG8_WAIT_L(n) asm volatile("s_waitcnt lgkmcnt(" #n ")" ::: "memory")
; template <class Epi, class Sched, bool ALIGN_EPI = false, bool SP2 = false>
; __device__ __forceinline__ void gemm_phase(PG8_LAS unsigned char* lds, const Gemm g, const Sched& S, const Epi& E) {
;     ...
;             const bool last = (t == nt - 2);
;             if constexpr (HasMid<Epi>::value) { if (t == ns) E.mid(acc, cur, wr, wc, fr, fq); }
;             const char* sA1 = (t + 1 >= ns) ? cA2 : cA; const char* sA2 = (t + 2 >= ns) ? cA2 : cA; const char* sB2 = (t + 2 >= ns) ? cB2 : cB;
;             const char* a1 = sA1 + (size_t)(t + 1) * kstep;
;             const char* a2 = last ? nA : sA2 + (size_t)(t + 2) * kstep; const char* b2 = last ? nB : sB2 + (size_t)(t + 2) * kstep;
;             const char* a3 = a2 + kstep; const char* b3 = b2 + kstep;
;             if (last && has_next) S.a_ready(nxt);
;             if constexpr (SP2) {
;             PG8_LDB(B0, 0, 0); PG8_LDB(B1, 0, 1); PG8_SCHED; PG8_LDA(At, 0, 0); PG8_STAGEA(PG8_SA(1, 1), a1 + hstep, voffA);
;             PG8_WAIT_V(8); PG8_WAIT_L(0); PG8_BAR; PG8_MMA(0, 0, At, B0); PG8_MMA(0, 1, At, B1); PG8_BAR; PG8_SCHED;
;             PG8_LDA(At, 0, 1); PG8_STAGEB(PG8_SB(0, 0), b2, voffB); PG8_STAGEB(PG8_SB(0, 1), b2 + hstep, voffB); PG8_STAGEA(PG8_SA(0, 0), a2, voffA);
.LBB0_643:
	s_add_i32 s97, s96, 2
	s_cmp_lt_u32 s96, 30
	s_cselect_b32 s37, s72, s50
	s_cselect_b32 s34, s71, s47
	s_cselect_b32 s35, s70, s46
	s_cselect_b32 s36, s73, s51
	s_add_u32 s37, s37, s74
	s_addc_u32 s36, s36, s75
	s_add_u32 s37, s37, 0xfff80080
	s_addc_u32 s36, s36, -1
	s_add_u32 s35, s35, s74
	s_addc_u32 s34, s34, s75
	s_add_u32 s35, s35, 0xfff80080
	s_addc_u32 s34, s34, -1
	s_cmp_eq_u32 s96, 30
	s_cselect_b32 s83, s61, s36
	s_cselect_b32 s82, s67, s37
	s_cselect_b32 s85, s59, s34
	s_cselect_b32 s84, s95, s35
	s_add_i32 s37, s93, s8
	s_add_i32 m0, s9, 0xc000
	s_add_i32 s36, s9, 0xe000
	s_add_i32 s38, s37, 0x2000
	s_add_u32 s86, s84, 0x80000
	ds_read_b128 v[82:85], v166
	ds_read_b128 v[90:93], v166 offset:1024
	ds_read_b128 v[94:97], v166 offset:2048
	ds_read_b128 v[158:161], v166 offset:3072
	ds_read_b128 v[170:173], v167
	ds_read_b128 v[174:177], v167 offset:1024
	ds_read_b128 v[178:181], v167 offset:2048
	ds_read_b128 v[182:185], v167 offset:3072
	s_addc_u32 s87, s85, 0
	s_add_i32 s39, s94, s8
	s_add_i32 s24, s39, 0x2000
	s_add_i32 s25, 0, 0x18000
	s_add_i32 vcc_hi, 0, 0x1c000
	s_add_u32 s80, s82, 0x80000
	s_addc_u32 s81, s83, 0
	s_add_i32 vcc_lo, s25, s8
	s_add_i32 s34, vcc_lo, 0x2000
	s_add_u32 s78, s84, 0x80080
	s_addc_u32 s79, s85, 0
	s_add_i32 s35, vcc_hi, s8
	s_add_i32 s28, s35, 0x2000
	s_add_u32 s76, s74, 0x100
	s_addc_u32 s77, s75, 0
	s_cmp_gt_u32 s96, 29
	v_lshl_add_u64 v[162:163], v[74:75], 0, s[74:75]
	ds_read_b128 v[186:189], v168
	ds_read_b128 v[190:193], v168 offset:1024
	ds_read_b128 v[194:197], v168 offset:2048
	ds_read_b128 v[198:201], v168 offset:3072
	ds_read_b128 v[202:205], v168 offset:4096
	ds_read_b128 v[206:209], v168 offset:5120
	ds_read_b128 v[210:213], v168 offset:6144
	ds_read_b128 v[214:217], v168 offset:7168
	global_load_lds_dwordx4 v[162:163], off
	v_lshl_add_u64 v[162:163], v[76:77], 0, s[74:75]
	s_mov_b32 m0, s36
	s_nop 0
	global_load_lds_dwordx4 v[162:163], off
	s_waitcnt vmcnt(8)
	s_waitcnt lgkmcnt(0)
	s_barrier
	s_setprio 1
	v_mfma_f32_16x16x32_bf16 v[142:145], v[82:85], v[186:189], v[142:145]
	v_mfma_f32_16x16x32_bf16 v[138:141], v[94:97], v[186:189], v[138:141]
	v_mfma_f32_16x16x32_bf16 v[126:129], v[82:85], v[194:197], v[126:129]
	v_mfma_f32_16x16x32_bf16 v[122:125], v[94:97], v[194:197], v[122:125]
	v_mfma_f32_16x16x32_bf16 v[110:113], v[82:85], v[202:205], v[110:113]
	v_mfma_f32_16x16x32_bf16 v[106:109], v[94:97], v[202:205], v[106:109]
	v_mfma_f32_16x16x32_bf16 v[86:89], v[82:85], v[210:213], v[86:89]
	v_mfma_f32_16x16x32_bf16 v[78:81], v[94:97], v[210:213], v[78:81]
	v_mfma_f32_16x16x32_bf16 v[142:145], v[90:93], v[190:193], v[142:145]
	v_mfma_f32_16x16x32_bf16 v[138:141], v[158:161], v[190:193], v[138:141]
	v_mfma_f32_16x16x32_bf16 v[126:129], v[90:93], v[198:201], v[126:129]
	v_mfma_f32_16x16x32_bf16 v[122:125], v[158:161], v[198:201], v[122:125]
	v_mfma_f32_16x16x32_bf16 v[110:113], v[90:93], v[206:209], v[110:113]
	v_mfma_f32_16x16x32_bf16 v[106:109], v[158:161], v[206:209], v[106:109]
	v_mfma_f32_16x16x32_bf16 v[86:89], v[90:93], v[214:217], v[86:89]
	v_mfma_f32_16x16x32_bf16 v[78:81], v[158:161], v[214:217], v[78:81]
	s_setprio 0
	s_setprio 1
	v_mfma_f32_16x16x32_bf16 v[134:137], v[170:173], v[186:189], v[134:137]
	v_mfma_f32_16x16x32_bf16 v[130:133], v[178:181], v[186:189], v[130:133]
	v_mfma_f32_16x16x32_bf16 v[118:121], v[170:173], v[194:197], v[118:121]
	v_mfma_f32_16x16x32_bf16 v[114:117], v[178:181], v[194:197], v[114:117]
	v_mfma_f32_16x16x32_bf16 v[102:105], v[170:173], v[202:205], v[102:105]
	v_mfma_f32_16x16x32_bf16 v[98:101], v[178:181], v[202:205], v[98:101]
	v_mfma_f32_16x16x32_bf16 v[70:73], v[170:173], v[210:213], v[70:73]
	v_mfma_f32_16x16x32_bf16 v[66:69], v[178:181], v[210:213], v[66:69]
	v_mfma_f32_16x16x32_bf16 v[134:137], v[174:177], v[190:193], v[134:137]
	v_mfma_f32_16x16x32_bf16 v[130:133], v[182:185], v[190:193], v[130:133]
	v_mfma_f32_16x16x32_bf16 v[118:121], v[174:177], v[198:201], v[118:121]
	v_mfma_f32_16x16x32_bf16 v[114:117], v[182:185], v[198:201], v[114:117]
	v_mfma_f32_16x16x32_bf16 v[102:105], v[174:177], v[206:209], v[102:105]
	v_mfma_f32_16x16x32_bf16 v[98:101], v[182:185], v[206:209], v[98:101]
	v_mfma_f32_16x16x32_bf16 v[70:73], v[174:177], v[214:217], v[70:73]
	v_mfma_f32_16x16x32_bf16 v[66:69], v[182:185], v[214:217], v[66:69]
	s_setprio 0
	s_barrier
	s_mov_b32 m0, s37
	v_lshl_add_u64 v[162:163], s[84:85], 0, v[146:147]
	ds_read_b128 v[186:189], v168 offset:16384
	ds_read_b128 v[190:193], v168 offset:17408
	ds_read_b128 v[194:197], v168 offset:18432
	ds_read_b128 v[198:201], v168 offset:19456
	ds_read_b128 v[202:205], v168 offset:20480
	ds_read_b128 v[206:209], v168 offset:21504
	ds_read_b128 v[210:213], v168 offset:22528
	ds_read_b128 v[214:217], v168 offset:23552
	global_load_lds_dwordx4 v[162:163], off
	v_lshl_add_u64 v[218:219], s[84:85], 0, v[148:149]
	s_mov_b32 m0, s38
	v_lshl_add_u64 v[220:221], s[86:87], 0, v[146:147]
	global_load_lds_dwordx4 v[218:219], off
	s_mov_b32 m0, s39
	v_lshl_add_u64 v[222:223], s[82:83], 0, v[148:149]
	global_load_lds_dwordx4 v[220:221], off
	v_lshl_add_u64 v[220:221], s[86:87], 0, v[148:149]
	s_mov_b32 m0, s24
	s_nop 0
	global_load_lds_dwordx4 v[220:221], off
	v_lshl_add_u64 v[220:221], s[82:83], 0, v[146:147]
	s_mov_b32 m0, s9
	s_nop 0
	global_load_lds_dwordx4 v[220:221], off
	s_mov_b32 m0, s11
	s_nop 0
	global_load_lds_dwordx4 v[222:223], off
	s_waitcnt vmcnt(8)
	s_waitcnt lgkmcnt(0)
	s_barrier
; #define PG8_STAGEA(bufoff, gbase, voff) PG8_STAGE_X(bufoff, gbase, voff, PG8_AUX_A)
; #define PG8_LDA(dst, b, h) do { _Pragma("unroll") for (int m = 0; m < 4; ++m) _Pragma("unroll") for (int k = 0; k < 2; ++k) dst[m][k] = *(const PG8_LAS bf16x8*)(lds + PG8_SA(b, h) + aoff + m * 2048 + k * 1024); } while (0)
; #define PG8_LDB(dst, b, h) do { _Pragma("unroll") for (int n = 0; n < 2; ++n) _Pragma("unroll") for (int k = 0; k < 2; ++k) dst[n][k] = *(const PG8_LAS bf16x8*)(lds + PG8_SB(b, h) + boff + n * 2048 + k * 1024); } while (0)
; #define PG8_MMA(ai, bj, At, Bt) do { __builtin_amdgcn_s_setprio(1); _Pragma("unroll") for (int m = 0; m < 4; ++m) _Pragma("unroll") for (int n = 0; n < 2; ++n) _Pragma("unroll") for (int k = 0; k < 2; ++k) \
;         acc[ai][bj][m][n] = __builtin_amdgcn_mfma_f32_16x16x32_bf16(Bt[n][k], At[m][k], acc[ai][bj][m][n], 0, 0, 0); __builtin_amdgcn_s_setprio(0); } while (0)
; #define PG8_WAIT_V(n) asm volatile("s_waitcnt vmcnt(" #n ")" ::: "memory")
; #define PG8_WAIT_L(n) asm volatile("s_waitcnt lgkmcnt(" #n ")" ::: "memory")
; #define PG8_BAR __builtin_amdgcn_s_barrier()
; #define PG8_SCHED __builtin_amdgcn_sched_barrier(0)
; template <class Epi, class Sched, bool ALIGN_EPI = false, bool SP2 = false>
; __device__ __forceinline__ void gemm_phase(PG8_LAS unsigned char* lds, const Gemm g, const Sched& S, const Epi& E) {
;     ...
;             PG8_WAIT_V(8); PG8_WAIT_L(0); PG8_BAR; PG8_MMA(1, 0, At, B0); PG8_MMA(1, 1, At, B1); PG8_BAR; PG8_SCHED;
;             PG8_LDB(B0, 1, 0); PG8_LDB(B1, 1, 1); PG8_SCHED; PG8_LDA(At, 1, 0); PG8_STAGEA(PG8_SA(0, 1), a2 + hstep, voffA);
;             PG8_WAIT_V(8); PG8_WAIT_L(0); PG8_BAR; PG8_MMA(0, 0, At, B0); PG8_MMA(0, 1, At, B1); PG8_BAR; PG8_SCHED;
	s_setprio 1
	v_mfma_f32_16x16x32_bf16 v[62:65], v[82:85], v[186:189], v[62:65]
	v_mfma_f32_16x16x32_bf16 v[58:61], v[94:97], v[186:189], v[58:61]
	v_mfma_f32_16x16x32_bf16 v[46:49], v[82:85], v[194:197], v[46:49]
	v_mfma_f32_16x16x32_bf16 v[42:45], v[94:97], v[194:197], v[42:45]
	v_mfma_f32_16x16x32_bf16 v[30:33], v[82:85], v[202:205], v[30:33]
	v_mfma_f32_16x16x32_bf16 v[26:29], v[94:97], v[202:205], v[26:29]
	v_mfma_f32_16x16x32_bf16 v[14:17], v[82:85], v[210:213], v[14:17]
	v_mfma_f32_16x16x32_bf16 v[10:13], v[94:97], v[210:213], v[10:13]
	v_mfma_f32_16x16x32_bf16 v[62:65], v[90:93], v[190:193], v[62:65]
	v_mfma_f32_16x16x32_bf16 v[58:61], v[158:161], v[190:193], v[58:61]
	v_mfma_f32_16x16x32_bf16 v[46:49], v[90:93], v[198:201], v[46:49]
	v_mfma_f32_16x16x32_bf16 v[42:45], v[158:161], v[198:201], v[42:45]
	v_mfma_f32_16x16x32_bf16 v[30:33], v[90:93], v[206:209], v[30:33]
	v_mfma_f32_16x16x32_bf16 v[26:29], v[158:161], v[206:209], v[26:29]
	v_mfma_f32_16x16x32_bf16 v[14:17], v[90:93], v[214:217], v[14:17]
	v_mfma_f32_16x16x32_bf16 v[10:13], v[158:161], v[214:217], v[10:13]
	s_setprio 0
	s_setprio 1
	v_mfma_f32_16x16x32_bf16 v[54:57], v[170:173], v[186:189], v[54:57]
	v_mfma_f32_16x16x32_bf16 v[50:53], v[178:181], v[186:189], v[50:53]
	v_mfma_f32_16x16x32_bf16 v[38:41], v[170:173], v[194:197], v[38:41]
	v_mfma_f32_16x16x32_bf16 v[34:37], v[178:181], v[194:197], v[34:37]
	v_mfma_f32_16x16x32_bf16 v[22:25], v[170:173], v[202:205], v[22:25]
	v_mfma_f32_16x16x32_bf16 v[18:21], v[178:181], v[202:205], v[18:21]
	v_mfma_f32_16x16x32_bf16 v[6:9], v[170:173], v[210:213], v[6:9]
	v_mfma_f32_16x16x32_bf16 v[2:5], v[178:181], v[210:213], v[2:5]
	v_mfma_f32_16x16x32_bf16 v[54:57], v[174:177], v[190:193], v[54:57]
	v_mfma_f32_16x16x32_bf16 v[50:53], v[182:185], v[190:193], v[50:53]
	v_mfma_f32_16x16x32_bf16 v[38:41], v[174:177], v[198:201], v[38:41]
	v_mfma_f32_16x16x32_bf16 v[34:37], v[182:185], v[198:201], v[34:37]
	v_mfma_f32_16x16x32_bf16 v[22:25], v[174:177], v[206:209], v[22:25]
	v_mfma_f32_16x16x32_bf16 v[18:21], v[182:185], v[206:209], v[18:21]
	v_mfma_f32_16x16x32_bf16 v[6:9], v[174:177], v[214:217], v[6:9]
	v_mfma_f32_16x16x32_bf16 v[2:5], v[182:185], v[214:217], v[2:5]
	s_setprio 0
	s_barrier
	v_add_u32_e32 v158, s25, v164
	v_add_u32_e32 v182, vcc_hi, v164
	ds_read_b128 v[82:85], v158
	ds_read_b128 v[90:93], v158 offset:1024
	ds_read_b128 v[94:97], v158 offset:2048
	ds_read_b128 v[158:161], v158 offset:3072
	ds_read_b128 v[170:173], v182
	ds_read_b128 v[174:177], v182 offset:1024
	ds_read_b128 v[178:181], v182 offset:2048
	ds_read_b128 v[182:185], v182 offset:3072
	s_mov_b32 m0, s21
	v_lshl_add_u64 v[224:225], s[80:81], 0, v[146:147]
	ds_read_b128 v[186:189], v168 offset:32768
	ds_read_b128 v[190:193], v168 offset:33792
	ds_read_b128 v[194:197], v168 offset:34816
	ds_read_b128 v[198:201], v168 offset:35840
	ds_read_b128 v[202:205], v168 offset:36864
	ds_read_b128 v[206:209], v168 offset:37888
	ds_read_b128 v[210:213], v168 offset:38912
	ds_read_b128 v[214:217], v168 offset:39936
	global_load_lds_dwordx4 v[224:225], off
	v_lshl_add_u64 v[224:225], s[80:81], 0, v[148:149]
	s_mov_b32 m0, s23
	s_nop 0
	global_load_lds_dwordx4 v[224:225], off
	s_waitcnt vmcnt(8)
	s_waitcnt lgkmcnt(0)
	s_barrier
	s_setprio 1
	v_mfma_f32_16x16x32_bf16 v[142:145], v[82:85], v[186:189], v[142:145]
	v_mfma_f32_16x16x32_bf16 v[138:141], v[94:97], v[186:189], v[138:141]
	v_mfma_f32_16x16x32_bf16 v[126:129], v[82:85], v[194:197], v[126:129]
	v_mfma_f32_16x16x32_bf16 v[122:125], v[94:97], v[194:197], v[122:125]
	v_mfma_f32_16x16x32_bf16 v[110:113], v[82:85], v[202:205], v[110:113]
	v_mfma_f32_16x16x32_bf16 v[106:109], v[94:97], v[202:205], v[106:109]
	v_mfma_f32_16x16x32_bf16 v[86:89], v[82:85], v[210:213], v[86:89]
	v_mfma_f32_16x16x32_bf16 v[78:81], v[94:97], v[210:213], v[78:81]
	v_mfma_f32_16x16x32_bf16 v[142:145], v[90:93], v[190:193], v[142:145]
	v_mfma_f32_16x16x32_bf16 v[138:141], v[158:161], v[190:193], v[138:141]
	v_mfma_f32_16x16x32_bf16 v[126:129], v[90:93], v[198:201], v[126:129]
	v_mfma_f32_16x16x32_bf16 v[122:125], v[158:161], v[198:201], v[122:125]
	v_mfma_f32_16x16x32_bf16 v[110:113], v[90:93], v[206:209], v[110:113]
	v_mfma_f32_16x16x32_bf16 v[106:109], v[158:161], v[206:209], v[106:109]
	v_mfma_f32_16x16x32_bf16 v[86:89], v[90:93], v[214:217], v[86:89]
	v_mfma_f32_16x16x32_bf16 v[78:81], v[158:161], v[214:217], v[78:81]
	s_setprio 0
	s_setprio 1
	v_mfma_f32_16x16x32_bf16 v[134:137], v[170:173], v[186:189], v[134:137]
	v_mfma_f32_16x16x32_bf16 v[130:133], v[178:181], v[186:189], v[130:133]
	v_mfma_f32_16x16x32_bf16 v[118:121], v[170:173], v[194:197], v[118:121]
	v_mfma_f32_16x16x32_bf16 v[114:117], v[178:181], v[194:197], v[114:117]
	v_mfma_f32_16x16x32_bf16 v[102:105], v[170:173], v[202:205], v[102:105]
	v_mfma_f32_16x16x32_bf16 v[98:101], v[178:181], v[202:205], v[98:101]
	v_mfma_f32_16x16x32_bf16 v[70:73], v[170:173], v[210:213], v[70:73]
	v_mfma_f32_16x16x32_bf16 v[66:69], v[178:181], v[210:213], v[66:69]
	v_mfma_f32_16x16x32_bf16 v[134:137], v[174:177], v[190:193], v[134:137]
	v_mfma_f32_16x16x32_bf16 v[130:133], v[182:185], v[190:193], v[130:133]
	v_mfma_f32_16x16x32_bf16 v[118:121], v[174:177], v[198:201], v[118:121]
	v_mfma_f32_16x16x32_bf16 v[114:117], v[182:185], v[198:201], v[114:117]
	v_mfma_f32_16x16x32_bf16 v[102:105], v[174:177], v[206:209], v[102:105]
	v_mfma_f32_16x16x32_bf16 v[98:101], v[182:185], v[206:209], v[98:101]
	v_mfma_f32_16x16x32_bf16 v[70:73], v[174:177], v[214:217], v[70:73]
	v_mfma_f32_16x16x32_bf16 v[66:69], v[182:185], v[214:217], v[66:69]
	s_setprio 0
	s_barrier
; #define PG8_STAGEA(bufoff, gbase, voff) PG8_STAGE_X(bufoff, gbase, voff, PG8_AUX_A)
; #define PG8_STAGEB(bufoff, gbase, voff) PG8_STAGE_X(bufoff, gbase, voff, PG8_AUX_B)
; #define PG8_LDA(dst, b, h) do { _Pragma("unroll") for (int m = 0; m < 4; ++m) _Pragma("unroll") for (int k = 0; k < 2; ++k) dst[m][k] = *(const PG8_LAS bf16x8*)(lds + PG8_SA(b, h) + aoff + m * 2048 + k * 1024); } while (0)
; #define PG8_MMA(ai, bj, At, Bt) do { __builtin_amdgcn_s_setprio(1); _Pragma("unroll") for (int m = 0; m < 4; ++m) _Pragma("unroll") for (int n = 0; n < 2; ++n) _Pragma("unroll") for (int k = 0; k < 2; ++k) \
;         acc[ai][bj][m][n] = __builtin_amdgcn_mfma_f32_16x16x32_bf16(Bt[n][k], At[m][k], acc[ai][bj][m][n], 0, 0, 0); __builtin_amdgcn_s_setprio(0); } while (0)
; #define PG8_WAIT_V(n) asm volatile("s_waitcnt vmcnt(" #n ")" ::: "memory")
; #define PG8_WAIT_L(n) asm volatile("s_waitcnt lgkmcnt(" #n ")" ::: "memory")
; #define PG8_BAR __builtin_amdgcn_s_barrier()
; #define PG8_SCHED __builtin_amdgcn_sched_barrier(0)
; template <class Epi, class Sched, bool ALIGN_EPI = false, bool SP2 = false>
; __device__ __forceinline__ void gemm_phase(PG8_LAS unsigned char* lds, const Gemm g, const Sched& S, const Epi& E) {
;     ...
;             PG8_LDA(At, 1, 1); PG8_STAGEB(PG8_SB(1, 0), b3, voffB); PG8_STAGEB(PG8_SB(1, 1), b3 + hstep, voffB); PG8_STAGEA(PG8_SA(1, 0), a3, voffA);
;             PG8_WAIT_V(8); PG8_WAIT_L(0); PG8_BAR; PG8_MMA(1, 0, At, B0); PG8_MMA(1, 1, At, B1); PG8_BAR; PG8_SCHED;
	s_mov_b32 m0, vcc_lo
	v_lshl_add_u64 v[162:163], v[162:163], 0, s[54:55]
	ds_read_b128 v[186:189], v168 offset:49152
	ds_read_b128 v[190:193], v168 offset:50176
	ds_read_b128 v[194:197], v168 offset:51200
	ds_read_b128 v[198:201], v168 offset:52224
	ds_read_b128 v[202:205], v168 offset:53248
	ds_read_b128 v[206:209], v168 offset:54272
	ds_read_b128 v[210:213], v168 offset:55296
	ds_read_b128 v[214:217], v168 offset:56320
	global_load_lds_dwordx4 v[162:163], off
	v_lshl_add_u64 v[162:163], v[218:219], 0, s[54:55]
	s_mov_b32 m0, s34
	s_nop 0
	global_load_lds_dwordx4 v[162:163], off
	v_lshl_add_u64 v[162:163], s[78:79], 0, v[146:147]
	s_mov_b32 m0, s35
	s_nop 0
	global_load_lds_dwordx4 v[162:163], off
	v_lshl_add_u64 v[162:163], s[78:79], 0, v[148:149]
	s_mov_b32 m0, s28
	s_nop 0
	global_load_lds_dwordx4 v[162:163], off
	v_lshl_add_u64 v[162:163], v[220:221], 0, s[54:55]
	s_mov_b32 m0, s90
	s_nop 0
	global_load_lds_dwordx4 v[162:163], off
	v_lshl_add_u64 v[162:163], v[222:223], 0, s[54:55]
	s_mov_b32 m0, s91
	s_nop 0
	global_load_lds_dwordx4 v[162:163], off
	s_waitcnt vmcnt(8)
	s_waitcnt lgkmcnt(0)
	s_barrier
	s_setprio 1
	v_mfma_f32_16x16x32_bf16 v[62:65], v[82:85], v[186:189], v[62:65]
	v_mfma_f32_16x16x32_bf16 v[58:61], v[94:97], v[186:189], v[58:61]
	v_mfma_f32_16x16x32_bf16 v[46:49], v[82:85], v[194:197], v[46:49]
	v_mfma_f32_16x16x32_bf16 v[42:45], v[94:97], v[194:197], v[42:45]
	v_mfma_f32_16x16x32_bf16 v[30:33], v[82:85], v[202:205], v[30:33]
	v_mfma_f32_16x16x32_bf16 v[26:29], v[94:97], v[202:205], v[26:29]
	v_mfma_f32_16x16x32_bf16 v[14:17], v[82:85], v[210:213], v[14:17]
	v_mfma_f32_16x16x32_bf16 v[10:13], v[94:97], v[210:213], v[10:13]
	v_mfma_f32_16x16x32_bf16 v[62:65], v[90:93], v[190:193], v[62:65]
	v_mfma_f32_16x16x32_bf16 v[58:61], v[158:161], v[190:193], v[58:61]
	v_mfma_f32_16x16x32_bf16 v[46:49], v[90:93], v[198:201], v[46:49]
	v_mfma_f32_16x16x32_bf16 v[42:45], v[158:161], v[198:201], v[42:45]
	v_mfma_f32_16x16x32_bf16 v[30:33], v[90:93], v[206:209], v[30:33]
	v_mfma_f32_16x16x32_bf16 v[26:29], v[158:161], v[206:209], v[26:29]
	v_mfma_f32_16x16x32_bf16 v[14:17], v[90:93], v[214:217], v[14:17]
	v_mfma_f32_16x16x32_bf16 v[10:13], v[158:161], v[214:217], v[10:13]
	s_setprio 0
	s_setprio 1
	v_mfma_f32_16x16x32_bf16 v[54:57], v[170:173], v[186:189], v[54:57]
	v_mfma_f32_16x16x32_bf16 v[50:53], v[178:181], v[186:189], v[50:53]
	v_mfma_f32_16x16x32_bf16 v[38:41], v[170:173], v[194:197], v[38:41]
	v_mfma_f32_16x16x32_bf16 v[34:37], v[178:181], v[194:197], v[34:37]
	v_mfma_f32_16x16x32_bf16 v[22:25], v[170:173], v[202:205], v[22:25]
	v_mfma_f32_16x16x32_bf16 v[18:21], v[178:181], v[202:205], v[18:21]
	v_mfma_f32_16x16x32_bf16 v[6:9], v[170:173], v[210:213], v[6:9]
	v_mfma_f32_16x16x32_bf16 v[2:5], v[178:181], v[210:213], v[2:5]
	v_mfma_f32_16x16x32_bf16 v[54:57], v[174:177], v[190:193], v[54:57]
	v_mfma_f32_16x16x32_bf16 v[50:53], v[182:185], v[190:193], v[50:53]
	v_mfma_f32_16x16x32_bf16 v[38:41], v[174:177], v[198:201], v[38:41]
	v_mfma_f32_16x16x32_bf16 v[34:37], v[182:185], v[198:201], v[34:37]
	v_mfma_f32_16x16x32_bf16 v[22:25], v[174:177], v[206:209], v[22:25]
	v_mfma_f32_16x16x32_bf16 v[18:21], v[182:185], v[206:209], v[18:21]
	v_mfma_f32_16x16x32_bf16 v[6:9], v[174:177], v[214:217], v[6:9]
	v_mfma_f32_16x16x32_bf16 v[2:5], v[182:185], v[214:217], v[2:5]
	s_setprio 0
	s_barrier
	s_mov_b64 s[74:75], s[76:77]
	s_mov_b32 s96, s97
	s_cbranch_scc0 .LBB0_643
	s_and_b64 vcc, exec, s[56:57]
	s_cbranch_vccz .LBB0_646
	s_barrier

; #define PG8_STAGEA(bufoff, gbase, voff) PG8_STAGE_X(bufoff, gbase, voff, PG8_AUX_A)
; #define PG8_STAGEB(bufoff, gbase, voff) PG8_STAGE_X(bufoff, gbase, voff, PG8_AUX_B)
; #define PG8_LDA(dst, b, h) do { _Pragma("unroll") for (int m = 0; m < 4; ++m) _Pragma("unroll") for (int k = 0; k < 2; ++k) dst[m][k] = *(const PG8_LAS bf16x8*)(lds + PG8_SA(b, h) + aoff + m * 2048 + k * 1024); } while (0)
; #define PG8_LDB(dst, b, h) do { _Pragma("unroll") for (int n = 0; n < 2; ++n) _Pragma("unroll") for (int k = 0; k < 2; ++k) dst[n][k] = *(const PG8_LAS bf16x8*)(lds + PG8_SB(b, h) + boff + n * 2048 + k * 1024); } while (0)
; #define PG8_MMA(ai, bj, At, Bt) do { __builtin_amdgcn_s_setprio(1); _Pragma("unroll") for (int m = 0; m < 4; ++m) _Pragma("unroll") for (int n = 0; n < 2; ++n) _Pragma("unroll") for (int k = 0; k < 2; ++k) \
;         acc[ai][bj][m][n] = __builtin_amdgcn_mfma_f32_16x16x32_bf16(Bt[n][k], At[m][k], acc[ai][bj][m][n], 0, 0, 0); __builtin_amdgcn_s_setprio(0); } while (0)
; #define PG8_WAIT_V(n) asm volatile("s_waitcnt vmcnt(" #n ")" ::: "memory")
; #define PG8_WAIT_L(n) asm volatile("s_waitcnt lgkmcnt(" #n ")" ::: "memory")
; template <class Epi, class Sched, bool ALIGN_EPI = false, bool SP2 = false>
; __device__ __forceinline__ void gemm_phase(PG8_LAS unsigned char* lds, const Gemm g, const Sched& S, const Epi& E) {
;     ...
;             const bool last = (t == nt - 2);
;             if constexpr (HasMid<Epi>::value) { if (t == ns) E.mid(acc, cur, wr, wc, fr, fq); }
;             const char* sA1 = (t + 1 >= ns) ? cA2 : cA; const char* sA2 = (t + 2 >= ns) ? cA2 : cA; const char* sB2 = (t + 2 >= ns) ? cB2 : cB;
;             const char* a1 = sA1 + (size_t)(t + 1) * kstep;
;             const char* a2 = last ? nA : sA2 + (size_t)(t + 2) * kstep; const char* b2 = last ? nB : sB2 + (size_t)(t + 2) * kstep;
;             const char* a3 = a2 + kstep; const char* b3 = b2 + kstep;
;             if (last && has_next) S.a_ready(nxt);
;             if constexpr (SP2) {
;             PG8_LDB(B0, 0, 0); PG8_LDB(B1, 0, 1); PG8_SCHED; PG8_LDA(At, 0, 0); PG8_STAGEA(PG8_SA(1, 1), a1 + hstep, voffA);
;             PG8_WAIT_V(8); PG8_WAIT_L(0); PG8_BAR; PG8_MMA(0, 0, At, B0); PG8_MMA(0, 1, At, B1); PG8_BAR; PG8_SCHED;
;             PG8_LDA(At, 0, 1); PG8_STAGEB(PG8_SB(0, 0), b2, voffB); PG8_STAGEB(PG8_SB(0, 1), b2 + hstep, voffB); PG8_STAGEA(PG8_SA(0, 0), a2, voffA);
.LBB0_734:
	s_add_i32 s90, s74, 2
	s_cmp_gt_u32 s90, 29
	s_cselect_b64 s[34:35], -1, 0
	s_and_b64 vcc, s[34:35], exec
	s_cselect_b32 s29, s50, s70
	ds_read_b128 v[150:153], v156
	ds_read_b128 v[162:165], v156 offset:1024
	ds_read_b128 v[166:169], v156 offset:2048
	ds_read_b128 v[170:173], v156 offset:3072
	ds_read_b128 v[174:177], v157
	ds_read_b128 v[178:181], v157 offset:1024
	ds_read_b128 v[182:185], v157 offset:2048
	ds_read_b128 v[186:189], v157 offset:3072
	s_cselect_b32 s24, s47, s69
	s_cselect_b32 s25, s46, s68
	s_cselect_b32 s28, s51, s71
	s_add_u32 s29, s29, s72
	s_addc_u32 s28, s28, s73
	s_add_u32 s29, s29, 0xfff80080
	s_addc_u32 s28, s28, -1
	s_add_u32 s25, s25, s72
	s_addc_u32 s24, s24, s73
	s_add_u32 s25, s25, 0xfff80080
	s_addc_u32 s24, s24, -1
	s_cmp_eq_u32 s74, 28
	s_cselect_b32 s74, s87, s25
	s_cselect_b32 s77, s63, s28
	s_cselect_b32 s76, s86, s29
	s_cselect_b32 s75, s61, s24
	v_lshl_add_u64 v[222:223], v[146:147], 0, s[72:73]
	s_add_i32 m0, s21, 0xc000
	ds_read_b128 v[190:193], v158
	ds_read_b128 v[194:197], v158 offset:1024
	ds_read_b128 v[198:201], v158 offset:2048
	ds_read_b128 v[202:205], v158 offset:3072
	ds_read_b128 v[206:209], v158 offset:4096
	ds_read_b128 v[210:213], v158 offset:5120
	ds_read_b128 v[214:217], v158 offset:6144
	ds_read_b128 v[218:221], v158 offset:7168
	global_load_lds_dwordx4 v[222:223], off
	v_lshl_add_u64 v[222:223], v[148:149], 0, s[72:73]
	s_add_i32 m0, s21, 0xe000
	s_nop 0
	global_load_lds_dwordx4 v[222:223], off
	s_waitcnt vmcnt(8)
	s_waitcnt lgkmcnt(0)
	s_barrier
	s_setprio 1
	v_mfma_f32_16x16x32_bf16 v[126:129], v[150:153], v[190:193], v[126:129]
	v_mfma_f32_16x16x32_bf16 v[122:125], v[166:169], v[190:193], v[122:125]
	v_mfma_f32_16x16x32_bf16 v[110:113], v[150:153], v[198:201], v[110:113]
	v_mfma_f32_16x16x32_bf16 v[106:109], v[166:169], v[198:201], v[106:109]
	v_mfma_f32_16x16x32_bf16 v[94:97], v[150:153], v[206:209], v[94:97]
	v_mfma_f32_16x16x32_bf16 v[90:93], v[166:169], v[206:209], v[90:93]
	v_mfma_f32_16x16x32_bf16 v[78:81], v[150:153], v[214:217], v[78:81]
	v_mfma_f32_16x16x32_bf16 v[74:77], v[166:169], v[214:217], v[74:77]
	v_mfma_f32_16x16x32_bf16 v[126:129], v[162:165], v[194:197], v[126:129]
	v_mfma_f32_16x16x32_bf16 v[122:125], v[170:173], v[194:197], v[122:125]
	v_mfma_f32_16x16x32_bf16 v[110:113], v[162:165], v[202:205], v[110:113]
	v_mfma_f32_16x16x32_bf16 v[106:109], v[170:173], v[202:205], v[106:109]
	v_mfma_f32_16x16x32_bf16 v[94:97], v[162:165], v[210:213], v[94:97]
	v_mfma_f32_16x16x32_bf16 v[90:93], v[170:173], v[210:213], v[90:93]
	v_mfma_f32_16x16x32_bf16 v[78:81], v[162:165], v[218:221], v[78:81]
	v_mfma_f32_16x16x32_bf16 v[74:77], v[170:173], v[218:221], v[74:77]
	s_setprio 0
	s_setprio 1
	v_mfma_f32_16x16x32_bf16 v[118:121], v[174:177], v[190:193], v[118:121]
	v_mfma_f32_16x16x32_bf16 v[114:117], v[182:185], v[190:193], v[114:117]
	v_mfma_f32_16x16x32_bf16 v[102:105], v[174:177], v[198:201], v[102:105]
	v_mfma_f32_16x16x32_bf16 v[98:101], v[182:185], v[198:201], v[98:101]
	v_mfma_f32_16x16x32_bf16 v[86:89], v[174:177], v[206:209], v[86:89]
	v_mfma_f32_16x16x32_bf16 v[82:85], v[182:185], v[206:209], v[82:85]
	v_mfma_f32_16x16x32_bf16 v[70:73], v[174:177], v[214:217], v[70:73]
	v_mfma_f32_16x16x32_bf16 v[66:69], v[182:185], v[214:217], v[66:69]
	v_mfma_f32_16x16x32_bf16 v[118:121], v[178:181], v[194:197], v[118:121]
	v_mfma_f32_16x16x32_bf16 v[114:117], v[186:189], v[194:197], v[114:117]
	v_mfma_f32_16x16x32_bf16 v[102:105], v[178:181], v[202:205], v[102:105]
	v_mfma_f32_16x16x32_bf16 v[98:101], v[186:189], v[202:205], v[98:101]
	v_mfma_f32_16x16x32_bf16 v[86:89], v[178:181], v[210:213], v[86:89]
	v_mfma_f32_16x16x32_bf16 v[82:85], v[186:189], v[210:213], v[82:85]
	v_mfma_f32_16x16x32_bf16 v[70:73], v[178:181], v[218:221], v[70:73]
	v_mfma_f32_16x16x32_bf16 v[66:69], v[186:189], v[218:221], v[66:69]
	s_setprio 0
	s_barrier
	s_add_i32 s24, s81, s9
	v_lshl_add_u64 v[222:223], s[74:75], 0, v[134:135]
	s_mov_b32 m0, s24
	ds_read_b128 v[190:193], v158 offset:16384
	ds_read_b128 v[194:197], v158 offset:17408
	ds_read_b128 v[198:201], v158 offset:18432
	ds_read_b128 v[202:205], v158 offset:19456
	ds_read_b128 v[206:209], v158 offset:20480
	ds_read_b128 v[210:213], v158 offset:21504
	ds_read_b128 v[214:217], v158 offset:22528
	ds_read_b128 v[218:221], v158 offset:23552
	global_load_lds_dwordx4 v[222:223], off
	s_add_i32 m0, s24, 0x2000
	s_add_u32 s34, s74, 0x80000
	v_lshl_add_u64 v[224:225], s[74:75], 0, v[130:131]
	s_addc_u32 s35, s75, 0
	s_add_i32 s24, s82, s9
	global_load_lds_dwordx4 v[224:225], off
	v_lshl_add_u64 v[226:227], s[34:35], 0, v[134:135]
	s_mov_b32 m0, s24
	v_lshl_add_u64 v[228:229], s[76:77], 0, v[132:133]
	global_load_lds_dwordx4 v[226:227], off
	v_lshl_add_u64 v[226:227], s[34:35], 0, v[130:131]
	s_add_i32 m0, s24, 0x2000
	s_nop 0
	global_load_lds_dwordx4 v[226:227], off
	v_lshl_add_u64 v[226:227], s[76:77], 0, v[136:137]
	s_mov_b32 m0, s21
	s_nop 0
	global_load_lds_dwordx4 v[226:227], off
	s_mov_b32 m0, s23
	s_nop 0
	global_load_lds_dwordx4 v[228:229], off
	s_waitcnt vmcnt(8)
	s_waitcnt lgkmcnt(0)
	s_barrier
; #define PG8_STAGEA(bufoff, gbase, voff) PG8_STAGE_X(bufoff, gbase, voff, PG8_AUX_A)
; #define PG8_LDA(dst, b, h) do { _Pragma("unroll") for (int m = 0; m < 4; ++m) _Pragma("unroll") for (int k = 0; k < 2; ++k) dst[m][k] = *(const PG8_LAS bf16x8*)(lds + PG8_SA(b, h) + aoff + m * 2048 + k * 1024); } while (0)
; #define PG8_LDB(dst, b, h) do { _Pragma("unroll") for (int n = 0; n < 2; ++n) _Pragma("unroll") for (int k = 0; k < 2; ++k) dst[n][k] = *(const PG8_LAS bf16x8*)(lds + PG8_SB(b, h) + boff + n * 2048 + k * 1024); } while (0)
; #define PG8_MMA(ai, bj, At, Bt) do { __builtin_amdgcn_s_setprio(1); _Pragma("unroll") for (int m = 0; m < 4; ++m) _Pragma("unroll") for (int n = 0; n < 2; ++n) _Pragma("unroll") for (int k = 0; k < 2; ++k) \
;         acc[ai][bj][m][n] = __builtin_amdgcn_mfma_f32_16x16x32_bf16(Bt[n][k], At[m][k], acc[ai][bj][m][n], 0, 0, 0); __builtin_amdgcn_s_setprio(0); } while (0)
; #define PG8_WAIT_V(n) asm volatile("s_waitcnt vmcnt(" #n ")" ::: "memory")
; #define PG8_WAIT_L(n) asm volatile("s_waitcnt lgkmcnt(" #n ")" ::: "memory")
; #define PG8_BAR __builtin_amdgcn_s_barrier()
; #define PG8_SCHED __builtin_amdgcn_sched_barrier(0)
; template <class Epi, class Sched, bool ALIGN_EPI = false, bool SP2 = false>
; __device__ __forceinline__ void gemm_phase(PG8_LAS unsigned char* lds, const Gemm g, const Sched& S, const Epi& E) {
;     ...
;             PG8_WAIT_V(8); PG8_WAIT_L(0); PG8_BAR; PG8_MMA(1, 0, At, B0); PG8_MMA(1, 1, At, B1); PG8_BAR; PG8_SCHED;
;             PG8_LDB(B0, 1, 0); PG8_LDB(B1, 1, 1); PG8_SCHED; PG8_LDA(At, 1, 0); PG8_STAGEA(PG8_SA(0, 1), a2 + hstep, voffA);
;             PG8_WAIT_V(8); PG8_WAIT_L(0); PG8_BAR; PG8_MMA(0, 0, At, B0); PG8_MMA(0, 1, At, B1); PG8_BAR; PG8_SCHED;
	s_setprio 1
	v_mfma_f32_16x16x32_bf16 v[62:65], v[150:153], v[190:193], v[62:65]
	v_mfma_f32_16x16x32_bf16 v[58:61], v[166:169], v[190:193], v[58:61]
	v_mfma_f32_16x16x32_bf16 v[46:49], v[150:153], v[198:201], v[46:49]
	v_mfma_f32_16x16x32_bf16 v[42:45], v[166:169], v[198:201], v[42:45]
	v_mfma_f32_16x16x32_bf16 v[30:33], v[150:153], v[206:209], v[30:33]
	v_mfma_f32_16x16x32_bf16 v[26:29], v[166:169], v[206:209], v[26:29]
	v_mfma_f32_16x16x32_bf16 v[14:17], v[150:153], v[214:217], v[14:17]
	v_mfma_f32_16x16x32_bf16 v[10:13], v[166:169], v[214:217], v[10:13]
	v_mfma_f32_16x16x32_bf16 v[62:65], v[162:165], v[194:197], v[62:65]
	v_mfma_f32_16x16x32_bf16 v[58:61], v[170:173], v[194:197], v[58:61]
	v_mfma_f32_16x16x32_bf16 v[46:49], v[162:165], v[202:205], v[46:49]
	v_mfma_f32_16x16x32_bf16 v[42:45], v[170:173], v[202:205], v[42:45]
	v_mfma_f32_16x16x32_bf16 v[30:33], v[162:165], v[210:213], v[30:33]
	v_mfma_f32_16x16x32_bf16 v[26:29], v[170:173], v[210:213], v[26:29]
	v_mfma_f32_16x16x32_bf16 v[14:17], v[162:165], v[218:221], v[14:17]
	v_mfma_f32_16x16x32_bf16 v[10:13], v[170:173], v[218:221], v[10:13]
	s_setprio 0
	s_setprio 1
	v_mfma_f32_16x16x32_bf16 v[54:57], v[174:177], v[190:193], v[54:57]
	v_mfma_f32_16x16x32_bf16 v[50:53], v[182:185], v[190:193], v[50:53]
	v_mfma_f32_16x16x32_bf16 v[38:41], v[174:177], v[198:201], v[38:41]
	v_mfma_f32_16x16x32_bf16 v[34:37], v[182:185], v[198:201], v[34:37]
	v_mfma_f32_16x16x32_bf16 v[22:25], v[174:177], v[206:209], v[22:25]
	v_mfma_f32_16x16x32_bf16 v[18:21], v[182:185], v[206:209], v[18:21]
	v_mfma_f32_16x16x32_bf16 v[6:9], v[174:177], v[214:217], v[6:9]
	v_mfma_f32_16x16x32_bf16 v[2:5], v[182:185], v[214:217], v[2:5]
	v_mfma_f32_16x16x32_bf16 v[54:57], v[178:181], v[194:197], v[54:57]
	v_mfma_f32_16x16x32_bf16 v[50:53], v[186:189], v[194:197], v[50:53]
	v_mfma_f32_16x16x32_bf16 v[38:41], v[178:181], v[202:205], v[38:41]
	v_mfma_f32_16x16x32_bf16 v[34:37], v[186:189], v[202:205], v[34:37]
	v_mfma_f32_16x16x32_bf16 v[22:25], v[178:181], v[210:213], v[22:25]
	v_mfma_f32_16x16x32_bf16 v[18:21], v[186:189], v[210:213], v[18:21]
	v_mfma_f32_16x16x32_bf16 v[6:9], v[178:181], v[218:221], v[6:9]
	v_mfma_f32_16x16x32_bf16 v[2:5], v[186:189], v[218:221], v[2:5]
	s_setprio 0
	s_barrier
	s_add_i32 s24, 0, 0x18000
	v_add_u32_e32 v161, s24, v154
	s_add_i32 s25, 0, 0x1c000
	ds_read_b128 v[150:153], v161
	ds_read_b128 v[162:165], v161 offset:1024
	ds_read_b128 v[166:169], v161 offset:2048
	ds_read_b128 v[170:173], v161 offset:3072
	v_add_u32_e32 v161, s25, v154
	ds_read_b128 v[174:177], v161
	ds_read_b128 v[178:181], v161 offset:1024
	ds_read_b128 v[182:185], v161 offset:2048
	ds_read_b128 v[186:189], v161 offset:3072
	s_add_u32 s34, s76, 0x80000
	s_addc_u32 s35, s77, 0
	s_mov_b32 m0, s26
	v_lshl_add_u64 v[230:231], s[34:35], 0, v[136:137]
	ds_read_b128 v[190:193], v158 offset:32768
	ds_read_b128 v[194:197], v158 offset:33792
	ds_read_b128 v[198:201], v158 offset:34816
	ds_read_b128 v[202:205], v158 offset:35840
	ds_read_b128 v[206:209], v158 offset:36864
	ds_read_b128 v[210:213], v158 offset:37888
	ds_read_b128 v[214:217], v158 offset:38912
	ds_read_b128 v[218:221], v158 offset:39936
	global_load_lds_dwordx4 v[230:231], off
	v_lshl_add_u64 v[230:231], s[34:35], 0, v[132:133]
	s_mov_b32 m0, s27
	s_nop 0
	global_load_lds_dwordx4 v[230:231], off
	s_waitcnt vmcnt(8)
	s_waitcnt lgkmcnt(0)
	s_barrier
	s_setprio 1
	v_mfma_f32_16x16x32_bf16 v[126:129], v[150:153], v[190:193], v[126:129]
	v_mfma_f32_16x16x32_bf16 v[122:125], v[166:169], v[190:193], v[122:125]
	v_mfma_f32_16x16x32_bf16 v[110:113], v[150:153], v[198:201], v[110:113]
	v_mfma_f32_16x16x32_bf16 v[106:109], v[166:169], v[198:201], v[106:109]
	v_mfma_f32_16x16x32_bf16 v[94:97], v[150:153], v[206:209], v[94:97]
	v_mfma_f32_16x16x32_bf16 v[90:93], v[166:169], v[206:209], v[90:93]
	v_mfma_f32_16x16x32_bf16 v[78:81], v[150:153], v[214:217], v[78:81]
	v_mfma_f32_16x16x32_bf16 v[74:77], v[166:169], v[214:217], v[74:77]
	v_mfma_f32_16x16x32_bf16 v[126:129], v[162:165], v[194:197], v[126:129]
	v_mfma_f32_16x16x32_bf16 v[122:125], v[170:173], v[194:197], v[122:125]
	v_mfma_f32_16x16x32_bf16 v[110:113], v[162:165], v[202:205], v[110:113]
	v_mfma_f32_16x16x32_bf16 v[106:109], v[170:173], v[202:205], v[106:109]
	v_mfma_f32_16x16x32_bf16 v[94:97], v[162:165], v[210:213], v[94:97]
	v_mfma_f32_16x16x32_bf16 v[90:93], v[170:173], v[210:213], v[90:93]
	v_mfma_f32_16x16x32_bf16 v[78:81], v[162:165], v[218:221], v[78:81]
	v_mfma_f32_16x16x32_bf16 v[74:77], v[170:173], v[218:221], v[74:77]
	s_setprio 0
	s_setprio 1
	v_mfma_f32_16x16x32_bf16 v[118:121], v[174:177], v[190:193], v[118:121]
	v_mfma_f32_16x16x32_bf16 v[114:117], v[182:185], v[190:193], v[114:117]
	v_mfma_f32_16x16x32_bf16 v[102:105], v[174:177], v[198:201], v[102:105]
	v_mfma_f32_16x16x32_bf16 v[98:101], v[182:185], v[198:201], v[98:101]
	v_mfma_f32_16x16x32_bf16 v[86:89], v[174:177], v[206:209], v[86:89]
	v_mfma_f32_16x16x32_bf16 v[82:85], v[182:185], v[206:209], v[82:85]
	v_mfma_f32_16x16x32_bf16 v[70:73], v[174:177], v[214:217], v[70:73]
	v_mfma_f32_16x16x32_bf16 v[66:69], v[182:185], v[214:217], v[66:69]
	v_mfma_f32_16x16x32_bf16 v[118:121], v[178:181], v[194:197], v[118:121]
	v_mfma_f32_16x16x32_bf16 v[114:117], v[186:189], v[194:197], v[114:117]
	v_mfma_f32_16x16x32_bf16 v[102:105], v[178:181], v[202:205], v[102:105]
	v_mfma_f32_16x16x32_bf16 v[98:101], v[186:189], v[202:205], v[98:101]
	v_mfma_f32_16x16x32_bf16 v[86:89], v[178:181], v[210:213], v[86:89]
	v_mfma_f32_16x16x32_bf16 v[82:85], v[186:189], v[210:213], v[82:85]
	v_mfma_f32_16x16x32_bf16 v[70:73], v[178:181], v[218:221], v[70:73]
	v_mfma_f32_16x16x32_bf16 v[66:69], v[186:189], v[218:221], v[66:69]
	s_setprio 0
	s_barrier
; #define PG8_STAGEA(bufoff, gbase, voff) PG8_STAGE_X(bufoff, gbase, voff, PG8_AUX_A)
; #define PG8_STAGEB(bufoff, gbase, voff) PG8_STAGE_X(bufoff, gbase, voff, PG8_AUX_B)
; #define PG8_LDA(dst, b, h) do { _Pragma("unroll") for (int m = 0; m < 4; ++m) _Pragma("unroll") for (int k = 0; k < 2; ++k) dst[m][k] = *(const PG8_LAS bf16x8*)(lds + PG8_SA(b, h) + aoff + m * 2048 + k * 1024); } while (0)
; #define PG8_MMA(ai, bj, At, Bt) do { __builtin_amdgcn_s_setprio(1); _Pragma("unroll") for (int m = 0; m < 4; ++m) _Pragma("unroll") for (int n = 0; n < 2; ++n) _Pragma("unroll") for (int k = 0; k < 2; ++k) \
;         acc[ai][bj][m][n] = __builtin_amdgcn_mfma_f32_16x16x32_bf16(Bt[n][k], At[m][k], acc[ai][bj][m][n], 0, 0, 0); __builtin_amdgcn_s_setprio(0); } while (0)
; #define PG8_WAIT_V(n) asm volatile("s_waitcnt vmcnt(" #n ")" ::: "memory")
; #define PG8_WAIT_L(n) asm volatile("s_waitcnt lgkmcnt(" #n ")" ::: "memory")
; #define PG8_BAR __builtin_amdgcn_s_barrier()
; #define PG8_SCHED __builtin_amdgcn_sched_barrier(0)
; template <class Epi, class Sched, bool ALIGN_EPI = false, bool SP2 = false>
; __device__ __forceinline__ void gemm_phase(PG8_LAS unsigned char* lds, const Gemm g, const Sched& S, const Epi& E) {
;     ...
;             PG8_LDA(At, 1, 1); PG8_STAGEB(PG8_SB(1, 0), b3, voffB); PG8_STAGEB(PG8_SB(1, 1), b3 + hstep, voffB); PG8_STAGEA(PG8_SA(1, 0), a3, voffA);
;             PG8_WAIT_V(8); PG8_WAIT_L(0); PG8_BAR; PG8_MMA(1, 0, At, B0); PG8_MMA(1, 1, At, B1); PG8_BAR; PG8_SCHED;
	s_add_i32 s24, s24, s9
	v_lshl_add_u64 v[222:223], v[222:223], 0, s[54:55]
	s_mov_b32 m0, s24
	ds_read_b128 v[190:193], v158 offset:49152
	ds_read_b128 v[194:197], v158 offset:50176
	ds_read_b128 v[198:201], v158 offset:51200
	ds_read_b128 v[202:205], v158 offset:52224
	ds_read_b128 v[206:209], v158 offset:53248
	ds_read_b128 v[210:213], v158 offset:54272
	ds_read_b128 v[214:217], v158 offset:55296
	ds_read_b128 v[218:221], v158 offset:56320
	global_load_lds_dwordx4 v[222:223], off
	s_add_i32 m0, s24, 0x2000
	s_add_u32 s34, s74, 0x80080
	v_lshl_add_u64 v[222:223], v[224:225], 0, s[54:55]
	s_addc_u32 s35, s75, 0
	s_add_i32 s24, s25, s9
	global_load_lds_dwordx4 v[222:223], off
	v_lshl_add_u64 v[222:223], s[34:35], 0, v[134:135]
	s_mov_b32 m0, s24
	s_nop 0
	global_load_lds_dwordx4 v[222:223], off
	v_lshl_add_u64 v[222:223], s[34:35], 0, v[130:131]
	s_add_i32 m0, s24, 0x2000
	s_nop 0
	global_load_lds_dwordx4 v[222:223], off
	v_lshl_add_u64 v[222:223], v[226:227], 0, s[54:55]
	s_mov_b32 m0, s79
	s_nop 0
	global_load_lds_dwordx4 v[222:223], off
	v_lshl_add_u64 v[222:223], v[228:229], 0, s[54:55]
	s_mov_b32 m0, s80
	s_nop 0
	global_load_lds_dwordx4 v[222:223], off
	s_waitcnt vmcnt(8)
	s_waitcnt lgkmcnt(0)
	s_barrier
	s_setprio 1
	v_mfma_f32_16x16x32_bf16 v[62:65], v[150:153], v[190:193], v[62:65]
	v_mfma_f32_16x16x32_bf16 v[58:61], v[166:169], v[190:193], v[58:61]
	v_mfma_f32_16x16x32_bf16 v[46:49], v[150:153], v[198:201], v[46:49]
	v_mfma_f32_16x16x32_bf16 v[42:45], v[166:169], v[198:201], v[42:45]
	v_mfma_f32_16x16x32_bf16 v[30:33], v[150:153], v[206:209], v[30:33]
	v_mfma_f32_16x16x32_bf16 v[26:29], v[166:169], v[206:209], v[26:29]
	v_mfma_f32_16x16x32_bf16 v[14:17], v[150:153], v[214:217], v[14:17]
	v_mfma_f32_16x16x32_bf16 v[10:13], v[166:169], v[214:217], v[10:13]
	v_mfma_f32_16x16x32_bf16 v[62:65], v[162:165], v[194:197], v[62:65]
	v_mfma_f32_16x16x32_bf16 v[58:61], v[170:173], v[194:197], v[58:61]
	v_mfma_f32_16x16x32_bf16 v[46:49], v[162:165], v[202:205], v[46:49]
	v_mfma_f32_16x16x32_bf16 v[42:45], v[170:173], v[202:205], v[42:45]
	v_mfma_f32_16x16x32_bf16 v[30:33], v[162:165], v[210:213], v[30:33]
	v_mfma_f32_16x16x32_bf16 v[26:29], v[170:173], v[210:213], v[26:29]
	v_mfma_f32_16x16x32_bf16 v[14:17], v[162:165], v[218:221], v[14:17]
	v_mfma_f32_16x16x32_bf16 v[10:13], v[170:173], v[218:221], v[10:13]
	s_setprio 0
	s_setprio 1
	v_mfma_f32_16x16x32_bf16 v[54:57], v[174:177], v[190:193], v[54:57]
	v_mfma_f32_16x16x32_bf16 v[50:53], v[182:185], v[190:193], v[50:53]
	v_mfma_f32_16x16x32_bf16 v[38:41], v[174:177], v[198:201], v[38:41]
	v_mfma_f32_16x16x32_bf16 v[34:37], v[182:185], v[198:201], v[34:37]
	v_mfma_f32_16x16x32_bf16 v[22:25], v[174:177], v[206:209], v[22:25]
	v_mfma_f32_16x16x32_bf16 v[18:21], v[182:185], v[206:209], v[18:21]
	v_mfma_f32_16x16x32_bf16 v[6:9], v[174:177], v[214:217], v[6:9]
	v_mfma_f32_16x16x32_bf16 v[2:5], v[182:185], v[214:217], v[2:5]
	v_mfma_f32_16x16x32_bf16 v[54:57], v[178:181], v[194:197], v[54:57]
	v_mfma_f32_16x16x32_bf16 v[50:53], v[186:189], v[194:197], v[50:53]
	v_mfma_f32_16x16x32_bf16 v[38:41], v[178:181], v[202:205], v[38:41]
	v_mfma_f32_16x16x32_bf16 v[34:37], v[186:189], v[202:205], v[34:37]
	v_mfma_f32_16x16x32_bf16 v[22:25], v[178:181], v[210:213], v[22:25]
	v_mfma_f32_16x16x32_bf16 v[18:21], v[186:189], v[210:213], v[18:21]
	v_mfma_f32_16x16x32_bf16 v[6:9], v[178:181], v[218:221], v[6:9]
	v_mfma_f32_16x16x32_bf16 v[2:5], v[186:189], v[218:221], v[2:5]
	s_setprio 0
	s_barrier
	s_add_u32 s72, s72, 0x100
	s_addc_u32 s73, s73, 0
	s_mov_b32 s74, s90
	s_cbranch_vccz .LBB0_734
	s_and_b64 vcc, exec, s[56:57]
	s_cbranch_vccz .LBB0_737
	s_barrier

; #define PG8_STAGEA(bufoff, gbase, voff) PG8_STAGE_X(bufoff, gbase, voff, PG8_AUX_A)
; #define PG8_STAGEB(bufoff, gbase, voff) PG8_STAGE_X(bufoff, gbase, voff, PG8_AUX_B)
; #define PG8_LDA(dst, b, h) do { _Pragma("unroll") for (int m = 0; m < 4; ++m) _Pragma("unroll") for (int k = 0; k < 2; ++k) dst[m][k] = *(const PG8_LAS bf16x8*)(lds + PG8_SA(b, h) + aoff + m * 2048 + k * 1024); } while (0)
; #define PG8_LDB(dst, b, h) do { _Pragma("unroll") for (int n = 0; n < 2; ++n) _Pragma("unroll") for (int k = 0; k < 2; ++k) dst[n][k] = *(const PG8_LAS bf16x8*)(lds + PG8_SB(b, h) + boff + n * 2048 + k * 1024); } while (0)
; #define PG8_MMA(ai, bj, At, Bt) do { __builtin_amdgcn_s_setprio(1); _Pragma("unroll") for (int m = 0; m < 4; ++m) _Pragma("unroll") for (int n = 0; n < 2; ++n) _Pragma("unroll") for (int k = 0; k < 2; ++k) \
;         acc[ai][bj][m][n] = __builtin_amdgcn_mfma_f32_16x16x32_bf16(Bt[n][k], At[m][k], acc[ai][bj][m][n], 0, 0, 0); __builtin_amdgcn_s_setprio(0); } while (0)
; #define PG8_WAIT_V(n) asm volatile("s_waitcnt vmcnt(" #n ")" ::: "memory")
; #define PG8_WAIT_L(n) asm volatile("s_waitcnt lgkmcnt(" #n ")" ::: "memory")
; template <class Epi, class Sched, bool ALIGN_EPI = false, bool SP2 = false>
; __device__ __forceinline__ void gemm_phase(PG8_LAS unsigned char* lds, const Gemm g, const Sched& S, const Epi& E) {
;     ...
;             const bool last = (t == nt - 2);
;             if constexpr (HasMid<Epi>::value) { if (t == ns) E.mid(acc, cur, wr, wc, fr, fq); }
;             const char* sA1 = (t + 1 >= ns) ? cA2 : cA; const char* sA2 = (t + 2 >= ns) ? cA2 : cA; const char* sB2 = (t + 2 >= ns) ? cB2 : cB;
;             const char* a1 = sA1 + (size_t)(t + 1) * kstep;
;             const char* a2 = last ? nA : sA2 + (size_t)(t + 2) * kstep; const char* b2 = last ? nB : sB2 + (size_t)(t + 2) * kstep;
;             const char* a3 = a2 + kstep; const char* b3 = b2 + kstep;
;             if (last && has_next) S.a_ready(nxt);
;             if constexpr (SP2) {
;             PG8_LDB(B0, 0, 0); PG8_LDB(B1, 0, 1); PG8_SCHED; PG8_LDA(At, 0, 0); PG8_STAGEA(PG8_SA(1, 1), a1 + hstep, voffA);
;             PG8_WAIT_V(8); PG8_WAIT_L(0); PG8_BAR; PG8_MMA(0, 0, At, B0); PG8_MMA(0, 1, At, B1); PG8_BAR; PG8_SCHED;
;             PG8_LDA(At, 0, 1); PG8_STAGEB(PG8_SB(0, 0), b2, voffB); PG8_STAGEB(PG8_SB(0, 1), b2 + hstep, voffB); PG8_STAGEA(PG8_SA(0, 0), a2, voffA);
.LBB0_750:
	s_add_i32 s91, s70, 2
	s_cmp_gt_u32 s91, 29
	s_cselect_b64 s[34:35], -1, 0
	s_and_b64 vcc, s[34:35], exec
	s_cselect_b32 s29, s4, s66
	ds_read_b128 v[152:155], v148
	ds_read_b128 v[156:159], v148 offset:1024
	ds_read_b128 v[160:163], v148 offset:2048
	ds_read_b128 v[164:167], v148 offset:3072
	ds_read_b128 v[168:171], v149
	ds_read_b128 v[172:175], v149 offset:1024
	ds_read_b128 v[176:179], v149 offset:2048
	ds_read_b128 v[180:183], v149 offset:3072
	s_cselect_b32 s24, s3, s65
	s_cselect_b32 s25, s2, s64
	s_cselect_b32 s28, s5, s67
	s_add_u32 s29, s29, s68
	s_addc_u32 s28, s28, s69
	s_add_u32 s29, s29, 0xfff80080
	s_addc_u32 s28, s28, -1
	s_add_u32 s25, s25, s68
	s_addc_u32 s24, s24, s69
	s_add_u32 s25, s25, 0xfff80080
	s_addc_u32 s24, s24, -1
	s_cmp_eq_u32 s70, 28
	s_cselect_b32 s70, s90, s25
	s_cselect_b32 s73, s55, s28
	s_cselect_b32 s72, s87, s29
	s_cselect_b32 s71, s53, s24
	v_lshl_add_u64 v[216:217], v[142:143], 0, s[68:69]
	s_add_i32 m0, s63, 0xc000
	ds_read_b128 v[184:187], v150
	ds_read_b128 v[188:191], v150 offset:1024
	ds_read_b128 v[192:195], v150 offset:2048
	ds_read_b128 v[196:199], v150 offset:3072
	ds_read_b128 v[200:203], v150 offset:4096
	ds_read_b128 v[204:207], v150 offset:5120
	ds_read_b128 v[208:211], v150 offset:6144
	ds_read_b128 v[212:215], v150 offset:7168
	global_load_lds_dwordx4 v[216:217], off
	v_lshl_add_u64 v[216:217], v[144:145], 0, s[68:69]
	s_add_i32 m0, s63, 0xe000
	s_nop 0
	global_load_lds_dwordx4 v[216:217], off
	s_waitcnt vmcnt(8)
	s_waitcnt lgkmcnt(0)
	s_barrier
	s_setprio 1
	v_mfma_f32_16x16x32_bf16 v[126:129], v[152:155], v[184:187], v[126:129]
	v_mfma_f32_16x16x32_bf16 v[122:125], v[160:163], v[184:187], v[122:125]
	v_mfma_f32_16x16x32_bf16 v[118:121], v[152:155], v[192:195], v[118:121]
	v_mfma_f32_16x16x32_bf16 v[110:113], v[160:163], v[192:195], v[110:113]
	v_mfma_f32_16x16x32_bf16 v[102:105], v[152:155], v[200:203], v[102:105]
	v_mfma_f32_16x16x32_bf16 v[94:97], v[160:163], v[200:203], v[94:97]
	v_mfma_f32_16x16x32_bf16 v[86:89], v[152:155], v[208:211], v[86:89]
	v_mfma_f32_16x16x32_bf16 v[78:81], v[160:163], v[208:211], v[78:81]
	v_mfma_f32_16x16x32_bf16 v[126:129], v[156:159], v[188:191], v[126:129]
	v_mfma_f32_16x16x32_bf16 v[122:125], v[164:167], v[188:191], v[122:125]
	v_mfma_f32_16x16x32_bf16 v[118:121], v[156:159], v[196:199], v[118:121]
	v_mfma_f32_16x16x32_bf16 v[110:113], v[164:167], v[196:199], v[110:113]
	v_mfma_f32_16x16x32_bf16 v[102:105], v[156:159], v[204:207], v[102:105]
	v_mfma_f32_16x16x32_bf16 v[94:97], v[164:167], v[204:207], v[94:97]
	v_mfma_f32_16x16x32_bf16 v[86:89], v[156:159], v[212:215], v[86:89]
	v_mfma_f32_16x16x32_bf16 v[78:81], v[164:167], v[212:215], v[78:81]
	s_setprio 0
	s_setprio 1
	v_mfma_f32_16x16x32_bf16 v[114:117], v[168:171], v[184:187], v[114:117]
	v_mfma_f32_16x16x32_bf16 v[106:109], v[176:179], v[184:187], v[106:109]
	v_mfma_f32_16x16x32_bf16 v[98:101], v[168:171], v[192:195], v[98:101]
	v_mfma_f32_16x16x32_bf16 v[90:93], v[176:179], v[192:195], v[90:93]
	v_mfma_f32_16x16x32_bf16 v[82:85], v[168:171], v[200:203], v[82:85]
	v_mfma_f32_16x16x32_bf16 v[74:77], v[176:179], v[200:203], v[74:77]
	v_mfma_f32_16x16x32_bf16 v[70:73], v[168:171], v[208:211], v[70:73]
	v_mfma_f32_16x16x32_bf16 v[66:69], v[176:179], v[208:211], v[66:69]
	v_mfma_f32_16x16x32_bf16 v[114:117], v[172:175], v[188:191], v[114:117]
	v_mfma_f32_16x16x32_bf16 v[106:109], v[180:183], v[188:191], v[106:109]
	v_mfma_f32_16x16x32_bf16 v[98:101], v[172:175], v[196:199], v[98:101]
	v_mfma_f32_16x16x32_bf16 v[90:93], v[180:183], v[196:199], v[90:93]
	v_mfma_f32_16x16x32_bf16 v[82:85], v[172:175], v[204:207], v[82:85]
	v_mfma_f32_16x16x32_bf16 v[74:77], v[180:183], v[204:207], v[74:77]
	v_mfma_f32_16x16x32_bf16 v[70:73], v[172:175], v[212:215], v[70:73]
	v_mfma_f32_16x16x32_bf16 v[66:69], v[180:183], v[212:215], v[66:69]
	s_setprio 0
	s_barrier
	s_add_i32 s24, s82, s74
	v_lshl_add_u64 v[216:217], s[70:71], 0, v[134:135]
	s_mov_b32 m0, s24
	ds_read_b128 v[184:187], v150 offset:16384
	ds_read_b128 v[188:191], v150 offset:17408
	ds_read_b128 v[192:195], v150 offset:18432
	ds_read_b128 v[196:199], v150 offset:19456
	ds_read_b128 v[200:203], v150 offset:20480
	ds_read_b128 v[204:207], v150 offset:21504
	ds_read_b128 v[208:211], v150 offset:22528
	ds_read_b128 v[212:215], v150 offset:23552
	global_load_lds_dwordx4 v[216:217], off
	s_add_i32 m0, s24, 0x2000
	s_add_u32 s34, s70, 0x80000
	v_lshl_add_u64 v[218:219], s[70:71], 0, v[130:131]
	s_addc_u32 s35, s71, 0
	s_add_i32 s24, s83, s74
	global_load_lds_dwordx4 v[218:219], off
	v_lshl_add_u64 v[220:221], s[34:35], 0, v[134:135]
	s_mov_b32 m0, s24
	v_lshl_add_u64 v[222:223], s[72:73], 0, v[132:133]
	global_load_lds_dwordx4 v[220:221], off
	v_lshl_add_u64 v[220:221], s[34:35], 0, v[130:131]
	s_add_i32 m0, s24, 0x2000
	s_nop 0
	global_load_lds_dwordx4 v[220:221], off
	v_lshl_add_u64 v[220:221], s[72:73], 0, v[136:137]
	s_mov_b32 m0, s63
	s_nop 0
	global_load_lds_dwordx4 v[220:221], off
	s_mov_b32 m0, s76
	s_nop 0
	global_load_lds_dwordx4 v[222:223], off
	s_waitcnt vmcnt(8)
	s_waitcnt lgkmcnt(0)
	s_barrier
; #define PG8_STAGEA(bufoff, gbase, voff) PG8_STAGE_X(bufoff, gbase, voff, PG8_AUX_A)
; #define PG8_LDA(dst, b, h) do { _Pragma("unroll") for (int m = 0; m < 4; ++m) _Pragma("unroll") for (int k = 0; k < 2; ++k) dst[m][k] = *(const PG8_LAS bf16x8*)(lds + PG8_SA(b, h) + aoff + m * 2048 + k * 1024); } while (0)
; #define PG8_LDB(dst, b, h) do { _Pragma("unroll") for (int n = 0; n < 2; ++n) _Pragma("unroll") for (int k = 0; k < 2; ++k) dst[n][k] = *(const PG8_LAS bf16x8*)(lds + PG8_SB(b, h) + boff + n * 2048 + k * 1024); } while (0)
; #define PG8_MMA(ai, bj, At, Bt) do { __builtin_amdgcn_s_setprio(1); _Pragma("unroll") for (int m = 0; m < 4; ++m) _Pragma("unroll") for (int n = 0; n < 2; ++n) _Pragma("unroll") for (int k = 0; k < 2; ++k) \
;         acc[ai][bj][m][n] = __builtin_amdgcn_mfma_f32_16x16x32_bf16(Bt[n][k], At[m][k], acc[ai][bj][m][n], 0, 0, 0); __builtin_amdgcn_s_setprio(0); } while (0)
; #define PG8_WAIT_V(n) asm volatile("s_waitcnt vmcnt(" #n ")" ::: "memory")
; #define PG8_WAIT_L(n) asm volatile("s_waitcnt lgkmcnt(" #n ")" ::: "memory")
; #define PG8_BAR __builtin_amdgcn_s_barrier()
; #define PG8_SCHED __builtin_amdgcn_sched_barrier(0)
; template <class Epi, class Sched, bool ALIGN_EPI = false, bool SP2 = false>
; __device__ __forceinline__ void gemm_phase(PG8_LAS unsigned char* lds, const Gemm g, const Sched& S, const Epi& E) {
;     ...
;             PG8_WAIT_V(8); PG8_WAIT_L(0); PG8_BAR; PG8_MMA(1, 0, At, B0); PG8_MMA(1, 1, At, B1); PG8_BAR; PG8_SCHED;
;             PG8_LDB(B0, 1, 0); PG8_LDB(B1, 1, 1); PG8_SCHED; PG8_LDA(At, 1, 0); PG8_STAGEA(PG8_SA(0, 1), a2 + hstep, voffA);
;             PG8_WAIT_V(8); PG8_WAIT_L(0); PG8_BAR; PG8_MMA(0, 0, At, B0); PG8_MMA(0, 1, At, B1); PG8_BAR; PG8_SCHED;
	s_setprio 1
	v_mfma_f32_16x16x32_bf16 v[62:65], v[152:155], v[184:187], v[62:65]
	v_mfma_f32_16x16x32_bf16 v[58:61], v[160:163], v[184:187], v[58:61]
	v_mfma_f32_16x16x32_bf16 v[54:57], v[152:155], v[192:195], v[54:57]
	v_mfma_f32_16x16x32_bf16 v[46:49], v[160:163], v[192:195], v[46:49]
	v_mfma_f32_16x16x32_bf16 v[38:41], v[152:155], v[200:203], v[38:41]
	v_mfma_f32_16x16x32_bf16 v[30:33], v[160:163], v[200:203], v[30:33]
	v_mfma_f32_16x16x32_bf16 v[22:25], v[152:155], v[208:211], v[22:25]
	v_mfma_f32_16x16x32_bf16 v[14:17], v[160:163], v[208:211], v[14:17]
	v_mfma_f32_16x16x32_bf16 v[62:65], v[156:159], v[188:191], v[62:65]
	v_mfma_f32_16x16x32_bf16 v[58:61], v[164:167], v[188:191], v[58:61]
	v_mfma_f32_16x16x32_bf16 v[54:57], v[156:159], v[196:199], v[54:57]
	v_mfma_f32_16x16x32_bf16 v[46:49], v[164:167], v[196:199], v[46:49]
	v_mfma_f32_16x16x32_bf16 v[38:41], v[156:159], v[204:207], v[38:41]
	v_mfma_f32_16x16x32_bf16 v[30:33], v[164:167], v[204:207], v[30:33]
	v_mfma_f32_16x16x32_bf16 v[22:25], v[156:159], v[212:215], v[22:25]
	v_mfma_f32_16x16x32_bf16 v[14:17], v[164:167], v[212:215], v[14:17]
	s_setprio 0
	s_setprio 1
	v_mfma_f32_16x16x32_bf16 v[50:53], v[168:171], v[184:187], v[50:53]
	v_mfma_f32_16x16x32_bf16 v[42:45], v[176:179], v[184:187], v[42:45]
	v_mfma_f32_16x16x32_bf16 v[34:37], v[168:171], v[192:195], v[34:37]
	v_mfma_f32_16x16x32_bf16 v[26:29], v[176:179], v[192:195], v[26:29]
	v_mfma_f32_16x16x32_bf16 v[18:21], v[168:171], v[200:203], v[18:21]
	v_mfma_f32_16x16x32_bf16 v[10:13], v[176:179], v[200:203], v[10:13]
	v_mfma_f32_16x16x32_bf16 v[6:9], v[168:171], v[208:211], v[6:9]
	v_mfma_f32_16x16x32_bf16 v[2:5], v[176:179], v[208:211], v[2:5]
	v_mfma_f32_16x16x32_bf16 v[50:53], v[172:175], v[188:191], v[50:53]
	v_mfma_f32_16x16x32_bf16 v[42:45], v[180:183], v[188:191], v[42:45]
	v_mfma_f32_16x16x32_bf16 v[34:37], v[172:175], v[196:199], v[34:37]
	v_mfma_f32_16x16x32_bf16 v[26:29], v[180:183], v[196:199], v[26:29]
	v_mfma_f32_16x16x32_bf16 v[18:21], v[172:175], v[204:207], v[18:21]
	v_mfma_f32_16x16x32_bf16 v[10:13], v[180:183], v[204:207], v[10:13]
	v_mfma_f32_16x16x32_bf16 v[6:9], v[172:175], v[212:215], v[6:9]
	v_mfma_f32_16x16x32_bf16 v[2:5], v[180:183], v[212:215], v[2:5]
	s_setprio 0
	s_barrier
	s_add_i32 s24, 0, 0x18000
	v_add_u32_e32 v151, s24, v146
	s_add_i32 s25, 0, 0x1c000
	ds_read_b128 v[152:155], v151
	ds_read_b128 v[156:159], v151 offset:1024
	ds_read_b128 v[160:163], v151 offset:2048
	ds_read_b128 v[164:167], v151 offset:3072
	v_add_u32_e32 v151, s25, v146
	ds_read_b128 v[168:171], v151
	ds_read_b128 v[172:175], v151 offset:1024
	ds_read_b128 v[176:179], v151 offset:2048
	ds_read_b128 v[180:183], v151 offset:3072
	s_add_u32 s34, s72, 0x80000
	s_addc_u32 s35, s73, 0
	s_mov_b32 m0, s77
	v_lshl_add_u64 v[224:225], s[34:35], 0, v[136:137]
	ds_read_b128 v[184:187], v150 offset:32768
	ds_read_b128 v[188:191], v150 offset:33792
	ds_read_b128 v[192:195], v150 offset:34816
	ds_read_b128 v[196:199], v150 offset:35840
	ds_read_b128 v[200:203], v150 offset:36864
	ds_read_b128 v[204:207], v150 offset:37888
	ds_read_b128 v[208:211], v150 offset:38912
	ds_read_b128 v[212:215], v150 offset:39936
	global_load_lds_dwordx4 v[224:225], off
	v_lshl_add_u64 v[224:225], s[34:35], 0, v[132:133]
	s_mov_b32 m0, s78
	s_nop 0
	global_load_lds_dwordx4 v[224:225], off
	s_waitcnt vmcnt(8)
	s_waitcnt lgkmcnt(0)
	s_barrier
	s_setprio 1
	v_mfma_f32_16x16x32_bf16 v[126:129], v[152:155], v[184:187], v[126:129]
	v_mfma_f32_16x16x32_bf16 v[122:125], v[160:163], v[184:187], v[122:125]
	v_mfma_f32_16x16x32_bf16 v[118:121], v[152:155], v[192:195], v[118:121]
	v_mfma_f32_16x16x32_bf16 v[110:113], v[160:163], v[192:195], v[110:113]
	v_mfma_f32_16x16x32_bf16 v[102:105], v[152:155], v[200:203], v[102:105]
	v_mfma_f32_16x16x32_bf16 v[94:97], v[160:163], v[200:203], v[94:97]
	v_mfma_f32_16x16x32_bf16 v[86:89], v[152:155], v[208:211], v[86:89]
	v_mfma_f32_16x16x32_bf16 v[78:81], v[160:163], v[208:211], v[78:81]
	v_mfma_f32_16x16x32_bf16 v[126:129], v[156:159], v[188:191], v[126:129]
	v_mfma_f32_16x16x32_bf16 v[122:125], v[164:167], v[188:191], v[122:125]
	v_mfma_f32_16x16x32_bf16 v[118:121], v[156:159], v[196:199], v[118:121]
	v_mfma_f32_16x16x32_bf16 v[110:113], v[164:167], v[196:199], v[110:113]
	v_mfma_f32_16x16x32_bf16 v[102:105], v[156:159], v[204:207], v[102:105]
	v_mfma_f32_16x16x32_bf16 v[94:97], v[164:167], v[204:207], v[94:97]
	v_mfma_f32_16x16x32_bf16 v[86:89], v[156:159], v[212:215], v[86:89]
	v_mfma_f32_16x16x32_bf16 v[78:81], v[164:167], v[212:215], v[78:81]
	s_setprio 0
	s_setprio 1
	v_mfma_f32_16x16x32_bf16 v[114:117], v[168:171], v[184:187], v[114:117]
	v_mfma_f32_16x16x32_bf16 v[106:109], v[176:179], v[184:187], v[106:109]
	v_mfma_f32_16x16x32_bf16 v[98:101], v[168:171], v[192:195], v[98:101]
	v_mfma_f32_16x16x32_bf16 v[90:93], v[176:179], v[192:195], v[90:93]
	v_mfma_f32_16x16x32_bf16 v[82:85], v[168:171], v[200:203], v[82:85]
	v_mfma_f32_16x16x32_bf16 v[74:77], v[176:179], v[200:203], v[74:77]
	v_mfma_f32_16x16x32_bf16 v[70:73], v[168:171], v[208:211], v[70:73]
	v_mfma_f32_16x16x32_bf16 v[66:69], v[176:179], v[208:211], v[66:69]
	v_mfma_f32_16x16x32_bf16 v[114:117], v[172:175], v[188:191], v[114:117]
	v_mfma_f32_16x16x32_bf16 v[106:109], v[180:183], v[188:191], v[106:109]
	v_mfma_f32_16x16x32_bf16 v[98:101], v[172:175], v[196:199], v[98:101]
	v_mfma_f32_16x16x32_bf16 v[90:93], v[180:183], v[196:199], v[90:93]
	v_mfma_f32_16x16x32_bf16 v[82:85], v[172:175], v[204:207], v[82:85]
	v_mfma_f32_16x16x32_bf16 v[74:77], v[180:183], v[204:207], v[74:77]
	v_mfma_f32_16x16x32_bf16 v[70:73], v[172:175], v[212:215], v[70:73]
	v_mfma_f32_16x16x32_bf16 v[66:69], v[180:183], v[212:215], v[66:69]
	s_setprio 0
	s_barrier
; #define PG8_STAGEA(bufoff, gbase, voff) PG8_STAGE_X(bufoff, gbase, voff, PG8_AUX_A)
; #define PG8_STAGEB(bufoff, gbase, voff) PG8_STAGE_X(bufoff, gbase, voff, PG8_AUX_B)
; #define PG8_LDA(dst, b, h) do { _Pragma("unroll") for (int m = 0; m < 4; ++m) _Pragma("unroll") for (int k = 0; k < 2; ++k) dst[m][k] = *(const PG8_LAS bf16x8*)(lds + PG8_SA(b, h) + aoff + m * 2048 + k * 1024); } while (0)
; #define PG8_MMA(ai, bj, At, Bt) do { __builtin_amdgcn_s_setprio(1); _Pragma("unroll") for (int m = 0; m < 4; ++m) _Pragma("unroll") for (int n = 0; n < 2; ++n) _Pragma("unroll") for (int k = 0; k < 2; ++k) \
;         acc[ai][bj][m][n] = __builtin_amdgcn_mfma_f32_16x16x32_bf16(Bt[n][k], At[m][k], acc[ai][bj][m][n], 0, 0, 0); __builtin_amdgcn_s_setprio(0); } while (0)
; #define PG8_WAIT_V(n) asm volatile("s_waitcnt vmcnt(" #n ")" ::: "memory")
; #define PG8_WAIT_L(n) asm volatile("s_waitcnt lgkmcnt(" #n ")" ::: "memory")
; #define PG8_BAR __builtin_amdgcn_s_barrier()
; #define PG8_SCHED __builtin_amdgcn_sched_barrier(0)
; template <class Epi, class Sched, bool ALIGN_EPI = false, bool SP2 = false>
; __device__ __forceinline__ void gemm_phase(PG8_LAS unsigned char* lds, const Gemm g, const Sched& S, const Epi& E) {
;     ...
;             PG8_LDA(At, 1, 1); PG8_STAGEB(PG8_SB(1, 0), b3, voffB); PG8_STAGEB(PG8_SB(1, 1), b3 + hstep, voffB); PG8_STAGEA(PG8_SA(1, 0), a3, voffA);
;             PG8_WAIT_V(8); PG8_WAIT_L(0); PG8_BAR; PG8_MMA(1, 0, At, B0); PG8_MMA(1, 1, At, B1); PG8_BAR; PG8_SCHED;
	s_add_i32 s24, s24, s74
	v_lshl_add_u64 v[216:217], v[216:217], 0, s[46:47]
	s_mov_b32 m0, s24
	ds_read_b128 v[184:187], v150 offset:49152
	ds_read_b128 v[188:191], v150 offset:50176
	ds_read_b128 v[192:195], v150 offset:51200
	ds_read_b128 v[196:199], v150 offset:52224
	ds_read_b128 v[200:203], v150 offset:53248
	ds_read_b128 v[204:207], v150 offset:54272
	ds_read_b128 v[208:211], v150 offset:55296
	ds_read_b128 v[212:215], v150 offset:56320
	global_load_lds_dwordx4 v[216:217], off
	s_add_i32 m0, s24, 0x2000
	s_add_u32 s34, s70, 0x80080
	v_lshl_add_u64 v[216:217], v[218:219], 0, s[46:47]
	s_addc_u32 s35, s71, 0
	s_add_i32 s24, s25, s74
	global_load_lds_dwordx4 v[216:217], off
	v_lshl_add_u64 v[216:217], s[34:35], 0, v[134:135]
	s_mov_b32 m0, s24
	s_nop 0
	global_load_lds_dwordx4 v[216:217], off
	v_lshl_add_u64 v[216:217], s[34:35], 0, v[130:131]
	s_add_i32 m0, s24, 0x2000
	s_nop 0
	global_load_lds_dwordx4 v[216:217], off
	v_lshl_add_u64 v[216:217], v[220:221], 0, s[46:47]
	s_mov_b32 m0, s79
	s_nop 0
	global_load_lds_dwordx4 v[216:217], off
	v_lshl_add_u64 v[216:217], v[222:223], 0, s[46:47]
	s_mov_b32 m0, s80
	s_nop 0
	global_load_lds_dwordx4 v[216:217], off
	s_waitcnt vmcnt(8)
	s_waitcnt lgkmcnt(0)
	s_barrier
	s_setprio 1
	v_mfma_f32_16x16x32_bf16 v[62:65], v[152:155], v[184:187], v[62:65]
	v_mfma_f32_16x16x32_bf16 v[58:61], v[160:163], v[184:187], v[58:61]
	v_mfma_f32_16x16x32_bf16 v[54:57], v[152:155], v[192:195], v[54:57]
	v_mfma_f32_16x16x32_bf16 v[46:49], v[160:163], v[192:195], v[46:49]
	v_mfma_f32_16x16x32_bf16 v[38:41], v[152:155], v[200:203], v[38:41]
	v_mfma_f32_16x16x32_bf16 v[30:33], v[160:163], v[200:203], v[30:33]
	v_mfma_f32_16x16x32_bf16 v[22:25], v[152:155], v[208:211], v[22:25]
	v_mfma_f32_16x16x32_bf16 v[14:17], v[160:163], v[208:211], v[14:17]
	v_mfma_f32_16x16x32_bf16 v[62:65], v[156:159], v[188:191], v[62:65]
	v_mfma_f32_16x16x32_bf16 v[58:61], v[164:167], v[188:191], v[58:61]
	v_mfma_f32_16x16x32_bf16 v[54:57], v[156:159], v[196:199], v[54:57]
	v_mfma_f32_16x16x32_bf16 v[46:49], v[164:167], v[196:199], v[46:49]
	v_mfma_f32_16x16x32_bf16 v[38:41], v[156:159], v[204:207], v[38:41]
	v_mfma_f32_16x16x32_bf16 v[30:33], v[164:167], v[204:207], v[30:33]
	v_mfma_f32_16x16x32_bf16 v[22:25], v[156:159], v[212:215], v[22:25]
	v_mfma_f32_16x16x32_bf16 v[14:17], v[164:167], v[212:215], v[14:17]
	s_setprio 0
	s_setprio 1
	v_mfma_f32_16x16x32_bf16 v[50:53], v[168:171], v[184:187], v[50:53]
	v_mfma_f32_16x16x32_bf16 v[42:45], v[176:179], v[184:187], v[42:45]
	v_mfma_f32_16x16x32_bf16 v[34:37], v[168:171], v[192:195], v[34:37]
	v_mfma_f32_16x16x32_bf16 v[26:29], v[176:179], v[192:195], v[26:29]
	v_mfma_f32_16x16x32_bf16 v[18:21], v[168:171], v[200:203], v[18:21]
	v_mfma_f32_16x16x32_bf16 v[10:13], v[176:179], v[200:203], v[10:13]
	v_mfma_f32_16x16x32_bf16 v[6:9], v[168:171], v[208:211], v[6:9]
	v_mfma_f32_16x16x32_bf16 v[2:5], v[176:179], v[208:211], v[2:5]
	v_mfma_f32_16x16x32_bf16 v[50:53], v[172:175], v[188:191], v[50:53]
	v_mfma_f32_16x16x32_bf16 v[42:45], v[180:183], v[188:191], v[42:45]
	v_mfma_f32_16x16x32_bf16 v[34:37], v[172:175], v[196:199], v[34:37]
	v_mfma_f32_16x16x32_bf16 v[26:29], v[180:183], v[196:199], v[26:29]
	v_mfma_f32_16x16x32_bf16 v[18:21], v[172:175], v[204:207], v[18:21]
	v_mfma_f32_16x16x32_bf16 v[10:13], v[180:183], v[204:207], v[10:13]
	v_mfma_f32_16x16x32_bf16 v[6:9], v[172:175], v[212:215], v[6:9]
	v_mfma_f32_16x16x32_bf16 v[2:5], v[180:183], v[212:215], v[2:5]
	s_setprio 0
	s_barrier
	s_add_u32 s68, s68, 0x100
	s_addc_u32 s69, s69, 0
	s_mov_b32 s70, s91
	s_cbranch_vccz .LBB0_750
	s_and_b64 vcc, exec, s[48:49]
	s_cbranch_vccz .LBB0_753
	s_barrier

; #define PG8_STAGEA(bufoff, gbase, voff) PG8_STAGE_X(bufoff, gbase, voff, PG8_AUX_A)
; #define PG8_STAGEB(bufoff, gbase, voff) PG8_STAGE_X(bufoff, gbase, voff, PG8_AUX_B)
; #define PG8_LDA(dst, b, h) do { _Pragma("unroll") for (int m = 0; m < 4; ++m) _Pragma("unroll") for (int k = 0; k < 2; ++k) dst[m][k] = *(const PG8_LAS bf16x8*)(lds + PG8_SA(b, h) + aoff + m * 2048 + k * 1024); } while (0)
; #define PG8_LDB(dst, b, h) do { _Pragma("unroll") for (int n = 0; n < 2; ++n) _Pragma("unroll") for (int k = 0; k < 2; ++k) dst[n][k] = *(const PG8_LAS bf16x8*)(lds + PG8_SB(b, h) + boff + n * 2048 + k * 1024); } while (0)
; #define PG8_MMA(ai, bj, At, Bt) do { __builtin_amdgcn_s_setprio(1); _Pragma("unroll") for (int m = 0; m < 4; ++m) _Pragma("unroll") for (int n = 0; n < 2; ++n) _Pragma("unroll") for (int k = 0; k < 2; ++k) \
;         acc[ai][bj][m][n] = __builtin_amdgcn_mfma_f32_16x16x32_bf16(Bt[n][k], At[m][k], acc[ai][bj][m][n], 0, 0, 0); __builtin_amdgcn_s_setprio(0); } while (0)
; #define PG8_WAIT_V(n) asm volatile("s_waitcnt vmcnt(" #n ")" ::: "memory")
; #define PG8_WAIT_L(n) asm volatile("s_waitcnt lgkmcnt(" #n ")" ::: "memory")
; template <class Epi, class Sched, bool ALIGN_EPI = false, bool SP2 = false>
; __device__ __forceinline__ void gemm_phase(PG8_LAS unsigned char* lds, const Gemm g, const Sched& S, const Epi& E) {
;     ...
;             const bool last = (t == nt - 2);
;             if constexpr (HasMid<Epi>::value) { if (t == ns) E.mid(acc, cur, wr, wc, fr, fq); }
;             const char* sA1 = (t + 1 >= ns) ? cA2 : cA; const char* sA2 = (t + 2 >= ns) ? cA2 : cA; const char* sB2 = (t + 2 >= ns) ? cB2 : cB;
;             const char* a1 = sA1 + (size_t)(t + 1) * kstep;
;             const char* a2 = last ? nA : sA2 + (size_t)(t + 2) * kstep; const char* b2 = last ? nB : sB2 + (size_t)(t + 2) * kstep;
;             const char* a3 = a2 + kstep; const char* b3 = b2 + kstep;
;             if (last && has_next) S.a_ready(nxt);
;             if constexpr (SP2) {
;             PG8_LDB(B0, 0, 0); PG8_LDB(B1, 0, 1); PG8_SCHED; PG8_LDA(At, 0, 0); PG8_STAGEA(PG8_SA(1, 1), a1 + hstep, voffA);
;             PG8_WAIT_V(8); PG8_WAIT_L(0); PG8_BAR; PG8_MMA(0, 0, At, B0); PG8_MMA(0, 1, At, B1); PG8_BAR; PG8_SCHED;
;             PG8_LDA(At, 0, 1); PG8_STAGEB(PG8_SB(0, 0), b2, voffB); PG8_STAGEB(PG8_SB(0, 1), b2 + hstep, voffB); PG8_STAGEA(PG8_SA(0, 0), a2, voffA);
.LBB0_766:
	s_add_i32 s91, s70, 2
	s_cmp_gt_u32 s91, 29
	s_cselect_b64 s[72:73], -1, 0
	s_and_b64 vcc, s[72:73], exec
	s_cselect_b32 s29, s4, s66
	ds_read_b128 v[152:155], v148
	ds_read_b128 v[156:159], v148 offset:1024
	ds_read_b128 v[160:163], v148 offset:2048
	ds_read_b128 v[164:167], v148 offset:3072
	ds_read_b128 v[168:171], v149
	ds_read_b128 v[172:175], v149 offset:1024
	ds_read_b128 v[176:179], v149 offset:2048
	ds_read_b128 v[180:183], v149 offset:3072
	s_cselect_b32 s24, s3, s65
	s_cselect_b32 s25, s2, s64
	s_cselect_b32 s28, s5, s67
	s_add_u32 s29, s29, s68
	s_addc_u32 s28, s28, s69
	s_add_u32 s29, s29, 0xfff80080
	s_addc_u32 s28, s28, -1
	s_add_u32 s25, s25, s68
	s_addc_u32 s24, s24, s69
	s_add_u32 s25, s25, 0xfff80080
	s_addc_u32 s24, s24, -1
	s_cmp_eq_u32 s70, 28
	s_cselect_b32 s70, s90, s25
	s_cselect_b32 s73, s55, s28
	s_cselect_b32 s72, s87, s29
	s_cselect_b32 s71, s53, s24
	v_lshl_add_u64 v[216:217], v[142:143], 0, s[68:69]
	s_add_i32 m0, s63, 0xc000
	ds_read_b128 v[184:187], v150
	ds_read_b128 v[188:191], v150 offset:1024
	ds_read_b128 v[192:195], v150 offset:2048
	ds_read_b128 v[196:199], v150 offset:3072
	ds_read_b128 v[200:203], v150 offset:4096
	ds_read_b128 v[204:207], v150 offset:5120
	ds_read_b128 v[208:211], v150 offset:6144
	ds_read_b128 v[212:215], v150 offset:7168
	global_load_lds_dwordx4 v[216:217], off
	v_lshl_add_u64 v[216:217], v[144:145], 0, s[68:69]
	s_add_i32 m0, s63, 0xe000
	s_nop 0
	global_load_lds_dwordx4 v[216:217], off
	s_waitcnt vmcnt(8)
	s_waitcnt lgkmcnt(0)
	s_barrier
	s_setprio 1
	v_mfma_f32_16x16x32_bf16 v[126:129], v[152:155], v[184:187], v[126:129]
	v_mfma_f32_16x16x32_bf16 v[122:125], v[160:163], v[184:187], v[122:125]
	v_mfma_f32_16x16x32_bf16 v[118:121], v[152:155], v[192:195], v[118:121]
	v_mfma_f32_16x16x32_bf16 v[110:113], v[160:163], v[192:195], v[110:113]
	v_mfma_f32_16x16x32_bf16 v[102:105], v[152:155], v[200:203], v[102:105]
	v_mfma_f32_16x16x32_bf16 v[94:97], v[160:163], v[200:203], v[94:97]
	v_mfma_f32_16x16x32_bf16 v[86:89], v[152:155], v[208:211], v[86:89]
	v_mfma_f32_16x16x32_bf16 v[78:81], v[160:163], v[208:211], v[78:81]
	v_mfma_f32_16x16x32_bf16 v[126:129], v[156:159], v[188:191], v[126:129]
	v_mfma_f32_16x16x32_bf16 v[122:125], v[164:167], v[188:191], v[122:125]
	v_mfma_f32_16x16x32_bf16 v[118:121], v[156:159], v[196:199], v[118:121]
	v_mfma_f32_16x16x32_bf16 v[110:113], v[164:167], v[196:199], v[110:113]
	v_mfma_f32_16x16x32_bf16 v[102:105], v[156:159], v[204:207], v[102:105]
	v_mfma_f32_16x16x32_bf16 v[94:97], v[164:167], v[204:207], v[94:97]
	v_mfma_f32_16x16x32_bf16 v[86:89], v[156:159], v[212:215], v[86:89]
	v_mfma_f32_16x16x32_bf16 v[78:81], v[164:167], v[212:215], v[78:81]
	s_setprio 0
	s_setprio 1
	v_mfma_f32_16x16x32_bf16 v[114:117], v[168:171], v[184:187], v[114:117]
	v_mfma_f32_16x16x32_bf16 v[106:109], v[176:179], v[184:187], v[106:109]
	v_mfma_f32_16x16x32_bf16 v[98:101], v[168:171], v[192:195], v[98:101]
	v_mfma_f32_16x16x32_bf16 v[90:93], v[176:179], v[192:195], v[90:93]
	v_mfma_f32_16x16x32_bf16 v[82:85], v[168:171], v[200:203], v[82:85]
	v_mfma_f32_16x16x32_bf16 v[74:77], v[176:179], v[200:203], v[74:77]
	v_mfma_f32_16x16x32_bf16 v[70:73], v[168:171], v[208:211], v[70:73]
	v_mfma_f32_16x16x32_bf16 v[66:69], v[176:179], v[208:211], v[66:69]
	v_mfma_f32_16x16x32_bf16 v[114:117], v[172:175], v[188:191], v[114:117]
	v_mfma_f32_16x16x32_bf16 v[106:109], v[180:183], v[188:191], v[106:109]
	v_mfma_f32_16x16x32_bf16 v[98:101], v[172:175], v[196:199], v[98:101]
	v_mfma_f32_16x16x32_bf16 v[90:93], v[180:183], v[196:199], v[90:93]
	v_mfma_f32_16x16x32_bf16 v[82:85], v[172:175], v[204:207], v[82:85]
	v_mfma_f32_16x16x32_bf16 v[74:77], v[180:183], v[204:207], v[74:77]
	v_mfma_f32_16x16x32_bf16 v[70:73], v[172:175], v[212:215], v[70:73]
	v_mfma_f32_16x16x32_bf16 v[66:69], v[180:183], v[212:215], v[66:69]
	s_setprio 0
	s_barrier
	s_add_i32 s24, s81, s23
	v_lshl_add_u64 v[216:217], s[70:71], 0, v[134:135]
	s_mov_b32 m0, s24
	ds_read_b128 v[184:187], v150 offset:16384
	ds_read_b128 v[188:191], v150 offset:17408
	ds_read_b128 v[192:195], v150 offset:18432
	ds_read_b128 v[196:199], v150 offset:19456
	ds_read_b128 v[200:203], v150 offset:20480
	ds_read_b128 v[204:207], v150 offset:21504
	ds_read_b128 v[208:211], v150 offset:22528
	ds_read_b128 v[212:215], v150 offset:23552
	global_load_lds_dwordx4 v[216:217], off
	s_add_i32 m0, s24, 0x2000
	s_add_u32 s92, s70, 0x80000
	v_lshl_add_u64 v[218:219], s[70:71], 0, v[130:131]
	s_addc_u32 s93, s71, 0
	s_add_i32 s24, s82, s23
	global_load_lds_dwordx4 v[218:219], off
	v_lshl_add_u64 v[220:221], s[92:93], 0, v[134:135]
	s_mov_b32 m0, s24
	v_lshl_add_u64 v[222:223], s[72:73], 0, v[132:133]
	global_load_lds_dwordx4 v[220:221], off
	v_lshl_add_u64 v[220:221], s[92:93], 0, v[130:131]
	s_add_i32 m0, s24, 0x2000
	s_nop 0
	global_load_lds_dwordx4 v[220:221], off
	v_lshl_add_u64 v[220:221], s[72:73], 0, v[136:137]
	s_mov_b32 m0, s63
	s_nop 0
	global_load_lds_dwordx4 v[220:221], off
	s_mov_b32 m0, s75
	s_nop 0
	global_load_lds_dwordx4 v[222:223], off
	s_waitcnt vmcnt(8)
	s_waitcnt lgkmcnt(0)
	s_barrier
; #define PG8_STAGEA(bufoff, gbase, voff) PG8_STAGE_X(bufoff, gbase, voff, PG8_AUX_A)
; #define PG8_LDA(dst, b, h) do { _Pragma("unroll") for (int m = 0; m < 4; ++m) _Pragma("unroll") for (int k = 0; k < 2; ++k) dst[m][k] = *(const PG8_LAS bf16x8*)(lds + PG8_SA(b, h) + aoff + m * 2048 + k * 1024); } while (0)
; #define PG8_LDB(dst, b, h) do { _Pragma("unroll") for (int n = 0; n < 2; ++n) _Pragma("unroll") for (int k = 0; k < 2; ++k) dst[n][k] = *(const PG8_LAS bf16x8*)(lds + PG8_SB(b, h) + boff + n * 2048 + k * 1024); } while (0)
; #define PG8_MMA(ai, bj, At, Bt) do { __builtin_amdgcn_s_setprio(1); _Pragma("unroll") for (int m = 0; m < 4; ++m) _Pragma("unroll") for (int n = 0; n < 2; ++n) _Pragma("unroll") for (int k = 0; k < 2; ++k) \
;         acc[ai][bj][m][n] = __builtin_amdgcn_mfma_f32_16x16x32_bf16(Bt[n][k], At[m][k], acc[ai][bj][m][n], 0, 0, 0); __builtin_amdgcn_s_setprio(0); } while (0)
; #define PG8_WAIT_V(n) asm volatile("s_waitcnt vmcnt(" #n ")" ::: "memory")
; #define PG8_WAIT_L(n) asm volatile("s_waitcnt lgkmcnt(" #n ")" ::: "memory")
; #define PG8_BAR __builtin_amdgcn_s_barrier()
; #define PG8_SCHED __builtin_amdgcn_sched_barrier(0)
; template <class Epi, class Sched, bool ALIGN_EPI = false, bool SP2 = false>
; __device__ __forceinline__ void gemm_phase(PG8_LAS unsigned char* lds, const Gemm g, const Sched& S, const Epi& E) {
;     ...
;             PG8_WAIT_V(8); PG8_WAIT_L(0); PG8_BAR; PG8_MMA(1, 0, At, B0); PG8_MMA(1, 1, At, B1); PG8_BAR; PG8_SCHED;
;             PG8_LDB(B0, 1, 0); PG8_LDB(B1, 1, 1); PG8_SCHED; PG8_LDA(At, 1, 0); PG8_STAGEA(PG8_SA(0, 1), a2 + hstep, voffA);
;             PG8_WAIT_V(8); PG8_WAIT_L(0); PG8_BAR; PG8_MMA(0, 0, At, B0); PG8_MMA(0, 1, At, B1); PG8_BAR; PG8_SCHED;
	s_setprio 1
	v_mfma_f32_16x16x32_bf16 v[62:65], v[152:155], v[184:187], v[62:65]
	v_mfma_f32_16x16x32_bf16 v[58:61], v[160:163], v[184:187], v[58:61]
	v_mfma_f32_16x16x32_bf16 v[54:57], v[152:155], v[192:195], v[54:57]
	v_mfma_f32_16x16x32_bf16 v[46:49], v[160:163], v[192:195], v[46:49]
	v_mfma_f32_16x16x32_bf16 v[38:41], v[152:155], v[200:203], v[38:41]
	v_mfma_f32_16x16x32_bf16 v[30:33], v[160:163], v[200:203], v[30:33]
	v_mfma_f32_16x16x32_bf16 v[22:25], v[152:155], v[208:211], v[22:25]
	v_mfma_f32_16x16x32_bf16 v[14:17], v[160:163], v[208:211], v[14:17]
	v_mfma_f32_16x16x32_bf16 v[62:65], v[156:159], v[188:191], v[62:65]
	v_mfma_f32_16x16x32_bf16 v[58:61], v[164:167], v[188:191], v[58:61]
	v_mfma_f32_16x16x32_bf16 v[54:57], v[156:159], v[196:199], v[54:57]
	v_mfma_f32_16x16x32_bf16 v[46:49], v[164:167], v[196:199], v[46:49]
	v_mfma_f32_16x16x32_bf16 v[38:41], v[156:159], v[204:207], v[38:41]
	v_mfma_f32_16x16x32_bf16 v[30:33], v[164:167], v[204:207], v[30:33]
	v_mfma_f32_16x16x32_bf16 v[22:25], v[156:159], v[212:215], v[22:25]
	v_mfma_f32_16x16x32_bf16 v[14:17], v[164:167], v[212:215], v[14:17]
	s_setprio 0
	s_setprio 1
	v_mfma_f32_16x16x32_bf16 v[50:53], v[168:171], v[184:187], v[50:53]
	v_mfma_f32_16x16x32_bf16 v[42:45], v[176:179], v[184:187], v[42:45]
	v_mfma_f32_16x16x32_bf16 v[34:37], v[168:171], v[192:195], v[34:37]
	v_mfma_f32_16x16x32_bf16 v[26:29], v[176:179], v[192:195], v[26:29]
	v_mfma_f32_16x16x32_bf16 v[18:21], v[168:171], v[200:203], v[18:21]
	v_mfma_f32_16x16x32_bf16 v[10:13], v[176:179], v[200:203], v[10:13]
	v_mfma_f32_16x16x32_bf16 v[6:9], v[168:171], v[208:211], v[6:9]
	v_mfma_f32_16x16x32_bf16 v[2:5], v[176:179], v[208:211], v[2:5]
	v_mfma_f32_16x16x32_bf16 v[50:53], v[172:175], v[188:191], v[50:53]
	v_mfma_f32_16x16x32_bf16 v[42:45], v[180:183], v[188:191], v[42:45]
	v_mfma_f32_16x16x32_bf16 v[34:37], v[172:175], v[196:199], v[34:37]
	v_mfma_f32_16x16x32_bf16 v[26:29], v[180:183], v[196:199], v[26:29]
	v_mfma_f32_16x16x32_bf16 v[18:21], v[172:175], v[204:207], v[18:21]
	v_mfma_f32_16x16x32_bf16 v[10:13], v[180:183], v[204:207], v[10:13]
	v_mfma_f32_16x16x32_bf16 v[6:9], v[172:175], v[212:215], v[6:9]
	v_mfma_f32_16x16x32_bf16 v[2:5], v[180:183], v[212:215], v[2:5]
	s_setprio 0
	s_barrier
	s_add_i32 s24, 0, 0x18000
	v_add_u32_e32 v151, s24, v146
	s_add_i32 s25, 0, 0x1c000
	ds_read_b128 v[152:155], v151
	ds_read_b128 v[156:159], v151 offset:1024
	ds_read_b128 v[160:163], v151 offset:2048
	ds_read_b128 v[164:167], v151 offset:3072
	v_add_u32_e32 v151, s25, v146
	ds_read_b128 v[168:171], v151
	ds_read_b128 v[172:175], v151 offset:1024
	ds_read_b128 v[176:179], v151 offset:2048
	ds_read_b128 v[180:183], v151 offset:3072
	s_add_u32 s72, s72, 0x80000
	s_addc_u32 s73, s73, 0
	s_mov_b32 m0, s76
	v_lshl_add_u64 v[224:225], s[72:73], 0, v[136:137]
	ds_read_b128 v[184:187], v150 offset:32768
	ds_read_b128 v[188:191], v150 offset:33792
	ds_read_b128 v[192:195], v150 offset:34816
	ds_read_b128 v[196:199], v150 offset:35840
	ds_read_b128 v[200:203], v150 offset:36864
	ds_read_b128 v[204:207], v150 offset:37888
	ds_read_b128 v[208:211], v150 offset:38912
	ds_read_b128 v[212:215], v150 offset:39936
	global_load_lds_dwordx4 v[224:225], off
	v_lshl_add_u64 v[224:225], s[72:73], 0, v[132:133]
	s_mov_b32 m0, s77
	s_nop 0
	global_load_lds_dwordx4 v[224:225], off
	s_waitcnt vmcnt(8)
	s_waitcnt lgkmcnt(0)
	s_barrier
	s_setprio 1
	v_mfma_f32_16x16x32_bf16 v[126:129], v[152:155], v[184:187], v[126:129]
	v_mfma_f32_16x16x32_bf16 v[122:125], v[160:163], v[184:187], v[122:125]
	v_mfma_f32_16x16x32_bf16 v[118:121], v[152:155], v[192:195], v[118:121]
	v_mfma_f32_16x16x32_bf16 v[110:113], v[160:163], v[192:195], v[110:113]
	v_mfma_f32_16x16x32_bf16 v[102:105], v[152:155], v[200:203], v[102:105]
	v_mfma_f32_16x16x32_bf16 v[94:97], v[160:163], v[200:203], v[94:97]
	v_mfma_f32_16x16x32_bf16 v[86:89], v[152:155], v[208:211], v[86:89]
	v_mfma_f32_16x16x32_bf16 v[78:81], v[160:163], v[208:211], v[78:81]
	v_mfma_f32_16x16x32_bf16 v[126:129], v[156:159], v[188:191], v[126:129]
	v_mfma_f32_16x16x32_bf16 v[122:125], v[164:167], v[188:191], v[122:125]
	v_mfma_f32_16x16x32_bf16 v[118:121], v[156:159], v[196:199], v[118:121]
	v_mfma_f32_16x16x32_bf16 v[110:113], v[164:167], v[196:199], v[110:113]
	v_mfma_f32_16x16x32_bf16 v[102:105], v[156:159], v[204:207], v[102:105]
	v_mfma_f32_16x16x32_bf16 v[94:97], v[164:167], v[204:207], v[94:97]
	v_mfma_f32_16x16x32_bf16 v[86:89], v[156:159], v[212:215], v[86:89]
	v_mfma_f32_16x16x32_bf16 v[78:81], v[164:167], v[212:215], v[78:81]
	s_setprio 0
	s_setprio 1
	v_mfma_f32_16x16x32_bf16 v[114:117], v[168:171], v[184:187], v[114:117]
	v_mfma_f32_16x16x32_bf16 v[106:109], v[176:179], v[184:187], v[106:109]
	v_mfma_f32_16x16x32_bf16 v[98:101], v[168:171], v[192:195], v[98:101]
	v_mfma_f32_16x16x32_bf16 v[90:93], v[176:179], v[192:195], v[90:93]
	v_mfma_f32_16x16x32_bf16 v[82:85], v[168:171], v[200:203], v[82:85]
	v_mfma_f32_16x16x32_bf16 v[74:77], v[176:179], v[200:203], v[74:77]
	v_mfma_f32_16x16x32_bf16 v[70:73], v[168:171], v[208:211], v[70:73]
	v_mfma_f32_16x16x32_bf16 v[66:69], v[176:179], v[208:211], v[66:69]
	v_mfma_f32_16x16x32_bf16 v[114:117], v[172:175], v[188:191], v[114:117]
	v_mfma_f32_16x16x32_bf16 v[106:109], v[180:183], v[188:191], v[106:109]
	v_mfma_f32_16x16x32_bf16 v[98:101], v[172:175], v[196:199], v[98:101]
	v_mfma_f32_16x16x32_bf16 v[90:93], v[180:183], v[196:199], v[90:93]
	v_mfma_f32_16x16x32_bf16 v[82:85], v[172:175], v[204:207], v[82:85]
	v_mfma_f32_16x16x32_bf16 v[74:77], v[180:183], v[204:207], v[74:77]
	v_mfma_f32_16x16x32_bf16 v[70:73], v[172:175], v[212:215], v[70:73]
	v_mfma_f32_16x16x32_bf16 v[66:69], v[180:183], v[212:215], v[66:69]
	s_setprio 0
	s_barrier
; #define PG8_STAGEA(bufoff, gbase, voff) PG8_STAGE_X(bufoff, gbase, voff, PG8_AUX_A)
; #define PG8_STAGEB(bufoff, gbase, voff) PG8_STAGE_X(bufoff, gbase, voff, PG8_AUX_B)
; #define PG8_LDA(dst, b, h) do { _Pragma("unroll") for (int m = 0; m < 4; ++m) _Pragma("unroll") for (int k = 0; k < 2; ++k) dst[m][k] = *(const PG8_LAS bf16x8*)(lds + PG8_SA(b, h) + aoff + m * 2048 + k * 1024); } while (0)
; #define PG8_MMA(ai, bj, At, Bt) do { __builtin_amdgcn_s_setprio(1); _Pragma("unroll") for (int m = 0; m < 4; ++m) _Pragma("unroll") for (int n = 0; n < 2; ++n) _Pragma("unroll") for (int k = 0; k < 2; ++k) \
;         acc[ai][bj][m][n] = __builtin_amdgcn_mfma_f32_16x16x32_bf16(Bt[n][k], At[m][k], acc[ai][bj][m][n], 0, 0, 0); __builtin_amdgcn_s_setprio(0); } while (0)
; #define PG8_WAIT_V(n) asm volatile("s_waitcnt vmcnt(" #n ")" ::: "memory")
; #define PG8_WAIT_L(n) asm volatile("s_waitcnt lgkmcnt(" #n ")" ::: "memory")
; #define PG8_BAR __builtin_amdgcn_s_barrier()
; #define PG8_SCHED __builtin_amdgcn_sched_barrier(0)
; template <class Epi, class Sched, bool ALIGN_EPI = false, bool SP2 = false>
; __device__ __forceinline__ void gemm_phase(PG8_LAS unsigned char* lds, const Gemm g, const Sched& S, const Epi& E) {
;     ...
;             PG8_LDA(At, 1, 1); PG8_STAGEB(PG8_SB(1, 0), b3, voffB); PG8_STAGEB(PG8_SB(1, 1), b3 + hstep, voffB); PG8_STAGEA(PG8_SA(1, 0), a3, voffA);
;             PG8_WAIT_V(8); PG8_WAIT_L(0); PG8_BAR; PG8_MMA(1, 0, At, B0); PG8_MMA(1, 1, At, B1); PG8_BAR; PG8_SCHED;
	s_add_i32 s24, s24, s23
	v_lshl_add_u64 v[216:217], v[216:217], 0, s[36:37]
	s_mov_b32 m0, s24
	ds_read_b128 v[184:187], v150 offset:49152
	ds_read_b128 v[188:191], v150 offset:50176
	ds_read_b128 v[192:195], v150 offset:51200
	ds_read_b128 v[196:199], v150 offset:52224
	ds_read_b128 v[200:203], v150 offset:53248
	ds_read_b128 v[204:207], v150 offset:54272
	ds_read_b128 v[208:211], v150 offset:55296
	ds_read_b128 v[212:215], v150 offset:56320
	global_load_lds_dwordx4 v[216:217], off
	s_add_i32 m0, s24, 0x2000
	s_add_u32 s70, s70, 0x80080
	v_lshl_add_u64 v[216:217], v[218:219], 0, s[36:37]
	s_addc_u32 s71, s71, 0
	s_add_i32 s24, s25, s23
	global_load_lds_dwordx4 v[216:217], off
	v_lshl_add_u64 v[216:217], s[70:71], 0, v[134:135]
	s_mov_b32 m0, s24
	s_nop 0
	global_load_lds_dwordx4 v[216:217], off
	v_lshl_add_u64 v[216:217], s[70:71], 0, v[130:131]
	s_add_i32 m0, s24, 0x2000
	s_nop 0
	global_load_lds_dwordx4 v[216:217], off
	v_lshl_add_u64 v[216:217], v[220:221], 0, s[36:37]
	s_mov_b32 m0, s79
	s_nop 0
	global_load_lds_dwordx4 v[216:217], off
	v_lshl_add_u64 v[216:217], v[222:223], 0, s[36:37]
	s_mov_b32 m0, s80
	s_nop 0
	global_load_lds_dwordx4 v[216:217], off
	s_waitcnt vmcnt(8)
	s_waitcnt lgkmcnt(0)
	s_barrier
	s_setprio 1
	v_mfma_f32_16x16x32_bf16 v[62:65], v[152:155], v[184:187], v[62:65]
	v_mfma_f32_16x16x32_bf16 v[58:61], v[160:163], v[184:187], v[58:61]
	v_mfma_f32_16x16x32_bf16 v[54:57], v[152:155], v[192:195], v[54:57]
	v_mfma_f32_16x16x32_bf16 v[46:49], v[160:163], v[192:195], v[46:49]
	v_mfma_f32_16x16x32_bf16 v[38:41], v[152:155], v[200:203], v[38:41]
	v_mfma_f32_16x16x32_bf16 v[30:33], v[160:163], v[200:203], v[30:33]
	v_mfma_f32_16x16x32_bf16 v[22:25], v[152:155], v[208:211], v[22:25]
	v_mfma_f32_16x16x32_bf16 v[14:17], v[160:163], v[208:211], v[14:17]
	v_mfma_f32_16x16x32_bf16 v[62:65], v[156:159], v[188:191], v[62:65]
	v_mfma_f32_16x16x32_bf16 v[58:61], v[164:167], v[188:191], v[58:61]
	v_mfma_f32_16x16x32_bf16 v[54:57], v[156:159], v[196:199], v[54:57]
	v_mfma_f32_16x16x32_bf16 v[46:49], v[164:167], v[196:199], v[46:49]
	v_mfma_f32_16x16x32_bf16 v[38:41], v[156:159], v[204:207], v[38:41]
	v_mfma_f32_16x16x32_bf16 v[30:33], v[164:167], v[204:207], v[30:33]
	v_mfma_f32_16x16x32_bf16 v[22:25], v[156:159], v[212:215], v[22:25]
	v_mfma_f32_16x16x32_bf16 v[14:17], v[164:167], v[212:215], v[14:17]
	s_setprio 0
	s_setprio 1
	v_mfma_f32_16x16x32_bf16 v[50:53], v[168:171], v[184:187], v[50:53]
	v_mfma_f32_16x16x32_bf16 v[42:45], v[176:179], v[184:187], v[42:45]
	v_mfma_f32_16x16x32_bf16 v[34:37], v[168:171], v[192:195], v[34:37]
	v_mfma_f32_16x16x32_bf16 v[26:29], v[176:179], v[192:195], v[26:29]
	v_mfma_f32_16x16x32_bf16 v[18:21], v[168:171], v[200:203], v[18:21]
	v_mfma_f32_16x16x32_bf16 v[10:13], v[176:179], v[200:203], v[10:13]
	v_mfma_f32_16x16x32_bf16 v[6:9], v[168:171], v[208:211], v[6:9]
	v_mfma_f32_16x16x32_bf16 v[2:5], v[176:179], v[208:211], v[2:5]
	v_mfma_f32_16x16x32_bf16 v[50:53], v[172:175], v[188:191], v[50:53]
	v_mfma_f32_16x16x32_bf16 v[42:45], v[180:183], v[188:191], v[42:45]
	v_mfma_f32_16x16x32_bf16 v[34:37], v[172:175], v[196:199], v[34:37]
	v_mfma_f32_16x16x32_bf16 v[26:29], v[180:183], v[196:199], v[26:29]
	v_mfma_f32_16x16x32_bf16 v[18:21], v[172:175], v[204:207], v[18:21]
	v_mfma_f32_16x16x32_bf16 v[10:13], v[180:183], v[204:207], v[10:13]
	v_mfma_f32_16x16x32_bf16 v[6:9], v[172:175], v[212:215], v[6:9]
	v_mfma_f32_16x16x32_bf16 v[2:5], v[180:183], v[212:215], v[2:5]
	s_setprio 0
	s_barrier
	s_add_u32 s68, s68, 0x100
	s_addc_u32 s69, s69, 0
	s_mov_b32 s70, s91
	s_cbranch_vccz .LBB0_766
	s_and_b64 vcc, exec, s[46:47]
	s_cbranch_vccz .LBB0_769
	s_barrier

; #define PG8_STAGEA(bufoff, gbase, voff) PG8_STAGE_X(bufoff, gbase, voff, PG8_AUX_A)
; #define PG8_STAGEB(bufoff, gbase, voff) PG8_STAGE_X(bufoff, gbase, voff, PG8_AUX_B)
; #define PG8_LDA(dst, b, h) do { _Pragma("unroll") for (int m = 0; m < 4; ++m) _Pragma("unroll") for (int k = 0; k < 2; ++k) dst[m][k] = *(const PG8_LAS bf16x8*)(lds + PG8_SA(b, h) + aoff + m * 2048 + k * 1024); } while (0)
; #define PG8_LDB(dst, b, h) do { _Pragma("unroll") for (int n = 0; n < 2; ++n) _Pragma("unroll") for (int k = 0; k < 2; ++k) dst[n][k] = *(const PG8_LAS bf16x8*)(lds + PG8_SB(b, h) + boff + n * 2048 + k * 1024); } while (0)
; #define PG8_MMA(ai, bj, At, Bt) do { __builtin_amdgcn_s_setprio(1); _Pragma("unroll") for (int m = 0; m < 4; ++m) _Pragma("unroll") for (int n = 0; n < 2; ++n) _Pragma("unroll") for (int k = 0; k < 2; ++k) \
;         acc[ai][bj][m][n] = __builtin_amdgcn_mfma_f32_16x16x32_bf16(Bt[n][k], At[m][k], acc[ai][bj][m][n], 0, 0, 0); __builtin_amdgcn_s_setprio(0); } while (0)
; #define PG8_WAIT_V(n) asm volatile("s_waitcnt vmcnt(" #n ")" ::: "memory")
; #define PG8_WAIT_L(n) asm volatile("s_waitcnt lgkmcnt(" #n ")" ::: "memory")
; template <class Epi, class Sched, bool ALIGN_EPI = false, bool SP2 = false>
; __device__ __forceinline__ void gemm_phase(PG8_LAS unsigned char* lds, const Gemm g, const Sched& S, const Epi& E) {
;     ...
;             const bool last = (t == nt - 2);
;             if constexpr (HasMid<Epi>::value) { if (t == ns) E.mid(acc, cur, wr, wc, fr, fq); }
;             const char* sA1 = (t + 1 >= ns) ? cA2 : cA; const char* sA2 = (t + 2 >= ns) ? cA2 : cA; const char* sB2 = (t + 2 >= ns) ? cB2 : cB;
;             const char* a1 = sA1 + (size_t)(t + 1) * kstep;
;             const char* a2 = last ? nA : sA2 + (size_t)(t + 2) * kstep; const char* b2 = last ? nB : sB2 + (size_t)(t + 2) * kstep;
;             const char* a3 = a2 + kstep; const char* b3 = b2 + kstep;
;             if (last && has_next) S.a_ready(nxt);
;             if constexpr (SP2) {
;             PG8_LDB(B0, 0, 0); PG8_LDB(B1, 0, 1); PG8_SCHED; PG8_LDA(At, 0, 0); PG8_STAGEA(PG8_SA(1, 1), a1 + hstep, voffA);
;             PG8_WAIT_V(8); PG8_WAIT_L(0); PG8_BAR; PG8_MMA(0, 0, At, B0); PG8_MMA(0, 1, At, B1); PG8_BAR; PG8_SCHED;
;             PG8_LDA(At, 0, 1); PG8_STAGEB(PG8_SB(0, 0), b2, voffB); PG8_STAGEB(PG8_SB(0, 1), b2 + hstep, voffB); PG8_STAGEA(PG8_SA(0, 0), a2, voffA);
.LBB0_920:
	s_add_i32 s87, s66, 2
	s_cmp_lt_u32 s87, 6
	s_cselect_b32 s29, s62, s40
	s_cselect_b32 s24, s61, s37
	s_cselect_b32 s25, s60, s36
	s_cselect_b32 s28, s63, s41
	s_add_u32 s29, s29, s64
	s_addc_u32 s28, s28, s65
	s_add_u32 s29, s29, 0xfffe0080
	s_addc_u32 s28, s28, -1
	s_add_u32 s25, s25, s64
	s_addc_u32 s24, s24, s65
	s_add_u32 s25, s25, 0xfffe0080
	s_addc_u32 s24, s24, -1
	s_cmp_eq_u32 s66, 4
	s_cselect_b32 s73, s51, s28
	s_cselect_b32 s72, s57, s29
	s_cselect_b32 s75, s49, s24
	s_cselect_b32 s74, s86, s25
	s_add_i32 s25, s84, s23
	s_add_i32 m0, s26, 0xc000
	s_add_i32 s24, s26, 0xe000
	s_add_i32 s28, s25, 0x2000
	s_add_u32 s76, s74, 0x20000
	ds_read_b128 v[82:85], v164
	ds_read_b128 v[90:93], v164 offset:1024
	ds_read_b128 v[94:97], v164 offset:2048
	ds_read_b128 v[158:161], v164 offset:3072
	ds_read_b128 v[168:171], v165
	ds_read_b128 v[172:175], v165 offset:1024
	ds_read_b128 v[176:179], v165 offset:2048
	ds_read_b128 v[180:183], v165 offset:3072
	s_addc_u32 s77, s75, 0
	s_add_i32 s29, s85, s23
	s_add_i32 s92, s29, 0x2000
	s_add_i32 s93, 0, 0x18000
	s_add_i32 s94, 0, 0x1c000
	s_add_u32 s70, s72, 0x20000
	s_addc_u32 s71, s73, 0
	s_add_i32 s90, s93, s23
	s_add_i32 s88, s90, 0x2000
	s_add_u32 s68, s74, 0x20080
	s_addc_u32 s69, s75, 0
	s_add_i32 s89, s94, s23
	s_add_i32 s91, s89, 0x2000
	s_add_u32 s66, s64, 0x100
	s_addc_u32 s67, s65, 0
	s_cmp_gt_u32 s87, 5
	v_lshl_add_u64 v[216:217], v[70:71], 0, s[64:65]
	ds_read_b128 v[184:187], v166
	ds_read_b128 v[188:191], v166 offset:1024
	ds_read_b128 v[192:195], v166 offset:2048
	ds_read_b128 v[196:199], v166 offset:3072
	ds_read_b128 v[200:203], v166 offset:4096
	ds_read_b128 v[204:207], v166 offset:5120
	ds_read_b128 v[208:211], v166 offset:6144
	ds_read_b128 v[212:215], v166 offset:7168
	global_load_lds_dwordx4 v[216:217], off
	v_lshl_add_u64 v[216:217], v[72:73], 0, s[64:65]
	s_mov_b32 m0, s24
	s_nop 0
	global_load_lds_dwordx4 v[216:217], off
	s_waitcnt vmcnt(8)
	s_waitcnt lgkmcnt(0)
	s_barrier
	s_setprio 1
	v_mfma_f32_16x16x32_bf16 v[142:145], v[82:85], v[184:187], v[142:145]
	v_mfma_f32_16x16x32_bf16 v[138:141], v[94:97], v[184:187], v[138:141]
	v_mfma_f32_16x16x32_bf16 v[126:129], v[82:85], v[192:195], v[126:129]
	v_mfma_f32_16x16x32_bf16 v[122:125], v[94:97], v[192:195], v[122:125]
	v_mfma_f32_16x16x32_bf16 v[110:113], v[82:85], v[200:203], v[110:113]
	v_mfma_f32_16x16x32_bf16 v[106:109], v[94:97], v[200:203], v[106:109]
	v_mfma_f32_16x16x32_bf16 v[86:89], v[82:85], v[208:211], v[86:89]
	v_mfma_f32_16x16x32_bf16 v[78:81], v[94:97], v[208:211], v[78:81]
	v_mfma_f32_16x16x32_bf16 v[142:145], v[90:93], v[188:191], v[142:145]
	v_mfma_f32_16x16x32_bf16 v[138:141], v[158:161], v[188:191], v[138:141]
	v_mfma_f32_16x16x32_bf16 v[126:129], v[90:93], v[196:199], v[126:129]
	v_mfma_f32_16x16x32_bf16 v[122:125], v[158:161], v[196:199], v[122:125]
	v_mfma_f32_16x16x32_bf16 v[110:113], v[90:93], v[204:207], v[110:113]
	v_mfma_f32_16x16x32_bf16 v[106:109], v[158:161], v[204:207], v[106:109]
	v_mfma_f32_16x16x32_bf16 v[86:89], v[90:93], v[212:215], v[86:89]
	v_mfma_f32_16x16x32_bf16 v[78:81], v[158:161], v[212:215], v[78:81]
	s_setprio 0
	s_setprio 1
	v_mfma_f32_16x16x32_bf16 v[134:137], v[168:171], v[184:187], v[134:137]
	v_mfma_f32_16x16x32_bf16 v[130:133], v[176:179], v[184:187], v[130:133]
	v_mfma_f32_16x16x32_bf16 v[118:121], v[168:171], v[192:195], v[118:121]
	v_mfma_f32_16x16x32_bf16 v[114:117], v[176:179], v[192:195], v[114:117]
	v_mfma_f32_16x16x32_bf16 v[102:105], v[168:171], v[200:203], v[102:105]
	v_mfma_f32_16x16x32_bf16 v[98:101], v[176:179], v[200:203], v[98:101]
	v_mfma_f32_16x16x32_bf16 v[74:77], v[168:171], v[208:211], v[74:77]
	v_mfma_f32_16x16x32_bf16 v[66:69], v[176:179], v[208:211], v[66:69]
	v_mfma_f32_16x16x32_bf16 v[134:137], v[172:175], v[188:191], v[134:137]
	v_mfma_f32_16x16x32_bf16 v[130:133], v[180:183], v[188:191], v[130:133]
	v_mfma_f32_16x16x32_bf16 v[118:121], v[172:175], v[196:199], v[118:121]
	v_mfma_f32_16x16x32_bf16 v[114:117], v[180:183], v[196:199], v[114:117]
	v_mfma_f32_16x16x32_bf16 v[102:105], v[172:175], v[204:207], v[102:105]
	v_mfma_f32_16x16x32_bf16 v[98:101], v[180:183], v[204:207], v[98:101]
	v_mfma_f32_16x16x32_bf16 v[74:77], v[172:175], v[212:215], v[74:77]
	v_mfma_f32_16x16x32_bf16 v[66:69], v[180:183], v[212:215], v[66:69]
	s_setprio 0
	s_barrier
	s_mov_b32 m0, s25
	v_lshl_add_u64 v[216:217], s[74:75], 0, v[146:147]
	ds_read_b128 v[184:187], v166 offset:16384
	ds_read_b128 v[188:191], v166 offset:17408
	ds_read_b128 v[192:195], v166 offset:18432
	ds_read_b128 v[196:199], v166 offset:19456
	ds_read_b128 v[200:203], v166 offset:20480
	ds_read_b128 v[204:207], v166 offset:21504
	ds_read_b128 v[208:211], v166 offset:22528
	ds_read_b128 v[212:215], v166 offset:23552
	global_load_lds_dwordx4 v[216:217], off
	v_lshl_add_u64 v[218:219], s[74:75], 0, v[148:149]
	s_mov_b32 m0, s28
	v_lshl_add_u64 v[220:221], s[76:77], 0, v[146:147]
	global_load_lds_dwordx4 v[218:219], off
	s_mov_b32 m0, s29
	v_lshl_add_u64 v[222:223], s[72:73], 0, v[148:149]
	global_load_lds_dwordx4 v[220:221], off
	v_lshl_add_u64 v[220:221], s[76:77], 0, v[148:149]
	s_mov_b32 m0, s92
	s_nop 0
	global_load_lds_dwordx4 v[220:221], off
	v_lshl_add_u64 v[220:221], s[72:73], 0, v[146:147]
	s_mov_b32 m0, s26
	s_nop 0
	global_load_lds_dwordx4 v[220:221], off
	s_mov_b32 m0, s27
	s_nop 0
	global_load_lds_dwordx4 v[222:223], off
	s_waitcnt vmcnt(8)
	s_waitcnt lgkmcnt(0)
	s_barrier
; #define PG8_STAGEA(bufoff, gbase, voff) PG8_STAGE_X(bufoff, gbase, voff, PG8_AUX_A)
; #define PG8_LDA(dst, b, h) do { _Pragma("unroll") for (int m = 0; m < 4; ++m) _Pragma("unroll") for (int k = 0; k < 2; ++k) dst[m][k] = *(const PG8_LAS bf16x8*)(lds + PG8_SA(b, h) + aoff + m * 2048 + k * 1024); } while (0)
; #define PG8_LDB(dst, b, h) do { _Pragma("unroll") for (int n = 0; n < 2; ++n) _Pragma("unroll") for (int k = 0; k < 2; ++k) dst[n][k] = *(const PG8_LAS bf16x8*)(lds + PG8_SB(b, h) + boff + n * 2048 + k * 1024); } while (0)
; #define PG8_MMA(ai, bj, At, Bt) do { __builtin_amdgcn_s_setprio(1); _Pragma("unroll") for (int m = 0; m < 4; ++m) _Pragma("unroll") for (int n = 0; n < 2; ++n) _Pragma("unroll") for (int k = 0; k < 2; ++k) \
;         acc[ai][bj][m][n] = __builtin_amdgcn_mfma_f32_16x16x32_bf16(Bt[n][k], At[m][k], acc[ai][bj][m][n], 0, 0, 0); __builtin_amdgcn_s_setprio(0); } while (0)
; #define PG8_WAIT_V(n) asm volatile("s_waitcnt vmcnt(" #n ")" ::: "memory")
; #define PG8_WAIT_L(n) asm volatile("s_waitcnt lgkmcnt(" #n ")" ::: "memory")
; #define PG8_BAR __builtin_amdgcn_s_barrier()
; #define PG8_SCHED __builtin_amdgcn_sched_barrier(0)
; template <class Epi, class Sched, bool ALIGN_EPI = false, bool SP2 = false>
; __device__ __forceinline__ void gemm_phase(PG8_LAS unsigned char* lds, const Gemm g, const Sched& S, const Epi& E) {
;     ...
;             PG8_WAIT_V(8); PG8_WAIT_L(0); PG8_BAR; PG8_MMA(1, 0, At, B0); PG8_MMA(1, 1, At, B1); PG8_BAR; PG8_SCHED;
;             PG8_LDB(B0, 1, 0); PG8_LDB(B1, 1, 1); PG8_SCHED; PG8_LDA(At, 1, 0); PG8_STAGEA(PG8_SA(0, 1), a2 + hstep, voffA);
;             PG8_WAIT_V(8); PG8_WAIT_L(0); PG8_BAR; PG8_MMA(0, 0, At, B0); PG8_MMA(0, 1, At, B1); PG8_BAR; PG8_SCHED;
	s_setprio 1
	v_mfma_f32_16x16x32_bf16 v[62:65], v[82:85], v[184:187], v[62:65]
	v_mfma_f32_16x16x32_bf16 v[58:61], v[94:97], v[184:187], v[58:61]
	v_mfma_f32_16x16x32_bf16 v[46:49], v[82:85], v[192:195], v[46:49]
	v_mfma_f32_16x16x32_bf16 v[42:45], v[94:97], v[192:195], v[42:45]
	v_mfma_f32_16x16x32_bf16 v[30:33], v[82:85], v[200:203], v[30:33]
	v_mfma_f32_16x16x32_bf16 v[26:29], v[94:97], v[200:203], v[26:29]
	v_mfma_f32_16x16x32_bf16 v[14:17], v[82:85], v[208:211], v[14:17]
	v_mfma_f32_16x16x32_bf16 v[10:13], v[94:97], v[208:211], v[10:13]
	v_mfma_f32_16x16x32_bf16 v[62:65], v[90:93], v[188:191], v[62:65]
	v_mfma_f32_16x16x32_bf16 v[58:61], v[158:161], v[188:191], v[58:61]
	v_mfma_f32_16x16x32_bf16 v[46:49], v[90:93], v[196:199], v[46:49]
	v_mfma_f32_16x16x32_bf16 v[42:45], v[158:161], v[196:199], v[42:45]
	v_mfma_f32_16x16x32_bf16 v[30:33], v[90:93], v[204:207], v[30:33]
	v_mfma_f32_16x16x32_bf16 v[26:29], v[158:161], v[204:207], v[26:29]
	v_mfma_f32_16x16x32_bf16 v[14:17], v[90:93], v[212:215], v[14:17]
	v_mfma_f32_16x16x32_bf16 v[10:13], v[158:161], v[212:215], v[10:13]
	s_setprio 0
	s_setprio 1
	v_mfma_f32_16x16x32_bf16 v[54:57], v[168:171], v[184:187], v[54:57]
	v_mfma_f32_16x16x32_bf16 v[50:53], v[176:179], v[184:187], v[50:53]
	v_mfma_f32_16x16x32_bf16 v[38:41], v[168:171], v[192:195], v[38:41]
	v_mfma_f32_16x16x32_bf16 v[34:37], v[176:179], v[192:195], v[34:37]
	v_mfma_f32_16x16x32_bf16 v[22:25], v[168:171], v[200:203], v[22:25]
	v_mfma_f32_16x16x32_bf16 v[18:21], v[176:179], v[200:203], v[18:21]
	v_mfma_f32_16x16x32_bf16 v[6:9], v[168:171], v[208:211], v[6:9]
	v_mfma_f32_16x16x32_bf16 v[2:5], v[176:179], v[208:211], v[2:5]
	v_mfma_f32_16x16x32_bf16 v[54:57], v[172:175], v[188:191], v[54:57]
	v_mfma_f32_16x16x32_bf16 v[50:53], v[180:183], v[188:191], v[50:53]
	v_mfma_f32_16x16x32_bf16 v[38:41], v[172:175], v[196:199], v[38:41]
	v_mfma_f32_16x16x32_bf16 v[34:37], v[180:183], v[196:199], v[34:37]
	v_mfma_f32_16x16x32_bf16 v[22:25], v[172:175], v[204:207], v[22:25]
	v_mfma_f32_16x16x32_bf16 v[18:21], v[180:183], v[204:207], v[18:21]
	v_mfma_f32_16x16x32_bf16 v[6:9], v[172:175], v[212:215], v[6:9]
	v_mfma_f32_16x16x32_bf16 v[2:5], v[180:183], v[212:215], v[2:5]
	s_setprio 0
	s_barrier
	v_add_u32_e32 v158, s93, v162
	v_add_u32_e32 v180, s94, v162
	ds_read_b128 v[82:85], v158
	ds_read_b128 v[90:93], v158 offset:1024
	ds_read_b128 v[94:97], v158 offset:2048
	ds_read_b128 v[158:161], v158 offset:3072
	ds_read_b128 v[168:171], v180
	ds_read_b128 v[172:175], v180 offset:1024
	ds_read_b128 v[176:179], v180 offset:2048
	ds_read_b128 v[180:183], v180 offset:3072
	s_mov_b32 m0, s33
	v_lshl_add_u64 v[224:225], s[70:71], 0, v[146:147]
	ds_read_b128 v[184:187], v166 offset:32768
	ds_read_b128 v[188:191], v166 offset:33792
	ds_read_b128 v[192:195], v166 offset:34816
	ds_read_b128 v[196:199], v166 offset:35840
	ds_read_b128 v[200:203], v166 offset:36864
	ds_read_b128 v[204:207], v166 offset:37888
	ds_read_b128 v[208:211], v166 offset:38912
	ds_read_b128 v[212:215], v166 offset:39936
	global_load_lds_dwordx4 v[224:225], off
	v_lshl_add_u64 v[224:225], s[70:71], 0, v[148:149]
	s_mov_b32 m0, s59
	s_nop 0
	global_load_lds_dwordx4 v[224:225], off
	s_waitcnt vmcnt(8)
	s_waitcnt lgkmcnt(0)
	s_barrier
	s_setprio 1
	v_mfma_f32_16x16x32_bf16 v[142:145], v[82:85], v[184:187], v[142:145]
	v_mfma_f32_16x16x32_bf16 v[138:141], v[94:97], v[184:187], v[138:141]
	v_mfma_f32_16x16x32_bf16 v[126:129], v[82:85], v[192:195], v[126:129]
	v_mfma_f32_16x16x32_bf16 v[122:125], v[94:97], v[192:195], v[122:125]
	v_mfma_f32_16x16x32_bf16 v[110:113], v[82:85], v[200:203], v[110:113]
	v_mfma_f32_16x16x32_bf16 v[106:109], v[94:97], v[200:203], v[106:109]
	v_mfma_f32_16x16x32_bf16 v[86:89], v[82:85], v[208:211], v[86:89]
	v_mfma_f32_16x16x32_bf16 v[78:81], v[94:97], v[208:211], v[78:81]
	v_mfma_f32_16x16x32_bf16 v[142:145], v[90:93], v[188:191], v[142:145]
	v_mfma_f32_16x16x32_bf16 v[138:141], v[158:161], v[188:191], v[138:141]
	v_mfma_f32_16x16x32_bf16 v[126:129], v[90:93], v[196:199], v[126:129]
	v_mfma_f32_16x16x32_bf16 v[122:125], v[158:161], v[196:199], v[122:125]
	v_mfma_f32_16x16x32_bf16 v[110:113], v[90:93], v[204:207], v[110:113]
	v_mfma_f32_16x16x32_bf16 v[106:109], v[158:161], v[204:207], v[106:109]
	v_mfma_f32_16x16x32_bf16 v[86:89], v[90:93], v[212:215], v[86:89]
	v_mfma_f32_16x16x32_bf16 v[78:81], v[158:161], v[212:215], v[78:81]
	s_setprio 0
	s_setprio 1
	v_mfma_f32_16x16x32_bf16 v[134:137], v[168:171], v[184:187], v[134:137]
	v_mfma_f32_16x16x32_bf16 v[130:133], v[176:179], v[184:187], v[130:133]
	v_mfma_f32_16x16x32_bf16 v[118:121], v[168:171], v[192:195], v[118:121]
	v_mfma_f32_16x16x32_bf16 v[114:117], v[176:179], v[192:195], v[114:117]
	v_mfma_f32_16x16x32_bf16 v[102:105], v[168:171], v[200:203], v[102:105]
	v_mfma_f32_16x16x32_bf16 v[98:101], v[176:179], v[200:203], v[98:101]
	v_mfma_f32_16x16x32_bf16 v[74:77], v[168:171], v[208:211], v[74:77]
	v_mfma_f32_16x16x32_bf16 v[66:69], v[176:179], v[208:211], v[66:69]
	v_mfma_f32_16x16x32_bf16 v[134:137], v[172:175], v[188:191], v[134:137]
	v_mfma_f32_16x16x32_bf16 v[130:133], v[180:183], v[188:191], v[130:133]
	v_mfma_f32_16x16x32_bf16 v[118:121], v[172:175], v[196:199], v[118:121]
	v_mfma_f32_16x16x32_bf16 v[114:117], v[180:183], v[196:199], v[114:117]
	v_mfma_f32_16x16x32_bf16 v[102:105], v[172:175], v[204:207], v[102:105]
	v_mfma_f32_16x16x32_bf16 v[98:101], v[180:183], v[204:207], v[98:101]
	v_mfma_f32_16x16x32_bf16 v[74:77], v[172:175], v[212:215], v[74:77]
	v_mfma_f32_16x16x32_bf16 v[66:69], v[180:183], v[212:215], v[66:69]
	s_setprio 0
	s_barrier
; #define PG8_STAGEA(bufoff, gbase, voff) PG8_STAGE_X(bufoff, gbase, voff, PG8_AUX_A)
; #define PG8_STAGEB(bufoff, gbase, voff) PG8_STAGE_X(bufoff, gbase, voff, PG8_AUX_B)
; #define PG8_LDA(dst, b, h) do { _Pragma("unroll") for (int m = 0; m < 4; ++m) _Pragma("unroll") for (int k = 0; k < 2; ++k) dst[m][k] = *(const PG8_LAS bf16x8*)(lds + PG8_SA(b, h) + aoff + m * 2048 + k * 1024); } while (0)
; #define PG8_MMA(ai, bj, At, Bt) do { __builtin_amdgcn_s_setprio(1); _Pragma("unroll") for (int m = 0; m < 4; ++m) _Pragma("unroll") for (int n = 0; n < 2; ++n) _Pragma("unroll") for (int k = 0; k < 2; ++k) \
;         acc[ai][bj][m][n] = __builtin_amdgcn_mfma_f32_16x16x32_bf16(Bt[n][k], At[m][k], acc[ai][bj][m][n], 0, 0, 0); __builtin_amdgcn_s_setprio(0); } while (0)
; #define PG8_WAIT_V(n) asm volatile("s_waitcnt vmcnt(" #n ")" ::: "memory")
; #define PG8_WAIT_L(n) asm volatile("s_waitcnt lgkmcnt(" #n ")" ::: "memory")
; #define PG8_BAR __builtin_amdgcn_s_barrier()
; #define PG8_SCHED __builtin_amdgcn_sched_barrier(0)
; template <class Epi, class Sched, bool ALIGN_EPI = false, bool SP2 = false>
; __device__ __forceinline__ void gemm_phase(PG8_LAS unsigned char* lds, const Gemm g, const Sched& S, const Epi& E) {
;     ...
;             PG8_LDA(At, 1, 1); PG8_STAGEB(PG8_SB(1, 0), b3, voffB); PG8_STAGEB(PG8_SB(1, 1), b3 + hstep, voffB); PG8_STAGEA(PG8_SA(1, 0), a3, voffA);
;             PG8_WAIT_V(8); PG8_WAIT_L(0); PG8_BAR; PG8_MMA(1, 0, At, B0); PG8_MMA(1, 1, At, B1); PG8_BAR; PG8_SCHED;
	s_mov_b32 m0, s90
	v_lshl_add_u64 v[216:217], v[216:217], 0, s[44:45]
	ds_read_b128 v[184:187], v166 offset:49152
	ds_read_b128 v[188:191], v166 offset:50176
	ds_read_b128 v[192:195], v166 offset:51200
	ds_read_b128 v[196:199], v166 offset:52224
	ds_read_b128 v[200:203], v166 offset:53248
	ds_read_b128 v[204:207], v166 offset:54272
	ds_read_b128 v[208:211], v166 offset:55296
	ds_read_b128 v[212:215], v166 offset:56320
	global_load_lds_dwordx4 v[216:217], off
	v_lshl_add_u64 v[216:217], v[218:219], 0, s[44:45]
	s_mov_b32 m0, s88
	s_nop 0
	global_load_lds_dwordx4 v[216:217], off
	v_lshl_add_u64 v[216:217], s[68:69], 0, v[146:147]
	s_mov_b32 m0, s89
	s_nop 0
	global_load_lds_dwordx4 v[216:217], off
	v_lshl_add_u64 v[216:217], s[68:69], 0, v[148:149]
	s_mov_b32 m0, s91
	s_nop 0
	global_load_lds_dwordx4 v[216:217], off
	v_lshl_add_u64 v[216:217], v[220:221], 0, s[44:45]
	s_mov_b32 m0, s79
	s_nop 0
	global_load_lds_dwordx4 v[216:217], off
	v_lshl_add_u64 v[216:217], v[222:223], 0, s[44:45]
	s_mov_b32 m0, s80
	s_nop 0
	global_load_lds_dwordx4 v[216:217], off
	s_waitcnt vmcnt(8)
	s_waitcnt lgkmcnt(0)
	s_barrier
	s_setprio 1
	v_mfma_f32_16x16x32_bf16 v[62:65], v[82:85], v[184:187], v[62:65]
	v_mfma_f32_16x16x32_bf16 v[58:61], v[94:97], v[184:187], v[58:61]
	v_mfma_f32_16x16x32_bf16 v[46:49], v[82:85], v[192:195], v[46:49]
	v_mfma_f32_16x16x32_bf16 v[42:45], v[94:97], v[192:195], v[42:45]
	v_mfma_f32_16x16x32_bf16 v[30:33], v[82:85], v[200:203], v[30:33]
	v_mfma_f32_16x16x32_bf16 v[26:29], v[94:97], v[200:203], v[26:29]
	v_mfma_f32_16x16x32_bf16 v[14:17], v[82:85], v[208:211], v[14:17]
	v_mfma_f32_16x16x32_bf16 v[10:13], v[94:97], v[208:211], v[10:13]
	v_mfma_f32_16x16x32_bf16 v[62:65], v[90:93], v[188:191], v[62:65]
	v_mfma_f32_16x16x32_bf16 v[58:61], v[158:161], v[188:191], v[58:61]
	v_mfma_f32_16x16x32_bf16 v[46:49], v[90:93], v[196:199], v[46:49]
	v_mfma_f32_16x16x32_bf16 v[42:45], v[158:161], v[196:199], v[42:45]
	v_mfma_f32_16x16x32_bf16 v[30:33], v[90:93], v[204:207], v[30:33]
	v_mfma_f32_16x16x32_bf16 v[26:29], v[158:161], v[204:207], v[26:29]
	v_mfma_f32_16x16x32_bf16 v[14:17], v[90:93], v[212:215], v[14:17]
	v_mfma_f32_16x16x32_bf16 v[10:13], v[158:161], v[212:215], v[10:13]
	s_setprio 0
	s_setprio 1
	v_mfma_f32_16x16x32_bf16 v[54:57], v[168:171], v[184:187], v[54:57]
	v_mfma_f32_16x16x32_bf16 v[50:53], v[176:179], v[184:187], v[50:53]
	v_mfma_f32_16x16x32_bf16 v[38:41], v[168:171], v[192:195], v[38:41]
	v_mfma_f32_16x16x32_bf16 v[34:37], v[176:179], v[192:195], v[34:37]
	v_mfma_f32_16x16x32_bf16 v[22:25], v[168:171], v[200:203], v[22:25]
	v_mfma_f32_16x16x32_bf16 v[18:21], v[176:179], v[200:203], v[18:21]
	v_mfma_f32_16x16x32_bf16 v[6:9], v[168:171], v[208:211], v[6:9]
	v_mfma_f32_16x16x32_bf16 v[2:5], v[176:179], v[208:211], v[2:5]
	v_mfma_f32_16x16x32_bf16 v[54:57], v[172:175], v[188:191], v[54:57]
	v_mfma_f32_16x16x32_bf16 v[50:53], v[180:183], v[188:191], v[50:53]
	v_mfma_f32_16x16x32_bf16 v[38:41], v[172:175], v[196:199], v[38:41]
	v_mfma_f32_16x16x32_bf16 v[34:37], v[180:183], v[196:199], v[34:37]
	v_mfma_f32_16x16x32_bf16 v[22:25], v[172:175], v[204:207], v[22:25]
	v_mfma_f32_16x16x32_bf16 v[18:21], v[180:183], v[204:207], v[18:21]
	v_mfma_f32_16x16x32_bf16 v[6:9], v[172:175], v[212:215], v[6:9]
	v_mfma_f32_16x16x32_bf16 v[2:5], v[180:183], v[212:215], v[2:5]
	s_setprio 0
	s_barrier
	s_mov_b64 s[64:65], s[66:67]
	s_mov_b32 s66, s87
	s_cbranch_scc0 .LBB0_920
	s_and_b64 vcc, exec, s[46:47]
	s_cbranch_vccz .LBB0_923
	s_barrier

; #define PG8_STAGEA(bufoff, gbase, voff) PG8_STAGE_X(bufoff, gbase, voff, PG8_AUX_A)
; #define PG8_STAGEB(bufoff, gbase, voff) PG8_STAGE_X(bufoff, gbase, voff, PG8_AUX_B)
; #define PG8_LDA(dst, b, h) do { _Pragma("unroll") for (int m = 0; m < 4; ++m) _Pragma("unroll") for (int k = 0; k < 2; ++k) dst[m][k] = *(const PG8_LAS bf16x8*)(lds + PG8_SA(b, h) + aoff + m * 2048 + k * 1024); } while (0)
; #define PG8_LDB(dst, b, h) do { _Pragma("unroll") for (int n = 0; n < 2; ++n) _Pragma("unroll") for (int k = 0; k < 2; ++k) dst[n][k] = *(const PG8_LAS bf16x8*)(lds + PG8_SB(b, h) + boff + n * 2048 + k * 1024); } while (0)
; #define PG8_MMA(ai, bj, At, Bt) do { __builtin_amdgcn_s_setprio(1); _Pragma("unroll") for (int m = 0; m < 4; ++m) _Pragma("unroll") for (int n = 0; n < 2; ++n) _Pragma("unroll") for (int k = 0; k < 2; ++k) \
;         acc[ai][bj][m][n] = __builtin_amdgcn_mfma_f32_16x16x32_bf16(Bt[n][k], At[m][k], acc[ai][bj][m][n], 0, 0, 0); __builtin_amdgcn_s_setprio(0); } while (0)
; #define PG8_WAIT_V(n) asm volatile("s_waitcnt vmcnt(" #n ")" ::: "memory")
; #define PG8_WAIT_L(n) asm volatile("s_waitcnt lgkmcnt(" #n ")" ::: "memory")
; template <class Epi, class Sched, bool ALIGN_EPI = false, bool SP2 = false>
; __device__ __forceinline__ void gemm_phase(PG8_LAS unsigned char* lds, const Gemm g, const Sched& S, const Epi& E) {
;     ...
;             const bool last = (t == nt - 2);
;             if constexpr (HasMid<Epi>::value) { if (t == ns) E.mid(acc, cur, wr, wc, fr, fq); }
;             const char* sA1 = (t + 1 >= ns) ? cA2 : cA; const char* sA2 = (t + 2 >= ns) ? cA2 : cA; const char* sB2 = (t + 2 >= ns) ? cB2 : cB;
;             const char* a1 = sA1 + (size_t)(t + 1) * kstep;
;             const char* a2 = last ? nA : sA2 + (size_t)(t + 2) * kstep; const char* b2 = last ? nB : sB2 + (size_t)(t + 2) * kstep;
;             const char* a3 = a2 + kstep; const char* b3 = b2 + kstep;
;             if (last && has_next) S.a_ready(nxt);
;             if constexpr (SP2) {
;             PG8_LDB(B0, 0, 0); PG8_LDB(B1, 0, 1); PG8_SCHED; PG8_LDA(At, 0, 0); PG8_STAGEA(PG8_SA(1, 1), a1 + hstep, voffA);
;             PG8_WAIT_V(8); PG8_WAIT_L(0); PG8_BAR; PG8_MMA(0, 0, At, B0); PG8_MMA(0, 1, At, B1); PG8_BAR; PG8_SCHED;
;             PG8_LDA(At, 0, 1); PG8_STAGEB(PG8_SB(0, 0), b2, voffB); PG8_STAGEB(PG8_SB(0, 1), b2 + hstep, voffB); PG8_STAGEA(PG8_SA(0, 0), a2, voffA);
.LBB0_1007:
	s_add_i32 s76, s58, 2
	s_cmp_gt_u32 s76, 29
	s_cselect_b64 s[60:61], -1, 0
	s_and_b64 vcc, s[60:61], exec
	s_cselect_b32 s29, s34, s54
	ds_read_b128 v[158:161], v152
	ds_read_b128 v[162:165], v152 offset:1024
	ds_read_b128 v[166:169], v152 offset:2048
	ds_read_b128 v[170:173], v152 offset:3072
	ds_read_b128 v[174:177], v153
	ds_read_b128 v[178:181], v153 offset:1024
	ds_read_b128 v[182:185], v153 offset:2048
	ds_read_b128 v[186:189], v153 offset:3072
	s_cselect_b32 s24, s27, s53
	s_cselect_b32 s25, s26, s52
	s_cselect_b32 s28, s35, s55
	s_add_u32 s29, s29, s56
	s_addc_u32 s28, s28, s57
	s_add_u32 s29, s29, 0xfff80080
	s_addc_u32 s28, s28, -1
	s_add_u32 s25, s25, s56
	s_addc_u32 s24, s24, s57
	s_add_u32 s25, s25, 0xfff80080
	s_addc_u32 s24, s24, -1
	s_cmp_eq_u32 s58, 28
	s_cselect_b32 s58, s75, s25
	s_cselect_b32 s61, s47, s28
	s_cselect_b32 s60, s74, s29
	s_cselect_b32 s59, s45, s24
	v_lshl_add_u64 v[222:223], v[146:147], 0, s[56:57]
	s_add_i32 m0, s33, 0xc000
	ds_read_b128 v[190:193], v154
	ds_read_b128 v[194:197], v154 offset:1024
	ds_read_b128 v[198:201], v154 offset:2048
	ds_read_b128 v[202:205], v154 offset:3072
	ds_read_b128 v[206:209], v154 offset:4096
	ds_read_b128 v[210:213], v154 offset:5120
	ds_read_b128 v[214:217], v154 offset:6144
	ds_read_b128 v[218:221], v154 offset:7168
	global_load_lds_dwordx4 v[222:223], off
	v_lshl_add_u64 v[222:223], v[148:149], 0, s[56:57]
	s_add_i32 m0, s33, 0xe000
	s_nop 0
	global_load_lds_dwordx4 v[222:223], off
	s_waitcnt vmcnt(8)
	s_waitcnt lgkmcnt(0)
	s_barrier
	s_setprio 1
	v_mfma_f32_16x16x32_bf16 v[118:121], v[158:161], v[190:193], v[118:121]
	v_mfma_f32_16x16x32_bf16 v[114:117], v[166:169], v[190:193], v[114:117]
	v_mfma_f32_16x16x32_bf16 v[102:105], v[158:161], v[198:201], v[102:105]
	v_mfma_f32_16x16x32_bf16 v[98:101], v[166:169], v[198:201], v[98:101]
	v_mfma_f32_16x16x32_bf16 v[86:89], v[158:161], v[206:209], v[86:89]
	v_mfma_f32_16x16x32_bf16 v[82:85], v[166:169], v[206:209], v[82:85]
	v_mfma_f32_16x16x32_bf16 v[70:73], v[158:161], v[214:217], v[70:73]
	v_mfma_f32_16x16x32_bf16 v[66:69], v[166:169], v[214:217], v[66:69]
	v_mfma_f32_16x16x32_bf16 v[118:121], v[162:165], v[194:197], v[118:121]
	v_mfma_f32_16x16x32_bf16 v[114:117], v[170:173], v[194:197], v[114:117]
	v_mfma_f32_16x16x32_bf16 v[102:105], v[162:165], v[202:205], v[102:105]
	v_mfma_f32_16x16x32_bf16 v[98:101], v[170:173], v[202:205], v[98:101]
	v_mfma_f32_16x16x32_bf16 v[86:89], v[162:165], v[210:213], v[86:89]
	v_mfma_f32_16x16x32_bf16 v[82:85], v[170:173], v[210:213], v[82:85]
	v_mfma_f32_16x16x32_bf16 v[70:73], v[162:165], v[218:221], v[70:73]
	v_mfma_f32_16x16x32_bf16 v[66:69], v[170:173], v[218:221], v[66:69]
	s_setprio 0
	s_setprio 1
	v_mfma_f32_16x16x32_bf16 v[126:129], v[174:177], v[190:193], v[126:129]
	v_mfma_f32_16x16x32_bf16 v[122:125], v[182:185], v[190:193], v[122:125]
	v_mfma_f32_16x16x32_bf16 v[110:113], v[174:177], v[198:201], v[110:113]
	v_mfma_f32_16x16x32_bf16 v[106:109], v[182:185], v[198:201], v[106:109]
	v_mfma_f32_16x16x32_bf16 v[94:97], v[174:177], v[206:209], v[94:97]
	v_mfma_f32_16x16x32_bf16 v[90:93], v[182:185], v[206:209], v[90:93]
	v_mfma_f32_16x16x32_bf16 v[78:81], v[174:177], v[214:217], v[78:81]
	v_mfma_f32_16x16x32_bf16 v[74:77], v[182:185], v[214:217], v[74:77]
	v_mfma_f32_16x16x32_bf16 v[126:129], v[178:181], v[194:197], v[126:129]
	v_mfma_f32_16x16x32_bf16 v[122:125], v[186:189], v[194:197], v[122:125]
	v_mfma_f32_16x16x32_bf16 v[110:113], v[178:181], v[202:205], v[110:113]
	v_mfma_f32_16x16x32_bf16 v[106:109], v[186:189], v[202:205], v[106:109]
	v_mfma_f32_16x16x32_bf16 v[94:97], v[178:181], v[210:213], v[94:97]
	v_mfma_f32_16x16x32_bf16 v[90:93], v[186:189], v[210:213], v[90:93]
	v_mfma_f32_16x16x32_bf16 v[78:81], v[178:181], v[218:221], v[78:81]
	v_mfma_f32_16x16x32_bf16 v[74:77], v[186:189], v[218:221], v[74:77]
	s_setprio 0
	s_barrier
	s_add_i32 s24, s70, s11
	v_lshl_add_u64 v[222:223], s[58:59], 0, v[134:135]
	s_mov_b32 m0, s24
	ds_read_b128 v[190:193], v154 offset:16384
	ds_read_b128 v[194:197], v154 offset:17408
	ds_read_b128 v[198:201], v154 offset:18432
	ds_read_b128 v[202:205], v154 offset:19456
	ds_read_b128 v[206:209], v154 offset:20480
	ds_read_b128 v[210:213], v154 offset:21504
	ds_read_b128 v[214:217], v154 offset:22528
	ds_read_b128 v[218:221], v154 offset:23552
	global_load_lds_dwordx4 v[222:223], off
	s_add_i32 m0, s24, 0x2000
	s_add_u32 s78, s58, 0x80000
	v_lshl_add_u64 v[224:225], s[58:59], 0, v[130:131]
	s_addc_u32 s79, s59, 0
	s_add_i32 s24, s71, s11
	global_load_lds_dwordx4 v[224:225], off
	v_lshl_add_u64 v[226:227], s[78:79], 0, v[134:135]
	s_mov_b32 m0, s24
	v_lshl_add_u64 v[228:229], s[60:61], 0, v[132:133]
	global_load_lds_dwordx4 v[226:227], off
	v_lshl_add_u64 v[226:227], s[78:79], 0, v[130:131]
	s_add_i32 m0, s24, 0x2000
	s_nop 0
	global_load_lds_dwordx4 v[226:227], off
	v_lshl_add_u64 v[226:227], s[60:61], 0, v[136:137]
	s_mov_b32 m0, s33
	s_nop 0
	global_load_lds_dwordx4 v[226:227], off
	s_mov_b32 m0, s62
	s_nop 0
	global_load_lds_dwordx4 v[228:229], off
	s_waitcnt vmcnt(8)
	s_waitcnt lgkmcnt(0)
	s_barrier
; #define PG8_STAGEA(bufoff, gbase, voff) PG8_STAGE_X(bufoff, gbase, voff, PG8_AUX_A)
; #define PG8_LDA(dst, b, h) do { _Pragma("unroll") for (int m = 0; m < 4; ++m) _Pragma("unroll") for (int k = 0; k < 2; ++k) dst[m][k] = *(const PG8_LAS bf16x8*)(lds + PG8_SA(b, h) + aoff + m * 2048 + k * 1024); } while (0)
; #define PG8_LDB(dst, b, h) do { _Pragma("unroll") for (int n = 0; n < 2; ++n) _Pragma("unroll") for (int k = 0; k < 2; ++k) dst[n][k] = *(const PG8_LAS bf16x8*)(lds + PG8_SB(b, h) + boff + n * 2048 + k * 1024); } while (0)
; #define PG8_MMA(ai, bj, At, Bt) do { __builtin_amdgcn_s_setprio(1); _Pragma("unroll") for (int m = 0; m < 4; ++m) _Pragma("unroll") for (int n = 0; n < 2; ++n) _Pragma("unroll") for (int k = 0; k < 2; ++k) \
;         acc[ai][bj][m][n] = __builtin_amdgcn_mfma_f32_16x16x32_bf16(Bt[n][k], At[m][k], acc[ai][bj][m][n], 0, 0, 0); __builtin_amdgcn_s_setprio(0); } while (0)
; #define PG8_WAIT_V(n) asm volatile("s_waitcnt vmcnt(" #n ")" ::: "memory")
; #define PG8_WAIT_L(n) asm volatile("s_waitcnt lgkmcnt(" #n ")" ::: "memory")
; #define PG8_BAR __builtin_amdgcn_s_barrier()
; #define PG8_SCHED __builtin_amdgcn_sched_barrier(0)
; template <class Epi, class Sched, bool ALIGN_EPI = false, bool SP2 = false>
; __device__ __forceinline__ void gemm_phase(PG8_LAS unsigned char* lds, const Gemm g, const Sched& S, const Epi& E) {
;     ...
;             PG8_WAIT_V(8); PG8_WAIT_L(0); PG8_BAR; PG8_MMA(1, 0, At, B0); PG8_MMA(1, 1, At, B1); PG8_BAR; PG8_SCHED;
;             PG8_LDB(B0, 1, 0); PG8_LDB(B1, 1, 1); PG8_SCHED; PG8_LDA(At, 1, 0); PG8_STAGEA(PG8_SA(0, 1), a2 + hstep, voffA);
;             PG8_WAIT_V(8); PG8_WAIT_L(0); PG8_BAR; PG8_MMA(0, 0, At, B0); PG8_MMA(0, 1, At, B1); PG8_BAR; PG8_SCHED;
	s_setprio 1
	v_mfma_f32_16x16x32_bf16 v[54:57], v[158:161], v[190:193], v[54:57]
	v_mfma_f32_16x16x32_bf16 v[50:53], v[166:169], v[190:193], v[50:53]
	v_mfma_f32_16x16x32_bf16 v[38:41], v[158:161], v[198:201], v[38:41]
	v_mfma_f32_16x16x32_bf16 v[34:37], v[166:169], v[198:201], v[34:37]
	v_mfma_f32_16x16x32_bf16 v[22:25], v[158:161], v[206:209], v[22:25]
	v_mfma_f32_16x16x32_bf16 v[18:21], v[166:169], v[206:209], v[18:21]
	v_mfma_f32_16x16x32_bf16 v[6:9], v[158:161], v[214:217], v[6:9]
	v_mfma_f32_16x16x32_bf16 v[2:5], v[166:169], v[214:217], v[2:5]
	v_mfma_f32_16x16x32_bf16 v[54:57], v[162:165], v[194:197], v[54:57]
	v_mfma_f32_16x16x32_bf16 v[50:53], v[170:173], v[194:197], v[50:53]
	v_mfma_f32_16x16x32_bf16 v[38:41], v[162:165], v[202:205], v[38:41]
	v_mfma_f32_16x16x32_bf16 v[34:37], v[170:173], v[202:205], v[34:37]
	v_mfma_f32_16x16x32_bf16 v[22:25], v[162:165], v[210:213], v[22:25]
	v_mfma_f32_16x16x32_bf16 v[18:21], v[170:173], v[210:213], v[18:21]
	v_mfma_f32_16x16x32_bf16 v[6:9], v[162:165], v[218:221], v[6:9]
	v_mfma_f32_16x16x32_bf16 v[2:5], v[170:173], v[218:221], v[2:5]
	s_setprio 0
	s_setprio 1
	v_mfma_f32_16x16x32_bf16 v[62:65], v[174:177], v[190:193], v[62:65]
	v_mfma_f32_16x16x32_bf16 v[58:61], v[182:185], v[190:193], v[58:61]
	v_mfma_f32_16x16x32_bf16 v[46:49], v[174:177], v[198:201], v[46:49]
	v_mfma_f32_16x16x32_bf16 v[42:45], v[182:185], v[198:201], v[42:45]
	v_mfma_f32_16x16x32_bf16 v[30:33], v[174:177], v[206:209], v[30:33]
	v_mfma_f32_16x16x32_bf16 v[26:29], v[182:185], v[206:209], v[26:29]
	v_mfma_f32_16x16x32_bf16 v[14:17], v[174:177], v[214:217], v[14:17]
	v_mfma_f32_16x16x32_bf16 v[10:13], v[182:185], v[214:217], v[10:13]
	v_mfma_f32_16x16x32_bf16 v[62:65], v[178:181], v[194:197], v[62:65]
	v_mfma_f32_16x16x32_bf16 v[58:61], v[186:189], v[194:197], v[58:61]
	v_mfma_f32_16x16x32_bf16 v[46:49], v[178:181], v[202:205], v[46:49]
	v_mfma_f32_16x16x32_bf16 v[42:45], v[186:189], v[202:205], v[42:45]
	v_mfma_f32_16x16x32_bf16 v[30:33], v[178:181], v[210:213], v[30:33]
	v_mfma_f32_16x16x32_bf16 v[26:29], v[186:189], v[210:213], v[26:29]
	v_mfma_f32_16x16x32_bf16 v[14:17], v[178:181], v[218:221], v[14:17]
	v_mfma_f32_16x16x32_bf16 v[10:13], v[186:189], v[218:221], v[10:13]
	s_setprio 0
	s_barrier
	s_add_i32 s24, 0, 0x18000
	v_add_u32_e32 v157, s24, v150
	s_add_i32 s25, 0, 0x1c000
	ds_read_b128 v[158:161], v157
	ds_read_b128 v[162:165], v157 offset:1024
	ds_read_b128 v[166:169], v157 offset:2048
	ds_read_b128 v[170:173], v157 offset:3072
	v_add_u32_e32 v157, s25, v150
	ds_read_b128 v[174:177], v157
	ds_read_b128 v[178:181], v157 offset:1024
	ds_read_b128 v[182:185], v157 offset:2048
	ds_read_b128 v[186:189], v157 offset:3072
	s_add_u32 s60, s60, 0x80000
	s_addc_u32 s61, s61, 0
	s_mov_b32 m0, s63
	v_lshl_add_u64 v[230:231], s[60:61], 0, v[136:137]
	ds_read_b128 v[190:193], v154 offset:32768
	ds_read_b128 v[194:197], v154 offset:33792
	ds_read_b128 v[198:201], v154 offset:34816
	ds_read_b128 v[202:205], v154 offset:35840
	ds_read_b128 v[206:209], v154 offset:36864
	ds_read_b128 v[210:213], v154 offset:37888
	ds_read_b128 v[214:217], v154 offset:38912
	ds_read_b128 v[218:221], v154 offset:39936
	global_load_lds_dwordx4 v[230:231], off
	v_lshl_add_u64 v[230:231], s[60:61], 0, v[132:133]
	s_mov_b32 m0, s64
	s_nop 0
	global_load_lds_dwordx4 v[230:231], off
	s_waitcnt vmcnt(8)
	s_waitcnt lgkmcnt(0)
	s_barrier
	s_setprio 1
	v_mfma_f32_16x16x32_bf16 v[118:121], v[158:161], v[190:193], v[118:121]
	v_mfma_f32_16x16x32_bf16 v[114:117], v[166:169], v[190:193], v[114:117]
	v_mfma_f32_16x16x32_bf16 v[102:105], v[158:161], v[198:201], v[102:105]
	v_mfma_f32_16x16x32_bf16 v[98:101], v[166:169], v[198:201], v[98:101]
	v_mfma_f32_16x16x32_bf16 v[86:89], v[158:161], v[206:209], v[86:89]
	v_mfma_f32_16x16x32_bf16 v[82:85], v[166:169], v[206:209], v[82:85]
	v_mfma_f32_16x16x32_bf16 v[70:73], v[158:161], v[214:217], v[70:73]
	v_mfma_f32_16x16x32_bf16 v[66:69], v[166:169], v[214:217], v[66:69]
	v_mfma_f32_16x16x32_bf16 v[118:121], v[162:165], v[194:197], v[118:121]
	v_mfma_f32_16x16x32_bf16 v[114:117], v[170:173], v[194:197], v[114:117]
	v_mfma_f32_16x16x32_bf16 v[102:105], v[162:165], v[202:205], v[102:105]
	v_mfma_f32_16x16x32_bf16 v[98:101], v[170:173], v[202:205], v[98:101]
	v_mfma_f32_16x16x32_bf16 v[86:89], v[162:165], v[210:213], v[86:89]
	v_mfma_f32_16x16x32_bf16 v[82:85], v[170:173], v[210:213], v[82:85]
	v_mfma_f32_16x16x32_bf16 v[70:73], v[162:165], v[218:221], v[70:73]
	v_mfma_f32_16x16x32_bf16 v[66:69], v[170:173], v[218:221], v[66:69]
	s_setprio 0
	s_setprio 1
	v_mfma_f32_16x16x32_bf16 v[126:129], v[174:177], v[190:193], v[126:129]
	v_mfma_f32_16x16x32_bf16 v[122:125], v[182:185], v[190:193], v[122:125]
	v_mfma_f32_16x16x32_bf16 v[110:113], v[174:177], v[198:201], v[110:113]
	v_mfma_f32_16x16x32_bf16 v[106:109], v[182:185], v[198:201], v[106:109]
	v_mfma_f32_16x16x32_bf16 v[94:97], v[174:177], v[206:209], v[94:97]
	v_mfma_f32_16x16x32_bf16 v[90:93], v[182:185], v[206:209], v[90:93]
	v_mfma_f32_16x16x32_bf16 v[78:81], v[174:177], v[214:217], v[78:81]
	v_mfma_f32_16x16x32_bf16 v[74:77], v[182:185], v[214:217], v[74:77]
	v_mfma_f32_16x16x32_bf16 v[126:129], v[178:181], v[194:197], v[126:129]
	v_mfma_f32_16x16x32_bf16 v[122:125], v[186:189], v[194:197], v[122:125]
	v_mfma_f32_16x16x32_bf16 v[110:113], v[178:181], v[202:205], v[110:113]
	v_mfma_f32_16x16x32_bf16 v[106:109], v[186:189], v[202:205], v[106:109]
	v_mfma_f32_16x16x32_bf16 v[94:97], v[178:181], v[210:213], v[94:97]
	v_mfma_f32_16x16x32_bf16 v[90:93], v[186:189], v[210:213], v[90:93]
	v_mfma_f32_16x16x32_bf16 v[78:81], v[178:181], v[218:221], v[78:81]
	v_mfma_f32_16x16x32_bf16 v[74:77], v[186:189], v[218:221], v[74:77]
	s_setprio 0
	s_barrier
; #define PG8_STAGEA(bufoff, gbase, voff) PG8_STAGE_X(bufoff, gbase, voff, PG8_AUX_A)
; #define PG8_STAGEB(bufoff, gbase, voff) PG8_STAGE_X(bufoff, gbase, voff, PG8_AUX_B)
; #define PG8_LDA(dst, b, h) do { _Pragma("unroll") for (int m = 0; m < 4; ++m) _Pragma("unroll") for (int k = 0; k < 2; ++k) dst[m][k] = *(const PG8_LAS bf16x8*)(lds + PG8_SA(b, h) + aoff + m * 2048 + k * 1024); } while (0)
; #define PG8_MMA(ai, bj, At, Bt) do { __builtin_amdgcn_s_setprio(1); _Pragma("unroll") for (int m = 0; m < 4; ++m) _Pragma("unroll") for (int n = 0; n < 2; ++n) _Pragma("unroll") for (int k = 0; k < 2; ++k) \
;         acc[ai][bj][m][n] = __builtin_amdgcn_mfma_f32_16x16x32_bf16(Bt[n][k], At[m][k], acc[ai][bj][m][n], 0, 0, 0); __builtin_amdgcn_s_setprio(0); } while (0)
; #define PG8_WAIT_V(n) asm volatile("s_waitcnt vmcnt(" #n ")" ::: "memory")
; #define PG8_WAIT_L(n) asm volatile("s_waitcnt lgkmcnt(" #n ")" ::: "memory")
; #define PG8_BAR __builtin_amdgcn_s_barrier()
; #define PG8_SCHED __builtin_amdgcn_sched_barrier(0)
; template <class Epi, class Sched, bool ALIGN_EPI = false, bool SP2 = false>
; __device__ __forceinline__ void gemm_phase(PG8_LAS unsigned char* lds, const Gemm g, const Sched& S, const Epi& E) {
;     ...
;             PG8_LDA(At, 1, 1); PG8_STAGEB(PG8_SB(1, 0), b3, voffB); PG8_STAGEB(PG8_SB(1, 1), b3 + hstep, voffB); PG8_STAGEA(PG8_SA(1, 0), a3, voffA);
;             PG8_WAIT_V(8); PG8_WAIT_L(0); PG8_BAR; PG8_MMA(1, 0, At, B0); PG8_MMA(1, 1, At, B1); PG8_BAR; PG8_SCHED;
	s_add_i32 s24, s24, s11
	v_lshl_add_u64 v[222:223], v[222:223], 0, s[40:41]
	s_mov_b32 m0, s24
	ds_read_b128 v[190:193], v154 offset:49152
	ds_read_b128 v[194:197], v154 offset:50176
	ds_read_b128 v[198:201], v154 offset:51200
	ds_read_b128 v[202:205], v154 offset:52224
	ds_read_b128 v[206:209], v154 offset:53248
	ds_read_b128 v[210:213], v154 offset:54272
	ds_read_b128 v[214:217], v154 offset:55296
	ds_read_b128 v[218:221], v154 offset:56320
	global_load_lds_dwordx4 v[222:223], off
	s_add_i32 m0, s24, 0x2000
	s_add_u32 s58, s58, 0x80080
	v_lshl_add_u64 v[222:223], v[224:225], 0, s[40:41]
	s_addc_u32 s59, s59, 0
	s_add_i32 s24, s25, s11
	global_load_lds_dwordx4 v[222:223], off
	v_lshl_add_u64 v[222:223], s[58:59], 0, v[134:135]
	s_mov_b32 m0, s24
	s_nop 0
	global_load_lds_dwordx4 v[222:223], off
	v_lshl_add_u64 v[222:223], s[58:59], 0, v[130:131]
	s_add_i32 m0, s24, 0x2000
	s_nop 0
	global_load_lds_dwordx4 v[222:223], off
	v_lshl_add_u64 v[222:223], v[226:227], 0, s[40:41]
	s_mov_b32 m0, s67
	s_nop 0
	global_load_lds_dwordx4 v[222:223], off
	v_lshl_add_u64 v[222:223], v[228:229], 0, s[40:41]
	s_mov_b32 m0, s68
	s_nop 0
	global_load_lds_dwordx4 v[222:223], off
	s_waitcnt vmcnt(8)
	s_waitcnt lgkmcnt(0)
	s_barrier
	s_setprio 1
	v_mfma_f32_16x16x32_bf16 v[54:57], v[158:161], v[190:193], v[54:57]
	v_mfma_f32_16x16x32_bf16 v[50:53], v[166:169], v[190:193], v[50:53]
	v_mfma_f32_16x16x32_bf16 v[38:41], v[158:161], v[198:201], v[38:41]
	v_mfma_f32_16x16x32_bf16 v[34:37], v[166:169], v[198:201], v[34:37]
	v_mfma_f32_16x16x32_bf16 v[22:25], v[158:161], v[206:209], v[22:25]
	v_mfma_f32_16x16x32_bf16 v[18:21], v[166:169], v[206:209], v[18:21]
	v_mfma_f32_16x16x32_bf16 v[6:9], v[158:161], v[214:217], v[6:9]
	v_mfma_f32_16x16x32_bf16 v[2:5], v[166:169], v[214:217], v[2:5]
	v_mfma_f32_16x16x32_bf16 v[54:57], v[162:165], v[194:197], v[54:57]
	v_mfma_f32_16x16x32_bf16 v[50:53], v[170:173], v[194:197], v[50:53]
	v_mfma_f32_16x16x32_bf16 v[38:41], v[162:165], v[202:205], v[38:41]
	v_mfma_f32_16x16x32_bf16 v[34:37], v[170:173], v[202:205], v[34:37]
	v_mfma_f32_16x16x32_bf16 v[22:25], v[162:165], v[210:213], v[22:25]
	v_mfma_f32_16x16x32_bf16 v[18:21], v[170:173], v[210:213], v[18:21]
	v_mfma_f32_16x16x32_bf16 v[6:9], v[162:165], v[218:221], v[6:9]
	v_mfma_f32_16x16x32_bf16 v[2:5], v[170:173], v[218:221], v[2:5]
	s_setprio 0
	s_setprio 1
	v_mfma_f32_16x16x32_bf16 v[62:65], v[174:177], v[190:193], v[62:65]
	v_mfma_f32_16x16x32_bf16 v[58:61], v[182:185], v[190:193], v[58:61]
	v_mfma_f32_16x16x32_bf16 v[46:49], v[174:177], v[198:201], v[46:49]
	v_mfma_f32_16x16x32_bf16 v[42:45], v[182:185], v[198:201], v[42:45]
	v_mfma_f32_16x16x32_bf16 v[30:33], v[174:177], v[206:209], v[30:33]
	v_mfma_f32_16x16x32_bf16 v[26:29], v[182:185], v[206:209], v[26:29]
	v_mfma_f32_16x16x32_bf16 v[14:17], v[174:177], v[214:217], v[14:17]
	v_mfma_f32_16x16x32_bf16 v[10:13], v[182:185], v[214:217], v[10:13]
	v_mfma_f32_16x16x32_bf16 v[62:65], v[178:181], v[194:197], v[62:65]
	v_mfma_f32_16x16x32_bf16 v[58:61], v[186:189], v[194:197], v[58:61]
	v_mfma_f32_16x16x32_bf16 v[46:49], v[178:181], v[202:205], v[46:49]
	v_mfma_f32_16x16x32_bf16 v[42:45], v[186:189], v[202:205], v[42:45]
	v_mfma_f32_16x16x32_bf16 v[30:33], v[178:181], v[210:213], v[30:33]
	v_mfma_f32_16x16x32_bf16 v[26:29], v[186:189], v[210:213], v[26:29]
	v_mfma_f32_16x16x32_bf16 v[14:17], v[178:181], v[218:221], v[14:17]
	v_mfma_f32_16x16x32_bf16 v[10:13], v[186:189], v[218:221], v[10:13]
	s_setprio 0
	s_barrier
	s_add_u32 s56, s56, 0x100
	s_addc_u32 s57, s57, 0
	s_mov_b32 s58, s76
	s_cbranch_vccz .LBB0_1007
	s_and_b64 vcc, exec, s[42:43]
	s_cbranch_vccz .LBB0_1010
	s_barrier

; #define PG8_STAGEA(bufoff, gbase, voff) PG8_STAGE_X(bufoff, gbase, voff, PG8_AUX_A)
; #define PG8_STAGEB(bufoff, gbase, voff) PG8_STAGE_X(bufoff, gbase, voff, PG8_AUX_B)
; #define PG8_LDA(dst, b, h) do { _Pragma("unroll") for (int m = 0; m < 4; ++m) _Pragma("unroll") for (int k = 0; k < 2; ++k) dst[m][k] = *(const PG8_LAS bf16x8*)(lds + PG8_SA(b, h) + aoff + m * 2048 + k * 1024); } while (0)
; #define PG8_LDB(dst, b, h) do { _Pragma("unroll") for (int n = 0; n < 2; ++n) _Pragma("unroll") for (int k = 0; k < 2; ++k) dst[n][k] = *(const PG8_LAS bf16x8*)(lds + PG8_SB(b, h) + boff + n * 2048 + k * 1024); } while (0)
; #define PG8_MMA(ai, bj, At, Bt) do { __builtin_amdgcn_s_setprio(1); _Pragma("unroll") for (int m = 0; m < 4; ++m) _Pragma("unroll") for (int n = 0; n < 2; ++n) _Pragma("unroll") for (int k = 0; k < 2; ++k) \
;         acc[ai][bj][m][n] = __builtin_amdgcn_mfma_f32_16x16x32_bf16(Bt[n][k], At[m][k], acc[ai][bj][m][n], 0, 0, 0); __builtin_amdgcn_s_setprio(0); } while (0)
; #define PG8_WAIT_V(n) asm volatile("s_waitcnt vmcnt(" #n ")" ::: "memory")
; #define PG8_WAIT_L(n) asm volatile("s_waitcnt lgkmcnt(" #n ")" ::: "memory")
; template <class Epi, class Sched, bool ALIGN_EPI = false, bool SP2 = false>
; __device__ __forceinline__ void gemm_phase(PG8_LAS unsigned char* lds, const Gemm g, const Sched& S, const Epi& E) {
;     ...
;             const bool last = (t == nt - 2);
;             if constexpr (HasMid<Epi>::value) { if (t == ns) E.mid(acc, cur, wr, wc, fr, fq); }
;             const char* sA1 = (t + 1 >= ns) ? cA2 : cA; const char* sA2 = (t + 2 >= ns) ? cA2 : cA; const char* sB2 = (t + 2 >= ns) ? cB2 : cB;
;             const char* a1 = sA1 + (size_t)(t + 1) * kstep;
;             const char* a2 = last ? nA : sA2 + (size_t)(t + 2) * kstep; const char* b2 = last ? nB : sB2 + (size_t)(t + 2) * kstep;
;             const char* a3 = a2 + kstep; const char* b3 = b2 + kstep;
;             if (last && has_next) S.a_ready(nxt);
;             if constexpr (SP2) {
;             PG8_LDB(B0, 0, 0); PG8_LDB(B1, 0, 1); PG8_SCHED; PG8_LDA(At, 0, 0); PG8_STAGEA(PG8_SA(1, 1), a1 + hstep, voffA);
;             PG8_WAIT_V(8); PG8_WAIT_L(0); PG8_BAR; PG8_MMA(0, 0, At, B0); PG8_MMA(0, 1, At, B1); PG8_BAR; PG8_SCHED;
;             PG8_LDA(At, 0, 1); PG8_STAGEB(PG8_SB(0, 0), b2, voffB); PG8_STAGEB(PG8_SB(0, 1), b2 + hstep, voffB); PG8_STAGEA(PG8_SA(0, 0), a2, voffA);
.LBB0_1090:
	s_add_i32 s75, s54, 2
	s_cmpk_gt_u32 s75, 0x55
	s_cselect_b64 s[56:57], -1, 0
	s_and_b64 vcc, s[56:57], exec
	s_cselect_b32 s56, s24, s50
	ds_read_b128 v[154:157], v150
	ds_read_b128 v[158:161], v150 offset:1024
	ds_read_b128 v[162:165], v150 offset:2048
	ds_read_b128 v[166:169], v150 offset:3072
	ds_read_b128 v[170:173], v151
	ds_read_b128 v[174:177], v151 offset:1024
	ds_read_b128 v[178:181], v151 offset:2048
	ds_read_b128 v[182:185], v151 offset:3072
	s_cselect_b32 s28, s9, s49
	s_cselect_b32 s29, s8, s48
	s_cselect_b32 s55, s25, s51
	s_add_u32 s56, s56, s52
	s_addc_u32 s55, s55, s53
	s_add_u32 s56, s56, 0xffea0080
	s_addc_u32 s55, s55, -1
	s_add_u32 s29, s29, s52
	s_addc_u32 s28, s28, s53
	s_add_u32 s29, s29, 0xffea0080
	s_addc_u32 s28, s28, -1
	s_cmpk_eq_i32 s54, 0x54
	s_cselect_b32 s54, s46, s29
	s_cselect_b32 s57, s5, s55
	s_cselect_b32 s56, s4, s56
	s_cselect_b32 s55, s47, s28
	v_lshl_add_u64 v[146:147], v[142:143], 0, s[52:53]
	s_add_i32 m0, s23, 0xc000
	ds_read_b128 v[186:189], v152
	ds_read_b128 v[190:193], v152 offset:1024
	ds_read_b128 v[194:197], v152 offset:2048
	ds_read_b128 v[198:201], v152 offset:3072
	ds_read_b128 v[202:205], v152 offset:4096
	ds_read_b128 v[206:209], v152 offset:5120
	ds_read_b128 v[210:213], v152 offset:6144
	ds_read_b128 v[214:217], v152 offset:7168
	global_load_lds_dwordx4 v[146:147], off
	v_lshl_add_u64 v[146:147], v[144:145], 0, s[52:53]
	s_add_i32 m0, s23, 0xe000
	s_nop 0
	global_load_lds_dwordx4 v[146:147], off
	s_waitcnt vmcnt(8)
	s_waitcnt lgkmcnt(0)
	s_barrier
	s_setprio 1
	v_mfma_f32_16x16x32_bf16 v[126:129], v[154:157], v[186:189], v[126:129]
	v_mfma_f32_16x16x32_bf16 v[122:125], v[162:165], v[186:189], v[122:125]
	v_mfma_f32_16x16x32_bf16 v[114:117], v[154:157], v[194:197], v[114:117]
	v_mfma_f32_16x16x32_bf16 v[106:109], v[162:165], v[194:197], v[106:109]
	v_mfma_f32_16x16x32_bf16 v[94:97], v[154:157], v[202:205], v[94:97]
	v_mfma_f32_16x16x32_bf16 v[90:93], v[162:165], v[202:205], v[90:93]
	v_mfma_f32_16x16x32_bf16 v[78:81], v[154:157], v[210:213], v[78:81]
	v_mfma_f32_16x16x32_bf16 v[74:77], v[162:165], v[210:213], v[74:77]
	v_mfma_f32_16x16x32_bf16 v[126:129], v[158:161], v[190:193], v[126:129]
	v_mfma_f32_16x16x32_bf16 v[122:125], v[166:169], v[190:193], v[122:125]
	v_mfma_f32_16x16x32_bf16 v[114:117], v[158:161], v[198:201], v[114:117]
	v_mfma_f32_16x16x32_bf16 v[106:109], v[166:169], v[198:201], v[106:109]
	v_mfma_f32_16x16x32_bf16 v[94:97], v[158:161], v[206:209], v[94:97]
	v_mfma_f32_16x16x32_bf16 v[90:93], v[166:169], v[206:209], v[90:93]
	v_mfma_f32_16x16x32_bf16 v[78:81], v[158:161], v[214:217], v[78:81]
	v_mfma_f32_16x16x32_bf16 v[74:77], v[166:169], v[214:217], v[74:77]
	s_setprio 0
	s_setprio 1
	v_mfma_f32_16x16x32_bf16 v[118:121], v[170:173], v[186:189], v[118:121]
	v_mfma_f32_16x16x32_bf16 v[110:113], v[178:181], v[186:189], v[110:113]
	v_mfma_f32_16x16x32_bf16 v[102:105], v[170:173], v[194:197], v[102:105]
	v_mfma_f32_16x16x32_bf16 v[98:101], v[178:181], v[194:197], v[98:101]
	v_mfma_f32_16x16x32_bf16 v[86:89], v[170:173], v[202:205], v[86:89]
	v_mfma_f32_16x16x32_bf16 v[82:85], v[178:181], v[202:205], v[82:85]
	v_mfma_f32_16x16x32_bf16 v[70:73], v[170:173], v[210:213], v[70:73]
	v_mfma_f32_16x16x32_bf16 v[66:69], v[178:181], v[210:213], v[66:69]
	v_mfma_f32_16x16x32_bf16 v[118:121], v[174:177], v[190:193], v[118:121]
	v_mfma_f32_16x16x32_bf16 v[110:113], v[182:185], v[190:193], v[110:113]
	v_mfma_f32_16x16x32_bf16 v[102:105], v[174:177], v[198:201], v[102:105]
	v_mfma_f32_16x16x32_bf16 v[98:101], v[182:185], v[198:201], v[98:101]
	v_mfma_f32_16x16x32_bf16 v[86:89], v[174:177], v[206:209], v[86:89]
	v_mfma_f32_16x16x32_bf16 v[82:85], v[182:185], v[206:209], v[82:85]
	v_mfma_f32_16x16x32_bf16 v[70:73], v[174:177], v[214:217], v[70:73]
	v_mfma_f32_16x16x32_bf16 v[66:69], v[182:185], v[214:217], v[66:69]
	s_setprio 0
	s_barrier
	s_add_i32 s28, s65, s21
	v_lshl_add_u64 v[146:147], s[54:55], 0, v[130:131]
	s_mov_b32 m0, s28
	ds_read_b128 v[186:189], v152 offset:16384
	ds_read_b128 v[190:193], v152 offset:17408
	ds_read_b128 v[194:197], v152 offset:18432
	ds_read_b128 v[198:201], v152 offset:19456
	ds_read_b128 v[202:205], v152 offset:20480
	ds_read_b128 v[206:209], v152 offset:21504
	ds_read_b128 v[210:213], v152 offset:22528
	ds_read_b128 v[214:217], v152 offset:23552
	global_load_lds_dwordx4 v[146:147], off
	s_add_i32 m0, s28, 0x2000
	s_add_u32 s76, s54, 0x160000
	v_lshl_add_u64 v[218:219], s[54:55], 0, v[132:133]
	s_addc_u32 s77, s55, 0
	s_add_i32 s28, s66, s21
	global_load_lds_dwordx4 v[218:219], off
	v_lshl_add_u64 v[220:221], s[76:77], 0, v[130:131]
	s_mov_b32 m0, s28
	v_lshl_add_u64 v[222:223], s[56:57], 0, v[132:133]
	global_load_lds_dwordx4 v[220:221], off
	v_lshl_add_u64 v[220:221], s[76:77], 0, v[132:133]
	s_add_i32 m0, s28, 0x2000
	s_nop 0
	global_load_lds_dwordx4 v[220:221], off
	v_lshl_add_u64 v[220:221], s[56:57], 0, v[130:131]
	s_mov_b32 m0, s23
	s_nop 0
	global_load_lds_dwordx4 v[220:221], off
	s_mov_b32 m0, s33
	s_nop 0
	global_load_lds_dwordx4 v[222:223], off
	s_waitcnt vmcnt(8)
	s_waitcnt lgkmcnt(0)
	s_barrier
; #define PG8_STAGEA(bufoff, gbase, voff) PG8_STAGE_X(bufoff, gbase, voff, PG8_AUX_A)
; #define PG8_LDA(dst, b, h) do { _Pragma("unroll") for (int m = 0; m < 4; ++m) _Pragma("unroll") for (int k = 0; k < 2; ++k) dst[m][k] = *(const PG8_LAS bf16x8*)(lds + PG8_SA(b, h) + aoff + m * 2048 + k * 1024); } while (0)
; #define PG8_LDB(dst, b, h) do { _Pragma("unroll") for (int n = 0; n < 2; ++n) _Pragma("unroll") for (int k = 0; k < 2; ++k) dst[n][k] = *(const PG8_LAS bf16x8*)(lds + PG8_SB(b, h) + boff + n * 2048 + k * 1024); } while (0)
; #define PG8_MMA(ai, bj, At, Bt) do { __builtin_amdgcn_s_setprio(1); _Pragma("unroll") for (int m = 0; m < 4; ++m) _Pragma("unroll") for (int n = 0; n < 2; ++n) _Pragma("unroll") for (int k = 0; k < 2; ++k) \
;         acc[ai][bj][m][n] = __builtin_amdgcn_mfma_f32_16x16x32_bf16(Bt[n][k], At[m][k], acc[ai][bj][m][n], 0, 0, 0); __builtin_amdgcn_s_setprio(0); } while (0)
; #define PG8_WAIT_V(n) asm volatile("s_waitcnt vmcnt(" #n ")" ::: "memory")
; #define PG8_WAIT_L(n) asm volatile("s_waitcnt lgkmcnt(" #n ")" ::: "memory")
; #define PG8_BAR __builtin_amdgcn_s_barrier()
; #define PG8_SCHED __builtin_amdgcn_sched_barrier(0)
; template <class Epi, class Sched, bool ALIGN_EPI = false, bool SP2 = false>
; __device__ __forceinline__ void gemm_phase(PG8_LAS unsigned char* lds, const Gemm g, const Sched& S, const Epi& E) {
;     ...
;             PG8_WAIT_V(8); PG8_WAIT_L(0); PG8_BAR; PG8_MMA(1, 0, At, B0); PG8_MMA(1, 1, At, B1); PG8_BAR; PG8_SCHED;
;             PG8_LDB(B0, 1, 0); PG8_LDB(B1, 1, 1); PG8_SCHED; PG8_LDA(At, 1, 0); PG8_STAGEA(PG8_SA(0, 1), a2 + hstep, voffA);
;             PG8_WAIT_V(8); PG8_WAIT_L(0); PG8_BAR; PG8_MMA(0, 0, At, B0); PG8_MMA(0, 1, At, B1); PG8_BAR; PG8_SCHED;
	s_setprio 1
	v_mfma_f32_16x16x32_bf16 v[62:65], v[154:157], v[186:189], v[62:65]
	v_mfma_f32_16x16x32_bf16 v[58:61], v[162:165], v[186:189], v[58:61]
	v_mfma_f32_16x16x32_bf16 v[46:49], v[154:157], v[194:197], v[46:49]
	v_mfma_f32_16x16x32_bf16 v[42:45], v[162:165], v[194:197], v[42:45]
	v_mfma_f32_16x16x32_bf16 v[30:33], v[154:157], v[202:205], v[30:33]
	v_mfma_f32_16x16x32_bf16 v[26:29], v[162:165], v[202:205], v[26:29]
	v_mfma_f32_16x16x32_bf16 v[14:17], v[154:157], v[210:213], v[14:17]
	v_mfma_f32_16x16x32_bf16 v[10:13], v[162:165], v[210:213], v[10:13]
	v_mfma_f32_16x16x32_bf16 v[62:65], v[158:161], v[190:193], v[62:65]
	v_mfma_f32_16x16x32_bf16 v[58:61], v[166:169], v[190:193], v[58:61]
	v_mfma_f32_16x16x32_bf16 v[46:49], v[158:161], v[198:201], v[46:49]
	v_mfma_f32_16x16x32_bf16 v[42:45], v[166:169], v[198:201], v[42:45]
	v_mfma_f32_16x16x32_bf16 v[30:33], v[158:161], v[206:209], v[30:33]
	v_mfma_f32_16x16x32_bf16 v[26:29], v[166:169], v[206:209], v[26:29]
	v_mfma_f32_16x16x32_bf16 v[14:17], v[158:161], v[214:217], v[14:17]
	v_mfma_f32_16x16x32_bf16 v[10:13], v[166:169], v[214:217], v[10:13]
	s_setprio 0
	s_setprio 1
	v_mfma_f32_16x16x32_bf16 v[54:57], v[170:173], v[186:189], v[54:57]
	v_mfma_f32_16x16x32_bf16 v[50:53], v[178:181], v[186:189], v[50:53]
	v_mfma_f32_16x16x32_bf16 v[38:41], v[170:173], v[194:197], v[38:41]
	v_mfma_f32_16x16x32_bf16 v[34:37], v[178:181], v[194:197], v[34:37]
	v_mfma_f32_16x16x32_bf16 v[22:25], v[170:173], v[202:205], v[22:25]
	v_mfma_f32_16x16x32_bf16 v[18:21], v[178:181], v[202:205], v[18:21]
	v_mfma_f32_16x16x32_bf16 v[6:9], v[170:173], v[210:213], v[6:9]
	v_mfma_f32_16x16x32_bf16 v[2:5], v[178:181], v[210:213], v[2:5]
	v_mfma_f32_16x16x32_bf16 v[54:57], v[174:177], v[190:193], v[54:57]
	v_mfma_f32_16x16x32_bf16 v[50:53], v[182:185], v[190:193], v[50:53]
	v_mfma_f32_16x16x32_bf16 v[38:41], v[174:177], v[198:201], v[38:41]
	v_mfma_f32_16x16x32_bf16 v[34:37], v[182:185], v[198:201], v[34:37]
	v_mfma_f32_16x16x32_bf16 v[22:25], v[174:177], v[206:209], v[22:25]
	v_mfma_f32_16x16x32_bf16 v[18:21], v[182:185], v[206:209], v[18:21]
	v_mfma_f32_16x16x32_bf16 v[6:9], v[174:177], v[214:217], v[6:9]
	v_mfma_f32_16x16x32_bf16 v[2:5], v[182:185], v[214:217], v[2:5]
	s_setprio 0
	s_barrier
	s_add_i32 s28, 0, 0x18000
	v_add_u32_e32 v153, s28, v148
	s_add_i32 s29, 0, 0x1c000
	ds_read_b128 v[154:157], v153
	ds_read_b128 v[158:161], v153 offset:1024
	ds_read_b128 v[162:165], v153 offset:2048
	ds_read_b128 v[166:169], v153 offset:3072
	v_add_u32_e32 v153, s29, v148
	ds_read_b128 v[170:173], v153
	ds_read_b128 v[174:177], v153 offset:1024
	ds_read_b128 v[178:181], v153 offset:2048
	ds_read_b128 v[182:185], v153 offset:3072
	s_add_u32 s56, s56, 0x160000
	s_addc_u32 s57, s57, 0
	s_mov_b32 m0, s58
	v_lshl_add_u64 v[224:225], s[56:57], 0, v[130:131]
	ds_read_b128 v[186:189], v152 offset:32768
	ds_read_b128 v[190:193], v152 offset:33792
	ds_read_b128 v[194:197], v152 offset:34816
	ds_read_b128 v[198:201], v152 offset:35840
	ds_read_b128 v[202:205], v152 offset:36864
	ds_read_b128 v[206:209], v152 offset:37888
	ds_read_b128 v[210:213], v152 offset:38912
	ds_read_b128 v[214:217], v152 offset:39936
	global_load_lds_dwordx4 v[224:225], off
	v_lshl_add_u64 v[224:225], s[56:57], 0, v[132:133]
	s_mov_b32 m0, s59
	s_nop 0
	global_load_lds_dwordx4 v[224:225], off
	s_waitcnt vmcnt(8)
	s_waitcnt lgkmcnt(0)
	s_barrier
	s_setprio 1
	v_mfma_f32_16x16x32_bf16 v[126:129], v[154:157], v[186:189], v[126:129]
	v_mfma_f32_16x16x32_bf16 v[122:125], v[162:165], v[186:189], v[122:125]
	v_mfma_f32_16x16x32_bf16 v[114:117], v[154:157], v[194:197], v[114:117]
	v_mfma_f32_16x16x32_bf16 v[106:109], v[162:165], v[194:197], v[106:109]
	v_mfma_f32_16x16x32_bf16 v[94:97], v[154:157], v[202:205], v[94:97]
	v_mfma_f32_16x16x32_bf16 v[90:93], v[162:165], v[202:205], v[90:93]
	v_mfma_f32_16x16x32_bf16 v[78:81], v[154:157], v[210:213], v[78:81]
	v_mfma_f32_16x16x32_bf16 v[74:77], v[162:165], v[210:213], v[74:77]
	v_mfma_f32_16x16x32_bf16 v[126:129], v[158:161], v[190:193], v[126:129]
	v_mfma_f32_16x16x32_bf16 v[122:125], v[166:169], v[190:193], v[122:125]
	v_mfma_f32_16x16x32_bf16 v[114:117], v[158:161], v[198:201], v[114:117]
	v_mfma_f32_16x16x32_bf16 v[106:109], v[166:169], v[198:201], v[106:109]
	v_mfma_f32_16x16x32_bf16 v[94:97], v[158:161], v[206:209], v[94:97]
	v_mfma_f32_16x16x32_bf16 v[90:93], v[166:169], v[206:209], v[90:93]
	v_mfma_f32_16x16x32_bf16 v[78:81], v[158:161], v[214:217], v[78:81]
	v_mfma_f32_16x16x32_bf16 v[74:77], v[166:169], v[214:217], v[74:77]
	s_setprio 0
	s_setprio 1
	v_mfma_f32_16x16x32_bf16 v[118:121], v[170:173], v[186:189], v[118:121]
	v_mfma_f32_16x16x32_bf16 v[110:113], v[178:181], v[186:189], v[110:113]
	v_mfma_f32_16x16x32_bf16 v[102:105], v[170:173], v[194:197], v[102:105]
	v_mfma_f32_16x16x32_bf16 v[98:101], v[178:181], v[194:197], v[98:101]
	v_mfma_f32_16x16x32_bf16 v[86:89], v[170:173], v[202:205], v[86:89]
	v_mfma_f32_16x16x32_bf16 v[82:85], v[178:181], v[202:205], v[82:85]
	v_mfma_f32_16x16x32_bf16 v[70:73], v[170:173], v[210:213], v[70:73]
	v_mfma_f32_16x16x32_bf16 v[66:69], v[178:181], v[210:213], v[66:69]
	v_mfma_f32_16x16x32_bf16 v[118:121], v[174:177], v[190:193], v[118:121]
	v_mfma_f32_16x16x32_bf16 v[110:113], v[182:185], v[190:193], v[110:113]
	v_mfma_f32_16x16x32_bf16 v[102:105], v[174:177], v[198:201], v[102:105]
	v_mfma_f32_16x16x32_bf16 v[98:101], v[182:185], v[198:201], v[98:101]
	v_mfma_f32_16x16x32_bf16 v[86:89], v[174:177], v[206:209], v[86:89]
	v_mfma_f32_16x16x32_bf16 v[82:85], v[182:185], v[206:209], v[82:85]
	v_mfma_f32_16x16x32_bf16 v[70:73], v[174:177], v[214:217], v[70:73]
	v_mfma_f32_16x16x32_bf16 v[66:69], v[182:185], v[214:217], v[66:69]
	s_setprio 0
	s_barrier
; #define PG8_STAGEA(bufoff, gbase, voff) PG8_STAGE_X(bufoff, gbase, voff, PG8_AUX_A)
; #define PG8_STAGEB(bufoff, gbase, voff) PG8_STAGE_X(bufoff, gbase, voff, PG8_AUX_B)
; #define PG8_LDA(dst, b, h) do { _Pragma("unroll") for (int m = 0; m < 4; ++m) _Pragma("unroll") for (int k = 0; k < 2; ++k) dst[m][k] = *(const PG8_LAS bf16x8*)(lds + PG8_SA(b, h) + aoff + m * 2048 + k * 1024); } while (0)
; #define PG8_MMA(ai, bj, At, Bt) do { __builtin_amdgcn_s_setprio(1); _Pragma("unroll") for (int m = 0; m < 4; ++m) _Pragma("unroll") for (int n = 0; n < 2; ++n) _Pragma("unroll") for (int k = 0; k < 2; ++k) \
;         acc[ai][bj][m][n] = __builtin_amdgcn_mfma_f32_16x16x32_bf16(Bt[n][k], At[m][k], acc[ai][bj][m][n], 0, 0, 0); __builtin_amdgcn_s_setprio(0); } while (0)
; #define PG8_WAIT_V(n) asm volatile("s_waitcnt vmcnt(" #n ")" ::: "memory")
; #define PG8_WAIT_L(n) asm volatile("s_waitcnt lgkmcnt(" #n ")" ::: "memory")
; #define PG8_BAR __builtin_amdgcn_s_barrier()
; #define PG8_SCHED __builtin_amdgcn_sched_barrier(0)
; template <class Epi, class Sched, bool ALIGN_EPI = false, bool SP2 = false>
; __device__ __forceinline__ void gemm_phase(PG8_LAS unsigned char* lds, const Gemm g, const Sched& S, const Epi& E) {
;     ...
;             PG8_LDA(At, 1, 1); PG8_STAGEB(PG8_SB(1, 0), b3, voffB); PG8_STAGEB(PG8_SB(1, 1), b3 + hstep, voffB); PG8_STAGEA(PG8_SA(1, 0), a3, voffA);
;             PG8_WAIT_V(8); PG8_WAIT_L(0); PG8_BAR; PG8_MMA(1, 0, At, B0); PG8_MMA(1, 1, At, B1); PG8_BAR; PG8_SCHED;
	s_add_i32 s28, s28, s21
	v_lshl_add_u64 v[146:147], v[146:147], 0, s[34:35]
	s_mov_b32 m0, s28
	ds_read_b128 v[186:189], v152 offset:49152
	ds_read_b128 v[190:193], v152 offset:50176
	ds_read_b128 v[194:197], v152 offset:51200
	ds_read_b128 v[198:201], v152 offset:52224
	ds_read_b128 v[202:205], v152 offset:53248
	ds_read_b128 v[206:209], v152 offset:54272
	ds_read_b128 v[210:213], v152 offset:55296
	ds_read_b128 v[214:217], v152 offset:56320
	global_load_lds_dwordx4 v[146:147], off
	s_add_i32 m0, s28, 0x2000
	s_add_u32 s54, s54, 0x160080
	v_lshl_add_u64 v[146:147], v[218:219], 0, s[34:35]
	s_addc_u32 s55, s55, 0
	s_add_i32 s28, s29, s21
	global_load_lds_dwordx4 v[146:147], off
	v_lshl_add_u64 v[146:147], s[54:55], 0, v[130:131]
	s_mov_b32 m0, s28
	s_nop 0
	global_load_lds_dwordx4 v[146:147], off
	v_lshl_add_u64 v[146:147], s[54:55], 0, v[132:133]
	s_add_i32 m0, s28, 0x2000
	s_nop 0
	global_load_lds_dwordx4 v[146:147], off
	v_lshl_add_u64 v[146:147], v[220:221], 0, s[34:35]
	s_mov_b32 m0, s61
	s_nop 0
	global_load_lds_dwordx4 v[146:147], off
	v_lshl_add_u64 v[146:147], v[222:223], 0, s[34:35]
	s_mov_b32 m0, s62
	s_nop 0
	global_load_lds_dwordx4 v[146:147], off
	s_waitcnt vmcnt(8)
	s_waitcnt lgkmcnt(0)
	s_barrier
	s_setprio 1
	v_mfma_f32_16x16x32_bf16 v[62:65], v[154:157], v[186:189], v[62:65]
	v_mfma_f32_16x16x32_bf16 v[58:61], v[162:165], v[186:189], v[58:61]
	v_mfma_f32_16x16x32_bf16 v[46:49], v[154:157], v[194:197], v[46:49]
	v_mfma_f32_16x16x32_bf16 v[42:45], v[162:165], v[194:197], v[42:45]
	v_mfma_f32_16x16x32_bf16 v[30:33], v[154:157], v[202:205], v[30:33]
	v_mfma_f32_16x16x32_bf16 v[26:29], v[162:165], v[202:205], v[26:29]
	v_mfma_f32_16x16x32_bf16 v[14:17], v[154:157], v[210:213], v[14:17]
	v_mfma_f32_16x16x32_bf16 v[10:13], v[162:165], v[210:213], v[10:13]
	v_mfma_f32_16x16x32_bf16 v[62:65], v[158:161], v[190:193], v[62:65]
	v_mfma_f32_16x16x32_bf16 v[58:61], v[166:169], v[190:193], v[58:61]
	v_mfma_f32_16x16x32_bf16 v[46:49], v[158:161], v[198:201], v[46:49]
	v_mfma_f32_16x16x32_bf16 v[42:45], v[166:169], v[198:201], v[42:45]
	v_mfma_f32_16x16x32_bf16 v[30:33], v[158:161], v[206:209], v[30:33]
	v_mfma_f32_16x16x32_bf16 v[26:29], v[166:169], v[206:209], v[26:29]
	v_mfma_f32_16x16x32_bf16 v[14:17], v[158:161], v[214:217], v[14:17]
	v_mfma_f32_16x16x32_bf16 v[10:13], v[166:169], v[214:217], v[10:13]
	s_setprio 0
	s_setprio 1
	v_mfma_f32_16x16x32_bf16 v[54:57], v[170:173], v[186:189], v[54:57]
	v_mfma_f32_16x16x32_bf16 v[50:53], v[178:181], v[186:189], v[50:53]
	v_mfma_f32_16x16x32_bf16 v[38:41], v[170:173], v[194:197], v[38:41]
	v_mfma_f32_16x16x32_bf16 v[34:37], v[178:181], v[194:197], v[34:37]
	v_mfma_f32_16x16x32_bf16 v[22:25], v[170:173], v[202:205], v[22:25]
	v_mfma_f32_16x16x32_bf16 v[18:21], v[178:181], v[202:205], v[18:21]
	v_mfma_f32_16x16x32_bf16 v[6:9], v[170:173], v[210:213], v[6:9]
	v_mfma_f32_16x16x32_bf16 v[2:5], v[178:181], v[210:213], v[2:5]
	v_mfma_f32_16x16x32_bf16 v[54:57], v[174:177], v[190:193], v[54:57]
	v_mfma_f32_16x16x32_bf16 v[50:53], v[182:185], v[190:193], v[50:53]
	v_mfma_f32_16x16x32_bf16 v[38:41], v[174:177], v[198:201], v[38:41]
	v_mfma_f32_16x16x32_bf16 v[34:37], v[182:185], v[198:201], v[34:37]
	v_mfma_f32_16x16x32_bf16 v[22:25], v[174:177], v[206:209], v[22:25]
	v_mfma_f32_16x16x32_bf16 v[18:21], v[182:185], v[206:209], v[18:21]
	v_mfma_f32_16x16x32_bf16 v[6:9], v[174:177], v[214:217], v[6:9]
	v_mfma_f32_16x16x32_bf16 v[2:5], v[182:185], v[214:217], v[2:5]
	s_setprio 0
	s_barrier
	s_add_u32 s52, s52, 0x100
	s_addc_u32 s53, s53, 0
	s_mov_b32 s54, s75
	s_cbranch_vccz .LBB0_1090
	s_and_b64 vcc, exec, s[36:37]
	s_cbranch_vccz .LBB0_1093
	s_barrier
